# GEMM K-loops: first trip peeled (C=0 on first MFMA per accumulator, no accumulator zeroing); dead DPP destination inits removed in FFN-up epilogue
# speedup vs baseline: 1.0139x; 1.0038x over previous
; #define PG8_STAGE(bufoff, gbase, voff) do { _Pragma("unroll") for (int _i = 0; _i < 2; ++_i) \
;         __builtin_amdgcn_global_load_lds((const unsigned*)((const char*)(gbase) + (voff)[_i]), (PG8_LAS unsigned*)(lds + (bufoff) + ldsw + _i * 8192), 16, 0, 0); } while (0)
; #define PG8_LDA(dst, b, h) do { _Pragma("unroll") for (int m = 0; m < 4; ++m) _Pragma("unroll") for (int k = 0; k < 2; ++k) dst[m][k] = *(const PG8_LAS bf16x8*)(lds + PG8_SA(b, h) + aoff + m * 2048 + k * 1024); } while (0)
; #define PG8_LDB(dst, b, h) do { _Pragma("unroll") for (int n = 0; n < 2; ++n) _Pragma("unroll") for (int k = 0; k < 2; ++k) dst[n][k] = *(const PG8_LAS bf16x8*)(lds + PG8_SB(b, h) + boff + n * 2048 + k * 1024); } while (0)
; #define PG8_MMA(ai, bj, At, Bt) do { __builtin_amdgcn_s_setprio(1); _Pragma("unroll") for (int m = 0; m < 4; ++m) _Pragma("unroll") for (int n = 0; n < 2; ++n) _Pragma("unroll") for (int k = 0; k < 2; ++k) \
;         acc[ai][bj][m][n] = __builtin_amdgcn_mfma_f32_16x16x32_bf16(Bt[n][k], At[m][k], acc[ai][bj][m][n], 0, 0, 0); __builtin_amdgcn_s_setprio(0); } while (0)
; #define PG8_WAIT_V(n) asm volatile("s_waitcnt vmcnt(" #n ")" ::: "memory")
; #define PG8_WAIT_L(n) asm volatile("s_waitcnt lgkmcnt(" #n ")" ::: "memory")
; template <class Epi, class Sched, bool ALIGN_EPI = false, bool SP2 = false>
; __device__ __forceinline__ void gemm_phase(PG8_LAS unsigned char* lds, const int Kdim  , const int Klen  , const Sched& S, const Epi& E, const int wave_s) {
;     ...
;             const bool last = (t == nt - 2);
;             const char* a1 = cA + (size_t)(t + 1) * kstep;
;             const char* a2 = last ? nA : cA + (size_t)(t + 2) * kstep; const char* b2 = last ? nB : cB + (size_t)(t + 2) * kstep;
;             const char* a3 = a2 + kstep; const char* b3 = b2 + kstep;
;             if (last && has_next) S.a_ready(nxt);
;             if constexpr (SP2) {
;             PG8_LDB(B0, 0, 0); PG8_LDB(B1, 0, 1); PG8_SCHED; PG8_LDA(At, 0, 0); PG8_STAGE(PG8_SA(1, 1), a1 + hstep, voffA);
;             PG8_WAIT_V(8); PG8_WAIT_L(0); PG8_BAR; PG8_MMA(0, 0, At, B0); PG8_MMA(0, 1, At, B1); PG8_BAR; PG8_SCHED;
;             PG8_LDA(At, 0, 1); PG8_STAGE(PG8_SB(0, 0), b2, voffB); PG8_STAGE(PG8_SB(0, 1), b2 + hstep, voffB); PG8_STAGE(PG8_SA(0, 0), a2, voffA);
;             PG8_WAIT_V(8); PG8_WAIT_L(0); PG8_BAR; PG8_MMA(1, 0, At, B0); PG8_MMA(1, 1, At, B1); PG8_BAR; PG8_SCHED;
.LBB0_488:
	s_add_u32 s28, s28, 0x80080
	s_addc_u32 s29, s29, 0
	s_add_u32 s17, s30, 0x100
	s_addc_u32 s19, s31, 0
	s_mov_b32 s27, -2
	s_add_u32 s30, s28, 0xfff80080
	s_addc_u32 s31, s29, -1
	s_cmp_eq_u32 s27, 28
	s_cselect_b32 s35, s23, s31
	s_cselect_b32 s34, s22, s30
	s_cselect_b32 s31, s25, s19
	s_cselect_b32 s30, s24, s17
	s_add_i32 s73, 0, 0x14000
	v_add_u32_e32 v152, s90, v146
	v_add_u32_e32 v168, s73, v146
	ds_read_b128 v[138:141], v152
	ds_read_b128 v[142:145], v152 offset:1024
	ds_read_b128 v[148:151], v152 offset:2048
	ds_read_b128 v[152:155], v152 offset:3072
	ds_read_b128 v[156:159], v168
	ds_read_b128 v[160:163], v168 offset:1024
	ds_read_b128 v[164:167], v168 offset:2048
	ds_read_b128 v[168:171], v168 offset:3072
	v_lshl_add_u64 v[206:207], s[28:29], 0, v[134:135]
	s_add_i32 m0, s21, 0xc000
	ds_read_b128 v[172:175], v147
	ds_read_b128 v[178:181], v147 offset:1024
	ds_read_b128 v[182:185], v147 offset:2048
	ds_read_b128 v[186:189], v147 offset:3072
	ds_read_b128 v[190:193], v147 offset:4096
	ds_read_b128 v[194:197], v147 offset:5120
	ds_read_b128 v[198:201], v147 offset:6144
	ds_read_b128 v[202:205], v147 offset:7168
	global_load_lds_dwordx4 v[206:207], off
	v_lshl_add_u64 v[206:207], s[28:29], 0, v[136:137]
	s_add_i32 m0, s21, 0xe000
	s_nop 0
	global_load_lds_dwordx4 v[206:207], off
	s_waitcnt vmcnt(8)
	s_waitcnt lgkmcnt(0)
	s_barrier
	s_setprio 1
	s_waitcnt lgkmcnt(0)
	v_mfma_f32_16x16x32_bf16 v[124:127], v[138:141], v[172:175], 0
	v_mfma_f32_16x16x32_bf16 v[120:123], v[148:151], v[172:175], 0
	v_mfma_f32_16x16x32_bf16 v[112:115], v[138:141], v[182:185], 0
	v_mfma_f32_16x16x32_bf16 v[104:107], v[148:151], v[182:185], 0
	v_mfma_f32_16x16x32_bf16 v[96:99], v[138:141], v[190:193], 0
	v_mfma_f32_16x16x32_bf16 v[88:91], v[148:151], v[190:193], 0
	v_mfma_f32_16x16x32_bf16 v[80:83], v[138:141], v[198:201], 0
	v_mfma_f32_16x16x32_bf16 v[72:75], v[148:151], v[198:201], 0
	v_mfma_f32_16x16x32_bf16 v[124:127], v[142:145], v[178:181], v[124:127]
	v_mfma_f32_16x16x32_bf16 v[120:123], v[152:155], v[178:181], v[120:123]
	v_mfma_f32_16x16x32_bf16 v[112:115], v[142:145], v[186:189], v[112:115]
	v_mfma_f32_16x16x32_bf16 v[104:107], v[152:155], v[186:189], v[104:107]
	v_mfma_f32_16x16x32_bf16 v[96:99], v[142:145], v[194:197], v[96:99]
	v_mfma_f32_16x16x32_bf16 v[88:91], v[152:155], v[194:197], v[88:91]
	v_mfma_f32_16x16x32_bf16 v[80:83], v[142:145], v[202:205], v[80:83]
	v_mfma_f32_16x16x32_bf16 v[72:75], v[152:155], v[202:205], v[72:75]
	s_setprio 0
	s_setprio 1
	v_mfma_f32_16x16x32_bf16 v[116:119], v[156:159], v[172:175], 0
	v_mfma_f32_16x16x32_bf16 v[108:111], v[164:167], v[172:175], 0
	v_mfma_f32_16x16x32_bf16 v[100:103], v[156:159], v[182:185], 0
	v_mfma_f32_16x16x32_bf16 v[92:95], v[164:167], v[182:185], 0
	v_mfma_f32_16x16x32_bf16 v[84:87], v[156:159], v[190:193], 0
	v_mfma_f32_16x16x32_bf16 v[76:79], v[164:167], v[190:193], 0
	v_mfma_f32_16x16x32_bf16 v[68:71], v[156:159], v[198:201], 0
	v_mfma_f32_16x16x32_bf16 v[64:67], v[164:167], v[198:201], 0
	v_mfma_f32_16x16x32_bf16 v[116:119], v[160:163], v[178:181], v[116:119]
	v_mfma_f32_16x16x32_bf16 v[108:111], v[168:171], v[178:181], v[108:111]
	v_mfma_f32_16x16x32_bf16 v[100:103], v[160:163], v[186:189], v[100:103]
	v_mfma_f32_16x16x32_bf16 v[92:95], v[168:171], v[186:189], v[92:95]
	v_mfma_f32_16x16x32_bf16 v[84:87], v[160:163], v[194:197], v[84:87]
	v_mfma_f32_16x16x32_bf16 v[76:79], v[168:171], v[194:197], v[76:79]
	v_mfma_f32_16x16x32_bf16 v[68:71], v[160:163], v[202:205], v[68:71]
	v_mfma_f32_16x16x32_bf16 v[64:67], v[168:171], v[202:205], v[64:67]
	s_setprio 0
	s_barrier
	s_add_i32 s74, s90, s37
	v_lshl_add_u64 v[206:207], s[30:31], 0, v[176:177]
	s_mov_b32 m0, s74
	ds_read_b128 v[172:175], v147 offset:16384
	ds_read_b128 v[178:181], v147 offset:17408
	ds_read_b128 v[182:185], v147 offset:18432
	ds_read_b128 v[186:189], v147 offset:19456
	ds_read_b128 v[190:193], v147 offset:20480
	ds_read_b128 v[194:197], v147 offset:21504
	ds_read_b128 v[198:201], v147 offset:22528
	ds_read_b128 v[202:205], v147 offset:23552
	global_load_lds_dwordx4 v[206:207], off
	s_add_i32 m0, s74, 0x2000
	s_add_u32 s74, s30, 0x80000
	v_lshl_add_u64 v[208:209], s[30:31], 0, v[132:133]
	s_addc_u32 s75, s31, 0
	s_add_i32 s73, s73, s37
	global_load_lds_dwordx4 v[208:209], off
	v_lshl_add_u64 v[210:211], s[74:75], 0, v[176:177]
	s_mov_b32 m0, s73
	v_lshl_add_u64 v[218:219], s[34:35], 0, v[130:131]
	global_load_lds_dwordx4 v[210:211], off
	v_lshl_add_u64 v[210:211], s[74:75], 0, v[132:133]
	s_add_i32 m0, s73, 0x2000
	s_nop 0
	global_load_lds_dwordx4 v[210:211], off
	v_lshl_add_u64 v[210:211], s[34:35], 0, v[128:129]
	s_mov_b32 m0, s21
	s_nop 0
	global_load_lds_dwordx4 v[210:211], off
	s_mov_b32 m0, s49
	s_nop 0
	global_load_lds_dwordx4 v[218:219], off
	s_waitcnt vmcnt(8)
	s_waitcnt lgkmcnt(0)
	s_barrier
; #define PG8_STAGE(bufoff, gbase, voff) do { _Pragma("unroll") for (int _i = 0; _i < 2; ++_i) \
;         __builtin_amdgcn_global_load_lds((const unsigned*)((const char*)(gbase) + (voff)[_i]), (PG8_LAS unsigned*)(lds + (bufoff) + ldsw + _i * 8192), 16, 0, 0); } while (0)
; #define PG8_LDA(dst, b, h) do { _Pragma("unroll") for (int m = 0; m < 4; ++m) _Pragma("unroll") for (int k = 0; k < 2; ++k) dst[m][k] = *(const PG8_LAS bf16x8*)(lds + PG8_SA(b, h) + aoff + m * 2048 + k * 1024); } while (0)
; #define PG8_LDB(dst, b, h) do { _Pragma("unroll") for (int n = 0; n < 2; ++n) _Pragma("unroll") for (int k = 0; k < 2; ++k) dst[n][k] = *(const PG8_LAS bf16x8*)(lds + PG8_SB(b, h) + boff + n * 2048 + k * 1024); } while (0)
; #define PG8_MMA(ai, bj, At, Bt) do { __builtin_amdgcn_s_setprio(1); _Pragma("unroll") for (int m = 0; m < 4; ++m) _Pragma("unroll") for (int n = 0; n < 2; ++n) _Pragma("unroll") for (int k = 0; k < 2; ++k) \
;         acc[ai][bj][m][n] = __builtin_amdgcn_mfma_f32_16x16x32_bf16(Bt[n][k], At[m][k], acc[ai][bj][m][n], 0, 0, 0); __builtin_amdgcn_s_setprio(0); } while (0)
; #define PG8_WAIT_V(n) asm volatile("s_waitcnt vmcnt(" #n ")" ::: "memory")
; #define PG8_WAIT_L(n) asm volatile("s_waitcnt lgkmcnt(" #n ")" ::: "memory")
; #define PG8_BAR __builtin_amdgcn_s_barrier()
; #define PG8_SCHED __builtin_amdgcn_sched_barrier(0)
; template <class Epi, class Sched, bool ALIGN_EPI = false, bool SP2 = false>
; __device__ __forceinline__ void gemm_phase(PG8_LAS unsigned char* lds, const int Kdim  , const int Klen  , const Sched& S, const Epi& E, const int wave_s) {
;     ...
;             PG8_WAIT_V(8); PG8_WAIT_L(0); PG8_BAR; PG8_MMA(1, 0, At, B0); PG8_MMA(1, 1, At, B1); PG8_BAR; PG8_SCHED;
;             PG8_LDB(B0, 1, 0); PG8_LDB(B1, 1, 1); PG8_SCHED; PG8_LDA(At, 1, 0); PG8_STAGE(PG8_SA(0, 1), a2 + hstep, voffA);
;             PG8_WAIT_V(8); PG8_WAIT_L(0); PG8_BAR; PG8_MMA(0, 0, At, B0); PG8_MMA(0, 1, At, B1); PG8_BAR; PG8_SCHED;
	s_setprio 1
	s_waitcnt lgkmcnt(0)
	v_mfma_f32_16x16x32_bf16 v[60:63], v[138:141], v[172:175], 0
	v_mfma_f32_16x16x32_bf16 v[56:59], v[148:151], v[172:175], 0
	v_mfma_f32_16x16x32_bf16 v[48:51], v[138:141], v[182:185], 0
	v_mfma_f32_16x16x32_bf16 v[40:43], v[148:151], v[182:185], 0
	v_mfma_f32_16x16x32_bf16 v[32:35], v[138:141], v[190:193], 0
	v_mfma_f32_16x16x32_bf16 v[24:27], v[148:151], v[190:193], 0
	v_mfma_f32_16x16x32_bf16 v[16:19], v[138:141], v[198:201], 0
	v_mfma_f32_16x16x32_bf16 v[8:11], v[148:151], v[198:201], 0
	v_mfma_f32_16x16x32_bf16 v[60:63], v[142:145], v[178:181], v[60:63]
	v_mfma_f32_16x16x32_bf16 v[56:59], v[152:155], v[178:181], v[56:59]
	v_mfma_f32_16x16x32_bf16 v[48:51], v[142:145], v[186:189], v[48:51]
	v_mfma_f32_16x16x32_bf16 v[40:43], v[152:155], v[186:189], v[40:43]
	v_mfma_f32_16x16x32_bf16 v[32:35], v[142:145], v[194:197], v[32:35]
	v_mfma_f32_16x16x32_bf16 v[24:27], v[152:155], v[194:197], v[24:27]
	v_mfma_f32_16x16x32_bf16 v[16:19], v[142:145], v[202:205], v[16:19]
	v_mfma_f32_16x16x32_bf16 v[8:11], v[152:155], v[202:205], v[8:11]
	s_setprio 0
	s_setprio 1
	v_mfma_f32_16x16x32_bf16 v[52:55], v[156:159], v[172:175], 0
	v_mfma_f32_16x16x32_bf16 v[44:47], v[164:167], v[172:175], 0
	v_mfma_f32_16x16x32_bf16 v[36:39], v[156:159], v[182:185], 0
	v_mfma_f32_16x16x32_bf16 v[28:31], v[164:167], v[182:185], 0
	v_mfma_f32_16x16x32_bf16 v[20:23], v[156:159], v[190:193], 0
	v_mfma_f32_16x16x32_bf16 v[12:15], v[164:167], v[190:193], 0
	v_mfma_f32_16x16x32_bf16 v[4:7], v[156:159], v[198:201], 0
	v_mfma_f32_16x16x32_bf16 v[0:3], v[164:167], v[198:201], 0
	v_mfma_f32_16x16x32_bf16 v[52:55], v[160:163], v[178:181], v[52:55]
	v_mfma_f32_16x16x32_bf16 v[44:47], v[168:171], v[178:181], v[44:47]
	v_mfma_f32_16x16x32_bf16 v[36:39], v[160:163], v[186:189], v[36:39]
	v_mfma_f32_16x16x32_bf16 v[28:31], v[168:171], v[186:189], v[28:31]
	v_mfma_f32_16x16x32_bf16 v[20:23], v[160:163], v[194:197], v[20:23]
	v_mfma_f32_16x16x32_bf16 v[12:15], v[168:171], v[194:197], v[12:15]
	v_mfma_f32_16x16x32_bf16 v[4:7], v[160:163], v[202:205], v[4:7]
	v_mfma_f32_16x16x32_bf16 v[0:3], v[168:171], v[202:205], v[0:3]
	s_setprio 0
	s_barrier
	s_add_i32 s73, 0, 0x18000
	s_add_i32 s74, 0, 0x1c000
	v_add_u32_e32 v152, s73, v146
	v_add_u32_e32 v168, s74, v146
	ds_read_b128 v[138:141], v152
	ds_read_b128 v[142:145], v152 offset:1024
	ds_read_b128 v[148:151], v152 offset:2048
	ds_read_b128 v[152:155], v152 offset:3072
	ds_read_b128 v[156:159], v168
	ds_read_b128 v[160:163], v168 offset:1024
	ds_read_b128 v[164:167], v168 offset:2048
	ds_read_b128 v[168:171], v168 offset:3072
	s_add_u32 s34, s34, 0x80000
	s_addc_u32 s35, s35, 0
	s_mov_b32 m0, s50
	v_lshl_add_u64 v[232:233], s[34:35], 0, v[128:129]
	ds_read_b128 v[172:175], v147 offset:32768
	ds_read_b128 v[178:181], v147 offset:33792
	ds_read_b128 v[182:185], v147 offset:34816
	ds_read_b128 v[186:189], v147 offset:35840
	ds_read_b128 v[190:193], v147 offset:36864
	ds_read_b128 v[194:197], v147 offset:37888
	ds_read_b128 v[198:201], v147 offset:38912
	ds_read_b128 v[202:205], v147 offset:39936
	global_load_lds_dwordx4 v[232:233], off
	v_lshl_add_u64 v[232:233], s[34:35], 0, v[130:131]
	s_mov_b32 m0, s58
	s_nop 0
	global_load_lds_dwordx4 v[232:233], off
	s_waitcnt vmcnt(8)
	s_waitcnt lgkmcnt(0)
	s_barrier
	s_setprio 1
	s_waitcnt lgkmcnt(0)
	v_mfma_f32_16x16x32_bf16 v[124:127], v[138:141], v[172:175], v[124:127]
	v_mfma_f32_16x16x32_bf16 v[120:123], v[148:151], v[172:175], v[120:123]
	v_mfma_f32_16x16x32_bf16 v[112:115], v[138:141], v[182:185], v[112:115]
	v_mfma_f32_16x16x32_bf16 v[104:107], v[148:151], v[182:185], v[104:107]
	v_mfma_f32_16x16x32_bf16 v[96:99], v[138:141], v[190:193], v[96:99]
	v_mfma_f32_16x16x32_bf16 v[88:91], v[148:151], v[190:193], v[88:91]
	v_mfma_f32_16x16x32_bf16 v[80:83], v[138:141], v[198:201], v[80:83]
	v_mfma_f32_16x16x32_bf16 v[72:75], v[148:151], v[198:201], v[72:75]
	v_mfma_f32_16x16x32_bf16 v[124:127], v[142:145], v[178:181], v[124:127]
	v_mfma_f32_16x16x32_bf16 v[120:123], v[152:155], v[178:181], v[120:123]
	v_mfma_f32_16x16x32_bf16 v[112:115], v[142:145], v[186:189], v[112:115]
	v_mfma_f32_16x16x32_bf16 v[104:107], v[152:155], v[186:189], v[104:107]
	v_mfma_f32_16x16x32_bf16 v[96:99], v[142:145], v[194:197], v[96:99]
	v_mfma_f32_16x16x32_bf16 v[88:91], v[152:155], v[194:197], v[88:91]
	v_mfma_f32_16x16x32_bf16 v[80:83], v[142:145], v[202:205], v[80:83]
	v_mfma_f32_16x16x32_bf16 v[72:75], v[152:155], v[202:205], v[72:75]
	s_setprio 0
	s_setprio 1
	v_mfma_f32_16x16x32_bf16 v[116:119], v[156:159], v[172:175], v[116:119]
	v_mfma_f32_16x16x32_bf16 v[108:111], v[164:167], v[172:175], v[108:111]
	v_mfma_f32_16x16x32_bf16 v[100:103], v[156:159], v[182:185], v[100:103]
	v_mfma_f32_16x16x32_bf16 v[92:95], v[164:167], v[182:185], v[92:95]
	v_mfma_f32_16x16x32_bf16 v[84:87], v[156:159], v[190:193], v[84:87]
	v_mfma_f32_16x16x32_bf16 v[76:79], v[164:167], v[190:193], v[76:79]
	v_mfma_f32_16x16x32_bf16 v[68:71], v[156:159], v[198:201], v[68:71]
	v_mfma_f32_16x16x32_bf16 v[64:67], v[164:167], v[198:201], v[64:67]
	v_mfma_f32_16x16x32_bf16 v[116:119], v[160:163], v[178:181], v[116:119]
	v_mfma_f32_16x16x32_bf16 v[108:111], v[168:171], v[178:181], v[108:111]
	v_mfma_f32_16x16x32_bf16 v[100:103], v[160:163], v[186:189], v[100:103]
	v_mfma_f32_16x16x32_bf16 v[92:95], v[168:171], v[186:189], v[92:95]
	v_mfma_f32_16x16x32_bf16 v[84:87], v[160:163], v[194:197], v[84:87]
	v_mfma_f32_16x16x32_bf16 v[76:79], v[168:171], v[194:197], v[76:79]
	v_mfma_f32_16x16x32_bf16 v[68:71], v[160:163], v[202:205], v[68:71]
	v_mfma_f32_16x16x32_bf16 v[64:67], v[168:171], v[202:205], v[64:67]
	s_setprio 0
	s_barrier
; #define PG8_STAGE(bufoff, gbase, voff) do { _Pragma("unroll") for (int _i = 0; _i < 2; ++_i) \
;         __builtin_amdgcn_global_load_lds((const unsigned*)((const char*)(gbase) + (voff)[_i]), (PG8_LAS unsigned*)(lds + (bufoff) + ldsw + _i * 8192), 16, 0, 0); } while (0)
; #define PG8_LDA(dst, b, h) do { _Pragma("unroll") for (int m = 0; m < 4; ++m) _Pragma("unroll") for (int k = 0; k < 2; ++k) dst[m][k] = *(const PG8_LAS bf16x8*)(lds + PG8_SA(b, h) + aoff + m * 2048 + k * 1024); } while (0)
; #define PG8_LDB(dst, b, h) do { _Pragma("unroll") for (int n = 0; n < 2; ++n) _Pragma("unroll") for (int k = 0; k < 2; ++k) dst[n][k] = *(const PG8_LAS bf16x8*)(lds + PG8_SB(b, h) + boff + n * 2048 + k * 1024); } while (0)
; #define PG8_MMA(ai, bj, At, Bt) do { __builtin_amdgcn_s_setprio(1); _Pragma("unroll") for (int m = 0; m < 4; ++m) _Pragma("unroll") for (int n = 0; n < 2; ++n) _Pragma("unroll") for (int k = 0; k < 2; ++k) \
;         acc[ai][bj][m][n] = __builtin_amdgcn_mfma_f32_16x16x32_bf16(Bt[n][k], At[m][k], acc[ai][bj][m][n], 0, 0, 0); __builtin_amdgcn_s_setprio(0); } while (0)
; #define PG8_WAIT_V(n) asm volatile("s_waitcnt vmcnt(" #n ")" ::: "memory")
; #define PG8_WAIT_L(n) asm volatile("s_waitcnt lgkmcnt(" #n ")" ::: "memory")
; #define PG8_BAR __builtin_amdgcn_s_barrier()
; #define PG8_SCHED __builtin_amdgcn_sched_barrier(0)
; template <class Epi, class Sched, bool ALIGN_EPI = false, bool SP2 = false>
; __device__ __forceinline__ void gemm_phase(PG8_LAS unsigned char* lds, const int Kdim  , const int Klen  , const Sched& S, const Epi& E, const int wave_s) {
;     ...
;             PG8_LDB(B0, 1, 0); PG8_LDB(B1, 1, 1); PG8_SCHED; PG8_LDA(At, 1, 0); PG8_STAGE(PG8_SA(0, 1), a2 + hstep, voffA);
;             PG8_WAIT_V(8); PG8_WAIT_L(0); PG8_BAR; PG8_MMA(0, 0, At, B0); PG8_MMA(0, 1, At, B1); PG8_BAR; PG8_SCHED;
;             PG8_LDA(At, 1, 1); PG8_STAGE(PG8_SB(1, 0), b3, voffB); PG8_STAGE(PG8_SB(1, 1), b3 + hstep, voffB); PG8_STAGE(PG8_SA(1, 0), a3, voffA);
;             PG8_WAIT_V(8); PG8_WAIT_L(0); PG8_BAR; PG8_MMA(1, 0, At, B0); PG8_MMA(1, 1, At, B1); PG8_BAR; PG8_SCHED;
	s_add_i32 s34, s73, s37
	v_lshl_add_u64 v[206:207], v[206:207], 0, s[96:97]
	s_mov_b32 m0, s34
	ds_read_b128 v[172:175], v147 offset:49152
	ds_read_b128 v[178:181], v147 offset:50176
	ds_read_b128 v[182:185], v147 offset:51200
	ds_read_b128 v[186:189], v147 offset:52224
	ds_read_b128 v[190:193], v147 offset:53248
	ds_read_b128 v[194:197], v147 offset:54272
	ds_read_b128 v[198:201], v147 offset:55296
	ds_read_b128 v[202:205], v147 offset:56320
	global_load_lds_dwordx4 v[206:207], off
	s_add_i32 m0, s34, 0x2000
	s_add_u32 s30, s30, 0x80080
	v_lshl_add_u64 v[206:207], v[208:209], 0, s[96:97]
	s_addc_u32 s31, s31, 0
	s_add_i32 s34, s74, s37
	global_load_lds_dwordx4 v[206:207], off
	v_lshl_add_u64 v[206:207], s[30:31], 0, v[176:177]
	s_mov_b32 m0, s34
	s_nop 0
	global_load_lds_dwordx4 v[206:207], off
	v_lshl_add_u64 v[206:207], s[30:31], 0, v[132:133]
	s_add_i32 m0, s34, 0x2000
	s_nop 0
	global_load_lds_dwordx4 v[206:207], off
	v_lshl_add_u64 v[206:207], v[210:211], 0, s[96:97]
	s_mov_b32 m0, s59
	s_nop 0
	global_load_lds_dwordx4 v[206:207], off
	v_lshl_add_u64 v[206:207], v[218:219], 0, s[96:97]
	s_mov_b32 m0, s62
	s_nop 0
	global_load_lds_dwordx4 v[206:207], off
	s_waitcnt vmcnt(8)
	s_waitcnt lgkmcnt(0)
	s_barrier
	s_setprio 1
	s_waitcnt lgkmcnt(0)
	v_mfma_f32_16x16x32_bf16 v[60:63], v[138:141], v[172:175], v[60:63]
	v_mfma_f32_16x16x32_bf16 v[56:59], v[148:151], v[172:175], v[56:59]
	v_mfma_f32_16x16x32_bf16 v[48:51], v[138:141], v[182:185], v[48:51]
	v_mfma_f32_16x16x32_bf16 v[40:43], v[148:151], v[182:185], v[40:43]
	v_mfma_f32_16x16x32_bf16 v[32:35], v[138:141], v[190:193], v[32:35]
	v_mfma_f32_16x16x32_bf16 v[24:27], v[148:151], v[190:193], v[24:27]
	v_mfma_f32_16x16x32_bf16 v[16:19], v[138:141], v[198:201], v[16:19]
	v_mfma_f32_16x16x32_bf16 v[8:11], v[148:151], v[198:201], v[8:11]
	v_mfma_f32_16x16x32_bf16 v[60:63], v[142:145], v[178:181], v[60:63]
	v_mfma_f32_16x16x32_bf16 v[56:59], v[152:155], v[178:181], v[56:59]
	v_mfma_f32_16x16x32_bf16 v[48:51], v[142:145], v[186:189], v[48:51]
	v_mfma_f32_16x16x32_bf16 v[40:43], v[152:155], v[186:189], v[40:43]
	v_mfma_f32_16x16x32_bf16 v[32:35], v[142:145], v[194:197], v[32:35]
	v_mfma_f32_16x16x32_bf16 v[24:27], v[152:155], v[194:197], v[24:27]
	v_mfma_f32_16x16x32_bf16 v[16:19], v[142:145], v[202:205], v[16:19]
	v_mfma_f32_16x16x32_bf16 v[8:11], v[152:155], v[202:205], v[8:11]
	s_setprio 0
	s_setprio 1
	v_mfma_f32_16x16x32_bf16 v[52:55], v[156:159], v[172:175], v[52:55]
	v_mfma_f32_16x16x32_bf16 v[44:47], v[164:167], v[172:175], v[44:47]
	v_mfma_f32_16x16x32_bf16 v[36:39], v[156:159], v[182:185], v[36:39]
	v_mfma_f32_16x16x32_bf16 v[28:31], v[164:167], v[182:185], v[28:31]
	v_mfma_f32_16x16x32_bf16 v[20:23], v[156:159], v[190:193], v[20:23]
	v_mfma_f32_16x16x32_bf16 v[12:15], v[164:167], v[190:193], v[12:15]
	v_mfma_f32_16x16x32_bf16 v[4:7], v[156:159], v[198:201], v[4:7]
	v_mfma_f32_16x16x32_bf16 v[0:3], v[164:167], v[198:201], v[0:3]
	v_mfma_f32_16x16x32_bf16 v[52:55], v[160:163], v[178:181], v[52:55]
	v_mfma_f32_16x16x32_bf16 v[44:47], v[168:171], v[178:181], v[44:47]
	v_mfma_f32_16x16x32_bf16 v[36:39], v[160:163], v[186:189], v[36:39]
	v_mfma_f32_16x16x32_bf16 v[28:31], v[168:171], v[186:189], v[28:31]
	v_mfma_f32_16x16x32_bf16 v[20:23], v[160:163], v[194:197], v[20:23]
	v_mfma_f32_16x16x32_bf16 v[12:15], v[168:171], v[194:197], v[12:15]
	v_mfma_f32_16x16x32_bf16 v[4:7], v[160:163], v[202:205], v[4:7]
	v_mfma_f32_16x16x32_bf16 v[0:3], v[168:171], v[202:205], v[0:3]
	s_setprio 0
	s_barrier
	s_add_i32 s27, s27, 2
	s_add_u32 s28, s28, 0x100
	s_addc_u32 s29, s29, 0
	s_add_u32 s17, s17, 0x100
	s_addc_u32 s19, s19, 0
	s_cmp_gt_u32 s27, 29
	s_cbranch_scc1 .Lkdone_0

; #define PG8_BAR __builtin_amdgcn_s_barrier()
; template <class Epi, class Sched, bool ALIGN_EPI = false, bool SP2 = false>
; __device__ __forceinline__ void gemm_phase(PG8_LAS unsigned char* lds, const int Kdim  , const int Klen  , const Sched& S, const Epi& E, const int wave_s) {
;     ...
;         }
;         if constexpr (ALIGN_EPI) { if (wr == 0) PG8_BAR; }
.Lkdone_0:
	s_and_b64 vcc, exec, s[14:15]
	s_cbranch_vccz .LBB0_492
	s_barrier

; #define PG8_STAGE(bufoff, gbase, voff) do { _Pragma("unroll") for (int _i = 0; _i < 2; ++_i) \
;         __builtin_amdgcn_global_load_lds((const unsigned*)((const char*)(gbase) + (voff)[_i]), (PG8_LAS unsigned*)(lds + (bufoff) + ldsw + _i * 8192), 16, 0, 0); } while (0)
; #define PG8_LDA(dst, b, h) do { _Pragma("unroll") for (int m = 0; m < 4; ++m) _Pragma("unroll") for (int k = 0; k < 2; ++k) dst[m][k] = *(const PG8_LAS bf16x8*)(lds + PG8_SA(b, h) + aoff + m * 2048 + k * 1024); } while (0)
; #define PG8_LDB(dst, b, h) do { _Pragma("unroll") for (int n = 0; n < 2; ++n) _Pragma("unroll") for (int k = 0; k < 2; ++k) dst[n][k] = *(const PG8_LAS bf16x8*)(lds + PG8_SB(b, h) + boff + n * 2048 + k * 1024); } while (0)
; #define PG8_MMA(ai, bj, At, Bt) do { __builtin_amdgcn_s_setprio(1); _Pragma("unroll") for (int m = 0; m < 4; ++m) _Pragma("unroll") for (int n = 0; n < 2; ++n) _Pragma("unroll") for (int k = 0; k < 2; ++k) \
;         acc[ai][bj][m][n] = __builtin_amdgcn_mfma_f32_16x16x32_bf16(Bt[n][k], At[m][k], acc[ai][bj][m][n], 0, 0, 0); __builtin_amdgcn_s_setprio(0); } while (0)
; #define PG8_WAIT_V(n) asm volatile("s_waitcnt vmcnt(" #n ")" ::: "memory")
; #define PG8_WAIT_L(n) asm volatile("s_waitcnt lgkmcnt(" #n ")" ::: "memory")
; template <class Epi, class Sched, bool ALIGN_EPI = false, bool SP2 = false>
; __device__ __forceinline__ void gemm_phase(PG8_LAS unsigned char* lds, const int Kdim  , const int Klen  , const Sched& S, const Epi& E, const int wave_s) {
;     ...
;             const bool last = (t == nt - 2);
;             const char* a1 = cA + (size_t)(t + 1) * kstep;
;             const char* a2 = last ? nA : cA + (size_t)(t + 2) * kstep; const char* b2 = last ? nB : cB + (size_t)(t + 2) * kstep;
;             const char* a3 = a2 + kstep; const char* b3 = b2 + kstep;
;             if (last && has_next) S.a_ready(nxt);
;             if constexpr (SP2) {
;             PG8_LDB(B0, 0, 0); PG8_LDB(B1, 0, 1); PG8_SCHED; PG8_LDA(At, 0, 0); PG8_STAGE(PG8_SA(1, 1), a1 + hstep, voffA);
;             PG8_WAIT_V(8); PG8_WAIT_L(0); PG8_BAR; PG8_MMA(0, 0, At, B0); PG8_MMA(0, 1, At, B1); PG8_BAR; PG8_SCHED;
;             PG8_LDA(At, 0, 1); PG8_STAGE(PG8_SB(0, 0), b2, voffB); PG8_STAGE(PG8_SB(0, 1), b2 + hstep, voffB); PG8_STAGE(PG8_SA(0, 0), a2, voffA);
;             PG8_WAIT_V(8); PG8_WAIT_L(0); PG8_BAR; PG8_MMA(1, 0, At, B0); PG8_MMA(1, 1, At, B1); PG8_BAR; PG8_SCHED;
.LBB0_1265:
	s_mov_b32 s79, s18
	s_add_i32 s18, s18, 1
	s_cmp_lt_u32 s79, 3
	s_mov_b64 s[6:7], s[16:17]
	s_mov_b64 s[8:9], s[12:13]
	s_cselect_b64 s[12:13], -1, 0
	s_lshl_b32 s5, s18, 5
	v_readlane_b32 s16, v254, 29
	v_readlane_b32 s17, v254, 30
	s_add_i32 s5, s16, s5
	s_and_b64 s[16:17], s[12:13], exec
	s_mov_b32 s19, s28
	v_readlane_b32 s16, v254, 59
	s_cselect_b32 s28, s5, s28
	s_mov_b32 s4, s26
	s_cselect_b32 s26, s16, s26
	s_ashr_i32 s29, s28, 31
	s_lshl_b64 s[16:17], s[28:29], 20
	s_add_u32 s5, s14, s16
	s_addc_u32 s27, s15, s17
	s_and_b64 s[16:17], s[12:13], exec
	s_cselect_b32 s17, s27, s7
	s_cselect_b32 s16, s5, s6
	s_ashr_i32 s27, s26, 31
	s_lshl_b64 s[30:31], s[26:27], 20
	s_add_u32 s5, s62, s30
	s_addc_u32 s27, s63, s31
	s_and_b64 s[12:13], s[12:13], exec
	s_cselect_b32 s13, s27, s9
	s_cselect_b32 s12, s5, s8
	s_add_u32 s5, s8, 0x100
	s_addc_u32 s27, s9, 0
	s_mov_b32 s29, -2
	s_add_u32 s8, s6, 0x100
	s_addc_u32 s9, s7, 0
	s_cmp_eq_u32 s29, 28
	s_cselect_b32 s35, s17, s9
	s_cselect_b32 s34, s16, s8
	s_cselect_b32 s31, s13, s27
	s_cselect_b32 s30, s12, s5
	s_add_i32 s65, 0, 0x14000
	v_add_u32_e32 v140, s90, v206
	v_add_u32_e32 v156, s65, v206
	ds_read_b128 v[128:131], v140
	ds_read_b128 v[132:135], v140 offset:1024
	ds_read_b128 v[136:139], v140 offset:2048
	ds_read_b128 v[140:143], v140 offset:3072
	ds_read_b128 v[144:147], v156
	ds_read_b128 v[148:151], v156 offset:1024
	ds_read_b128 v[152:155], v156 offset:2048
	ds_read_b128 v[156:159], v156 offset:3072
	v_lshl_add_u64 v[178:179], s[6:7], 0, v[182:183]
	s_add_i32 m0, s2, 0xc000
	ds_read_b128 v[160:163], v207
	ds_read_b128 v[164:167], v207 offset:1024
	ds_read_b128 v[168:171], v207 offset:2048
	ds_read_b128 v[172:175], v207 offset:3072
	ds_read_b128 v[186:189], v207 offset:4096
	ds_read_b128 v[190:193], v207 offset:5120
	ds_read_b128 v[194:197], v207 offset:6144
	ds_read_b128 v[198:201], v207 offset:7168
	global_load_lds_dwordx4 v[178:179], off
	v_lshl_add_u64 v[178:179], s[6:7], 0, v[184:185]
	s_add_i32 m0, s2, 0xe000
	s_nop 0
	global_load_lds_dwordx4 v[178:179], off
	s_waitcnt vmcnt(8)
	s_waitcnt lgkmcnt(0)
	s_barrier
	s_setprio 1
	s_waitcnt lgkmcnt(0)
	v_mfma_f32_16x16x32_bf16 v[76:79], v[128:131], v[160:163], 0
	v_mfma_f32_16x16x32_bf16 v[68:71], v[136:139], v[160:163], 0
	v_mfma_f32_16x16x32_bf16 v[92:95], v[128:131], v[168:171], 0
	v_mfma_f32_16x16x32_bf16 v[88:91], v[136:139], v[168:171], 0
	v_mfma_f32_16x16x32_bf16 v[104:107], v[128:131], v[186:189], 0
	v_mfma_f32_16x16x32_bf16 v[96:99], v[136:139], v[186:189], 0
	v_mfma_f32_16x16x32_bf16 v[124:127], v[128:131], v[194:197], 0
	v_mfma_f32_16x16x32_bf16 v[120:123], v[136:139], v[194:197], 0
	v_mfma_f32_16x16x32_bf16 v[76:79], v[132:135], v[164:167], v[76:79]
	v_mfma_f32_16x16x32_bf16 v[68:71], v[140:143], v[164:167], v[68:71]
	v_mfma_f32_16x16x32_bf16 v[92:95], v[132:135], v[172:175], v[92:95]
	v_mfma_f32_16x16x32_bf16 v[88:91], v[140:143], v[172:175], v[88:91]
	v_mfma_f32_16x16x32_bf16 v[104:107], v[132:135], v[190:193], v[104:107]
	v_mfma_f32_16x16x32_bf16 v[96:99], v[140:143], v[190:193], v[96:99]
	v_mfma_f32_16x16x32_bf16 v[124:127], v[132:135], v[198:201], v[124:127]
	v_mfma_f32_16x16x32_bf16 v[120:123], v[140:143], v[198:201], v[120:123]
	s_setprio 0
	s_setprio 1
	v_mfma_f32_16x16x32_bf16 v[64:67], v[144:147], v[160:163], 0
	v_mfma_f32_16x16x32_bf16 v[60:63], v[152:155], v[160:163], 0
	v_mfma_f32_16x16x32_bf16 v[84:87], v[144:147], v[168:171], 0
	v_mfma_f32_16x16x32_bf16 v[80:83], v[152:155], v[168:171], 0
	v_mfma_f32_16x16x32_bf16 v[100:103], v[144:147], v[186:189], 0
	v_mfma_f32_16x16x32_bf16 v[108:111], v[152:155], v[186:189], 0
	v_mfma_f32_16x16x32_bf16 v[116:119], v[144:147], v[194:197], 0
	v_mfma_f32_16x16x32_bf16 v[112:115], v[152:155], v[194:197], 0
	v_mfma_f32_16x16x32_bf16 v[64:67], v[148:151], v[164:167], v[64:67]
	v_mfma_f32_16x16x32_bf16 v[60:63], v[156:159], v[164:167], v[60:63]
	v_mfma_f32_16x16x32_bf16 v[84:87], v[148:151], v[172:175], v[84:87]
	v_mfma_f32_16x16x32_bf16 v[80:83], v[156:159], v[172:175], v[80:83]
	v_mfma_f32_16x16x32_bf16 v[100:103], v[148:151], v[190:193], v[100:103]
	v_mfma_f32_16x16x32_bf16 v[108:111], v[156:159], v[190:193], v[108:111]
	v_mfma_f32_16x16x32_bf16 v[116:119], v[148:151], v[198:201], v[116:119]
	v_mfma_f32_16x16x32_bf16 v[112:115], v[156:159], v[198:201], v[112:115]
	s_setprio 0
	s_barrier
	s_add_i32 s6, s90, s0
	v_lshl_add_u64 v[178:179], s[30:31], 0, v[176:177]
	s_mov_b32 m0, s6
	ds_read_b128 v[160:163], v207 offset:16384
	ds_read_b128 v[164:167], v207 offset:17408
	ds_read_b128 v[168:171], v207 offset:18432
	ds_read_b128 v[172:175], v207 offset:19456
	ds_read_b128 v[186:189], v207 offset:20480
	ds_read_b128 v[190:193], v207 offset:21504
	ds_read_b128 v[194:197], v207 offset:22528
	ds_read_b128 v[198:201], v207 offset:23552
	global_load_lds_dwordx4 v[178:179], off
	s_add_i32 m0, s6, 0x2000
	s_add_u32 s6, s30, 0x80000
	v_lshl_add_u64 v[202:203], s[30:31], 0, v[180:181]
	s_addc_u32 s7, s31, 0
	s_add_i32 s36, s65, s0
	global_load_lds_dwordx4 v[202:203], off
	v_lshl_add_u64 v[204:205], s[6:7], 0, v[176:177]
	s_mov_b32 m0, s36
	v_lshl_add_u64 v[208:209], s[34:35], 0, v[180:181]
	global_load_lds_dwordx4 v[204:205], off
	v_lshl_add_u64 v[204:205], s[6:7], 0, v[180:181]
	s_add_i32 m0, s36, 0x2000
	s_nop 0
	global_load_lds_dwordx4 v[204:205], off
	v_lshl_add_u64 v[204:205], s[34:35], 0, v[176:177]
	s_mov_b32 m0, s2
	s_nop 0
	global_load_lds_dwordx4 v[204:205], off
	s_mov_b32 m0, s3
	s_nop 0
	global_load_lds_dwordx4 v[208:209], off
	s_waitcnt vmcnt(8)
	s_waitcnt lgkmcnt(0)
	s_barrier
; #define PG8_STAGE(bufoff, gbase, voff) do { _Pragma("unroll") for (int _i = 0; _i < 2; ++_i) \
;         __builtin_amdgcn_global_load_lds((const unsigned*)((const char*)(gbase) + (voff)[_i]), (PG8_LAS unsigned*)(lds + (bufoff) + ldsw + _i * 8192), 16, 0, 0); } while (0)
; #define PG8_LDA(dst, b, h) do { _Pragma("unroll") for (int m = 0; m < 4; ++m) _Pragma("unroll") for (int k = 0; k < 2; ++k) dst[m][k] = *(const PG8_LAS bf16x8*)(lds + PG8_SA(b, h) + aoff + m * 2048 + k * 1024); } while (0)
; #define PG8_LDB(dst, b, h) do { _Pragma("unroll") for (int n = 0; n < 2; ++n) _Pragma("unroll") for (int k = 0; k < 2; ++k) dst[n][k] = *(const PG8_LAS bf16x8*)(lds + PG8_SB(b, h) + boff + n * 2048 + k * 1024); } while (0)
; #define PG8_MMA(ai, bj, At, Bt) do { __builtin_amdgcn_s_setprio(1); _Pragma("unroll") for (int m = 0; m < 4; ++m) _Pragma("unroll") for (int n = 0; n < 2; ++n) _Pragma("unroll") for (int k = 0; k < 2; ++k) \
;         acc[ai][bj][m][n] = __builtin_amdgcn_mfma_f32_16x16x32_bf16(Bt[n][k], At[m][k], acc[ai][bj][m][n], 0, 0, 0); __builtin_amdgcn_s_setprio(0); } while (0)
; #define PG8_WAIT_V(n) asm volatile("s_waitcnt vmcnt(" #n ")" ::: "memory")
; #define PG8_WAIT_L(n) asm volatile("s_waitcnt lgkmcnt(" #n ")" ::: "memory")
; #define PG8_BAR __builtin_amdgcn_s_barrier()
; #define PG8_SCHED __builtin_amdgcn_sched_barrier(0)
; template <class Epi, class Sched, bool ALIGN_EPI = false, bool SP2 = false>
; __device__ __forceinline__ void gemm_phase(PG8_LAS unsigned char* lds, const int Kdim  , const int Klen  , const Sched& S, const Epi& E, const int wave_s) {
;     ...
;             PG8_WAIT_V(8); PG8_WAIT_L(0); PG8_BAR; PG8_MMA(1, 0, At, B0); PG8_MMA(1, 1, At, B1); PG8_BAR; PG8_SCHED;
;             PG8_LDB(B0, 1, 0); PG8_LDB(B1, 1, 1); PG8_SCHED; PG8_LDA(At, 1, 0); PG8_STAGE(PG8_SA(0, 1), a2 + hstep, voffA);
;             PG8_WAIT_V(8); PG8_WAIT_L(0); PG8_BAR; PG8_MMA(0, 0, At, B0); PG8_MMA(0, 1, At, B1); PG8_BAR; PG8_SCHED;
	s_setprio 1
	s_waitcnt lgkmcnt(0)
	v_mfma_f32_16x16x32_bf16 v[72:75], v[128:131], v[160:163], 0
	v_mfma_f32_16x16x32_bf16 v[56:59], v[136:139], v[160:163], 0
	v_mfma_f32_16x16x32_bf16 v[44:47], v[128:131], v[168:171], 0
	v_mfma_f32_16x16x32_bf16 v[40:43], v[136:139], v[168:171], 0
	v_mfma_f32_16x16x32_bf16 v[28:31], v[128:131], v[186:189], 0
	v_mfma_f32_16x16x32_bf16 v[24:27], v[136:139], v[186:189], 0
	v_mfma_f32_16x16x32_bf16 v[12:15], v[128:131], v[194:197], 0
	v_mfma_f32_16x16x32_bf16 v[8:11], v[136:139], v[194:197], 0
	v_mfma_f32_16x16x32_bf16 v[72:75], v[132:135], v[164:167], v[72:75]
	v_mfma_f32_16x16x32_bf16 v[56:59], v[140:143], v[164:167], v[56:59]
	v_mfma_f32_16x16x32_bf16 v[44:47], v[132:135], v[172:175], v[44:47]
	v_mfma_f32_16x16x32_bf16 v[40:43], v[140:143], v[172:175], v[40:43]
	v_mfma_f32_16x16x32_bf16 v[28:31], v[132:135], v[190:193], v[28:31]
	v_mfma_f32_16x16x32_bf16 v[24:27], v[140:143], v[190:193], v[24:27]
	v_mfma_f32_16x16x32_bf16 v[12:15], v[132:135], v[198:201], v[12:15]
	v_mfma_f32_16x16x32_bf16 v[8:11], v[140:143], v[198:201], v[8:11]
	s_setprio 0
	s_setprio 1
	v_mfma_f32_16x16x32_bf16 v[52:55], v[144:147], v[160:163], 0
	v_mfma_f32_16x16x32_bf16 v[48:51], v[152:155], v[160:163], 0
	v_mfma_f32_16x16x32_bf16 v[36:39], v[144:147], v[168:171], 0
	v_mfma_f32_16x16x32_bf16 v[32:35], v[152:155], v[168:171], 0
	v_mfma_f32_16x16x32_bf16 v[20:23], v[144:147], v[186:189], 0
	v_mfma_f32_16x16x32_bf16 v[16:19], v[152:155], v[186:189], 0
	v_mfma_f32_16x16x32_bf16 v[4:7], v[144:147], v[194:197], 0
	v_mfma_f32_16x16x32_bf16 v[0:3], v[152:155], v[194:197], 0
	v_mfma_f32_16x16x32_bf16 v[52:55], v[148:151], v[164:167], v[52:55]
	v_mfma_f32_16x16x32_bf16 v[48:51], v[156:159], v[164:167], v[48:51]
	v_mfma_f32_16x16x32_bf16 v[36:39], v[148:151], v[172:175], v[36:39]
	v_mfma_f32_16x16x32_bf16 v[32:35], v[156:159], v[172:175], v[32:35]
	v_mfma_f32_16x16x32_bf16 v[20:23], v[148:151], v[190:193], v[20:23]
	v_mfma_f32_16x16x32_bf16 v[16:19], v[156:159], v[190:193], v[16:19]
	v_mfma_f32_16x16x32_bf16 v[4:7], v[148:151], v[198:201], v[4:7]
	v_mfma_f32_16x16x32_bf16 v[0:3], v[156:159], v[198:201], v[0:3]
	s_setprio 0
	s_barrier
	s_add_i32 s71, 0, 0x18000
	s_add_i32 s73, 0, 0x1c000
	v_add_u32_e32 v140, s71, v206
	v_add_u32_e32 v156, s73, v206
	ds_read_b128 v[128:131], v140
	ds_read_b128 v[132:135], v140 offset:1024
	ds_read_b128 v[136:139], v140 offset:2048
	ds_read_b128 v[140:143], v140 offset:3072
	ds_read_b128 v[144:147], v156
	ds_read_b128 v[148:151], v156 offset:1024
	ds_read_b128 v[152:155], v156 offset:2048
	ds_read_b128 v[156:159], v156 offset:3072
	s_add_u32 s6, s34, 0x80000
	s_addc_u32 s7, s35, 0
	s_mov_b32 m0, s33
	v_lshl_add_u64 v[210:211], s[6:7], 0, v[176:177]
	ds_read_b128 v[160:163], v207 offset:32768
	ds_read_b128 v[164:167], v207 offset:33792
	ds_read_b128 v[168:171], v207 offset:34816
	ds_read_b128 v[172:175], v207 offset:35840
	ds_read_b128 v[186:189], v207 offset:36864
	ds_read_b128 v[190:193], v207 offset:37888
	ds_read_b128 v[194:197], v207 offset:38912
	ds_read_b128 v[198:201], v207 offset:39936
	global_load_lds_dwordx4 v[210:211], off
	v_lshl_add_u64 v[210:211], s[6:7], 0, v[180:181]
	s_mov_b32 m0, s41
	s_nop 0
	global_load_lds_dwordx4 v[210:211], off
	s_waitcnt vmcnt(8)
	s_waitcnt lgkmcnt(0)
	s_barrier
	s_setprio 1
	s_waitcnt lgkmcnt(0)
	v_mfma_f32_16x16x32_bf16 v[76:79], v[128:131], v[160:163], v[76:79]
	v_mfma_f32_16x16x32_bf16 v[68:71], v[136:139], v[160:163], v[68:71]
	v_mfma_f32_16x16x32_bf16 v[92:95], v[128:131], v[168:171], v[92:95]
	v_mfma_f32_16x16x32_bf16 v[88:91], v[136:139], v[168:171], v[88:91]
	v_mfma_f32_16x16x32_bf16 v[104:107], v[128:131], v[186:189], v[104:107]
	v_mfma_f32_16x16x32_bf16 v[96:99], v[136:139], v[186:189], v[96:99]
	v_mfma_f32_16x16x32_bf16 v[124:127], v[128:131], v[194:197], v[124:127]
	v_mfma_f32_16x16x32_bf16 v[120:123], v[136:139], v[194:197], v[120:123]
	v_mfma_f32_16x16x32_bf16 v[76:79], v[132:135], v[164:167], v[76:79]
	v_mfma_f32_16x16x32_bf16 v[68:71], v[140:143], v[164:167], v[68:71]
	v_mfma_f32_16x16x32_bf16 v[92:95], v[132:135], v[172:175], v[92:95]
	v_mfma_f32_16x16x32_bf16 v[88:91], v[140:143], v[172:175], v[88:91]
	v_mfma_f32_16x16x32_bf16 v[104:107], v[132:135], v[190:193], v[104:107]
	v_mfma_f32_16x16x32_bf16 v[96:99], v[140:143], v[190:193], v[96:99]
	v_mfma_f32_16x16x32_bf16 v[124:127], v[132:135], v[198:201], v[124:127]
	v_mfma_f32_16x16x32_bf16 v[120:123], v[140:143], v[198:201], v[120:123]
	s_setprio 0
	s_setprio 1
	v_mfma_f32_16x16x32_bf16 v[64:67], v[144:147], v[160:163], v[64:67]
	v_mfma_f32_16x16x32_bf16 v[60:63], v[152:155], v[160:163], v[60:63]
	v_mfma_f32_16x16x32_bf16 v[84:87], v[144:147], v[168:171], v[84:87]
	v_mfma_f32_16x16x32_bf16 v[80:83], v[152:155], v[168:171], v[80:83]
	v_mfma_f32_16x16x32_bf16 v[100:103], v[144:147], v[186:189], v[100:103]
	v_mfma_f32_16x16x32_bf16 v[108:111], v[152:155], v[186:189], v[108:111]
	v_mfma_f32_16x16x32_bf16 v[116:119], v[144:147], v[194:197], v[116:119]
	v_mfma_f32_16x16x32_bf16 v[112:115], v[152:155], v[194:197], v[112:115]
	v_mfma_f32_16x16x32_bf16 v[64:67], v[148:151], v[164:167], v[64:67]
	v_mfma_f32_16x16x32_bf16 v[60:63], v[156:159], v[164:167], v[60:63]
	v_mfma_f32_16x16x32_bf16 v[84:87], v[148:151], v[172:175], v[84:87]
	v_mfma_f32_16x16x32_bf16 v[80:83], v[156:159], v[172:175], v[80:83]
	v_mfma_f32_16x16x32_bf16 v[100:103], v[148:151], v[190:193], v[100:103]
	v_mfma_f32_16x16x32_bf16 v[108:111], v[156:159], v[190:193], v[108:111]
	v_mfma_f32_16x16x32_bf16 v[116:119], v[148:151], v[198:201], v[116:119]
	v_mfma_f32_16x16x32_bf16 v[112:115], v[156:159], v[198:201], v[112:115]
	s_setprio 0
	s_barrier
; #define PG8_STAGE(bufoff, gbase, voff) do { _Pragma("unroll") for (int _i = 0; _i < 2; ++_i) \
;         __builtin_amdgcn_global_load_lds((const unsigned*)((const char*)(gbase) + (voff)[_i]), (PG8_LAS unsigned*)(lds + (bufoff) + ldsw + _i * 8192), 16, 0, 0); } while (0)
; #define PG8_LDA(dst, b, h) do { _Pragma("unroll") for (int m = 0; m < 4; ++m) _Pragma("unroll") for (int k = 0; k < 2; ++k) dst[m][k] = *(const PG8_LAS bf16x8*)(lds + PG8_SA(b, h) + aoff + m * 2048 + k * 1024); } while (0)
; #define PG8_LDB(dst, b, h) do { _Pragma("unroll") for (int n = 0; n < 2; ++n) _Pragma("unroll") for (int k = 0; k < 2; ++k) dst[n][k] = *(const PG8_LAS bf16x8*)(lds + PG8_SB(b, h) + boff + n * 2048 + k * 1024); } while (0)
; #define PG8_MMA(ai, bj, At, Bt) do { __builtin_amdgcn_s_setprio(1); _Pragma("unroll") for (int m = 0; m < 4; ++m) _Pragma("unroll") for (int n = 0; n < 2; ++n) _Pragma("unroll") for (int k = 0; k < 2; ++k) \
;         acc[ai][bj][m][n] = __builtin_amdgcn_mfma_f32_16x16x32_bf16(Bt[n][k], At[m][k], acc[ai][bj][m][n], 0, 0, 0); __builtin_amdgcn_s_setprio(0); } while (0)
; #define PG8_WAIT_V(n) asm volatile("s_waitcnt vmcnt(" #n ")" ::: "memory")
; #define PG8_WAIT_L(n) asm volatile("s_waitcnt lgkmcnt(" #n ")" ::: "memory")
; #define PG8_BAR __builtin_amdgcn_s_barrier()
; #define PG8_SCHED __builtin_amdgcn_sched_barrier(0)
; template <class Epi, class Sched, bool ALIGN_EPI = false, bool SP2 = false>
; __device__ __forceinline__ void gemm_phase(PG8_LAS unsigned char* lds, const int Kdim  , const int Klen  , const Sched& S, const Epi& E, const int wave_s) {
;     ...
;             PG8_LDB(B0, 1, 0); PG8_LDB(B1, 1, 1); PG8_SCHED; PG8_LDA(At, 1, 0); PG8_STAGE(PG8_SA(0, 1), a2 + hstep, voffA);
;             PG8_WAIT_V(8); PG8_WAIT_L(0); PG8_BAR; PG8_MMA(0, 0, At, B0); PG8_MMA(0, 1, At, B1); PG8_BAR; PG8_SCHED;
;             PG8_LDA(At, 1, 1); PG8_STAGE(PG8_SB(1, 0), b3, voffB); PG8_STAGE(PG8_SB(1, 1), b3 + hstep, voffB); PG8_STAGE(PG8_SA(1, 0), a3, voffA);
;             PG8_WAIT_V(8); PG8_WAIT_L(0); PG8_BAR; PG8_MMA(1, 0, At, B0); PG8_MMA(1, 1, At, B1); PG8_BAR; PG8_SCHED;
	s_add_i32 s6, s71, s0
	v_lshl_add_u64 v[178:179], v[178:179], 0, s[96:97]
	s_mov_b32 m0, s6
	ds_read_b128 v[160:163], v207 offset:49152
	ds_read_b128 v[164:167], v207 offset:50176
	ds_read_b128 v[168:171], v207 offset:51200
	ds_read_b128 v[172:175], v207 offset:52224
	ds_read_b128 v[186:189], v207 offset:53248
	ds_read_b128 v[190:193], v207 offset:54272
	ds_read_b128 v[194:197], v207 offset:55296
	ds_read_b128 v[198:201], v207 offset:56320
	global_load_lds_dwordx4 v[178:179], off
	s_add_i32 m0, s6, 0x2000
	s_add_u32 s6, s30, 0x80080
	v_lshl_add_u64 v[178:179], v[202:203], 0, s[96:97]
	s_addc_u32 s7, s31, 0
	s_add_i32 s30, s73, s0
	global_load_lds_dwordx4 v[178:179], off
	v_lshl_add_u64 v[178:179], s[6:7], 0, v[176:177]
	s_mov_b32 m0, s30
	s_nop 0
	global_load_lds_dwordx4 v[178:179], off
	v_lshl_add_u64 v[178:179], s[6:7], 0, v[180:181]
	s_add_i32 m0, s30, 0x2000
	s_nop 0
	global_load_lds_dwordx4 v[178:179], off
	v_lshl_add_u64 v[178:179], v[204:205], 0, s[96:97]
	s_mov_b32 m0, s94
	s_nop 0
	global_load_lds_dwordx4 v[178:179], off
	v_lshl_add_u64 v[178:179], v[208:209], 0, s[96:97]
	s_mov_b32 m0, s95
	s_nop 0
	global_load_lds_dwordx4 v[178:179], off
	s_waitcnt vmcnt(8)
	s_waitcnt lgkmcnt(0)
	s_barrier
	s_setprio 1
	s_waitcnt lgkmcnt(0)
	v_mfma_f32_16x16x32_bf16 v[72:75], v[128:131], v[160:163], v[72:75]
	v_mfma_f32_16x16x32_bf16 v[56:59], v[136:139], v[160:163], v[56:59]
	v_mfma_f32_16x16x32_bf16 v[44:47], v[128:131], v[168:171], v[44:47]
	v_mfma_f32_16x16x32_bf16 v[40:43], v[136:139], v[168:171], v[40:43]
	v_mfma_f32_16x16x32_bf16 v[28:31], v[128:131], v[186:189], v[28:31]
	v_mfma_f32_16x16x32_bf16 v[24:27], v[136:139], v[186:189], v[24:27]
	v_mfma_f32_16x16x32_bf16 v[12:15], v[128:131], v[194:197], v[12:15]
	v_mfma_f32_16x16x32_bf16 v[8:11], v[136:139], v[194:197], v[8:11]
	v_mfma_f32_16x16x32_bf16 v[72:75], v[132:135], v[164:167], v[72:75]
	v_mfma_f32_16x16x32_bf16 v[56:59], v[140:143], v[164:167], v[56:59]
	v_mfma_f32_16x16x32_bf16 v[44:47], v[132:135], v[172:175], v[44:47]
	v_mfma_f32_16x16x32_bf16 v[40:43], v[140:143], v[172:175], v[40:43]
	v_mfma_f32_16x16x32_bf16 v[28:31], v[132:135], v[190:193], v[28:31]
	v_mfma_f32_16x16x32_bf16 v[24:27], v[140:143], v[190:193], v[24:27]
	v_mfma_f32_16x16x32_bf16 v[12:15], v[132:135], v[198:201], v[12:15]
	v_mfma_f32_16x16x32_bf16 v[8:11], v[140:143], v[198:201], v[8:11]
	s_setprio 0
	s_setprio 1
	v_mfma_f32_16x16x32_bf16 v[52:55], v[144:147], v[160:163], v[52:55]
	v_mfma_f32_16x16x32_bf16 v[48:51], v[152:155], v[160:163], v[48:51]
	v_mfma_f32_16x16x32_bf16 v[36:39], v[144:147], v[168:171], v[36:39]
	v_mfma_f32_16x16x32_bf16 v[32:35], v[152:155], v[168:171], v[32:35]
	v_mfma_f32_16x16x32_bf16 v[20:23], v[144:147], v[186:189], v[20:23]
	v_mfma_f32_16x16x32_bf16 v[16:19], v[152:155], v[186:189], v[16:19]
	v_mfma_f32_16x16x32_bf16 v[4:7], v[144:147], v[194:197], v[4:7]
	v_mfma_f32_16x16x32_bf16 v[0:3], v[152:155], v[194:197], v[0:3]
	v_mfma_f32_16x16x32_bf16 v[52:55], v[148:151], v[164:167], v[52:55]
	v_mfma_f32_16x16x32_bf16 v[48:51], v[156:159], v[164:167], v[48:51]
	v_mfma_f32_16x16x32_bf16 v[36:39], v[148:151], v[172:175], v[36:39]
	v_mfma_f32_16x16x32_bf16 v[32:35], v[156:159], v[172:175], v[32:35]
	v_mfma_f32_16x16x32_bf16 v[20:23], v[148:151], v[190:193], v[20:23]
	v_mfma_f32_16x16x32_bf16 v[16:19], v[156:159], v[190:193], v[16:19]
	v_mfma_f32_16x16x32_bf16 v[4:7], v[148:151], v[198:201], v[4:7]
	v_mfma_f32_16x16x32_bf16 v[0:3], v[156:159], v[198:201], v[0:3]
	s_setprio 0
	s_barrier
	s_add_i32 s29, s29, 2
	s_add_u32 s5, s5, 0x100
	s_addc_u32 s27, s27, 0
	s_cmp_gt_u32 s29, 29
	s_mov_b64 s[6:7], s[8:9]
	s_cbranch_scc1 .Lkdone_1

; #define PG8_BAR __builtin_amdgcn_s_barrier()
; template <class Epi, class Sched, bool ALIGN_EPI = false, bool SP2 = false>
; __device__ __forceinline__ void gemm_phase(PG8_LAS unsigned char* lds, const int Kdim  , const int Klen  , const Sched& S, const Epi& E, const int wave_s) {
;     ...
;         }
;         if constexpr (ALIGN_EPI) { if (wr == 0) PG8_BAR; }
.Lkdone_1:
	s_and_b64 vcc, exec, s[24:25]
	s_cbranch_vccz .LBB0_1269
	s_barrier

; #define PG8_STAGE(bufoff, gbase, voff) do { _Pragma("unroll") for (int _i = 0; _i < 2; ++_i) \
;         __builtin_amdgcn_global_load_lds((const unsigned*)((const char*)(gbase) + (voff)[_i]), (PG8_LAS unsigned*)(lds + (bufoff) + ldsw + _i * 8192), 16, 0, 0); } while (0)
; #define PG8_LDA(dst, b, h) do { _Pragma("unroll") for (int m = 0; m < 4; ++m) _Pragma("unroll") for (int k = 0; k < 2; ++k) dst[m][k] = *(const PG8_LAS bf16x8*)(lds + PG8_SA(b, h) + aoff + m * 2048 + k * 1024); } while (0)
; #define PG8_LDB(dst, b, h) do { _Pragma("unroll") for (int n = 0; n < 2; ++n) _Pragma("unroll") for (int k = 0; k < 2; ++k) dst[n][k] = *(const PG8_LAS bf16x8*)(lds + PG8_SB(b, h) + boff + n * 2048 + k * 1024); } while (0)
; #define PG8_MMA(ai, bj, At, Bt) do { __builtin_amdgcn_s_setprio(1); _Pragma("unroll") for (int m = 0; m < 4; ++m) _Pragma("unroll") for (int n = 0; n < 2; ++n) _Pragma("unroll") for (int k = 0; k < 2; ++k) \
;         acc[ai][bj][m][n] = __builtin_amdgcn_mfma_f32_16x16x32_bf16(Bt[n][k], At[m][k], acc[ai][bj][m][n], 0, 0, 0); __builtin_amdgcn_s_setprio(0); } while (0)
; #define PG8_WAIT_V(n) asm volatile("s_waitcnt vmcnt(" #n ")" ::: "memory")
; #define PG8_WAIT_L(n) asm volatile("s_waitcnt lgkmcnt(" #n ")" ::: "memory")
; template <class Epi, class Sched, bool ALIGN_EPI = false, bool SP2 = false>
; __device__ __forceinline__ void gemm_phase(PG8_LAS unsigned char* lds, const int Kdim  , const int Klen  , const Sched& S, const Epi& E, const int wave_s) {
;     ...
;             const bool last = (t == nt - 2);
;             const char* a1 = cA + (size_t)(t + 1) * kstep;
;             const char* a2 = last ? nA : cA + (size_t)(t + 2) * kstep; const char* b2 = last ? nB : cB + (size_t)(t + 2) * kstep;
;             const char* a3 = a2 + kstep; const char* b3 = b2 + kstep;
;             if (last && has_next) S.a_ready(nxt);
;             if constexpr (SP2) {
;             PG8_LDB(B0, 0, 0); PG8_LDB(B1, 0, 1); PG8_SCHED; PG8_LDA(At, 0, 0); PG8_STAGE(PG8_SA(1, 1), a1 + hstep, voffA);
;             PG8_WAIT_V(8); PG8_WAIT_L(0); PG8_BAR; PG8_MMA(0, 0, At, B0); PG8_MMA(0, 1, At, B1); PG8_BAR; PG8_SCHED;
;             PG8_LDA(At, 0, 1); PG8_STAGE(PG8_SB(0, 0), b2, voffB); PG8_STAGE(PG8_SB(0, 1), b2 + hstep, voffB); PG8_STAGE(PG8_SA(0, 0), a2, voffA);
;             PG8_WAIT_V(8); PG8_WAIT_L(0); PG8_BAR; PG8_MMA(1, 0, At, B0); PG8_MMA(1, 1, At, B1); PG8_BAR; PG8_SCHED;
.LBB0_1327:
	s_add_u32 s13, s28, 0x100
	s_addc_u32 s17, s29, 0
	s_mov_b32 s19, -2
	v_add_u32_e32 v132, s90, v156
	v_add_u32_e32 v154, s65, v156
	ds_read_b128 v[112:115], v132
	ds_read_b128 v[116:119], v132 offset:1024
	ds_read_b128 v[120:123], v132 offset:2048
	ds_read_b128 v[132:135], v132 offset:3072
	ds_read_b128 v[150:153], v154
	ds_read_b128 v[158:161], v154 offset:1024
	ds_read_b128 v[162:165], v154 offset:2048
	ds_read_b128 v[166:169], v154 offset:3072
	s_add_u32 s28, s26, 0x100
	s_addc_u32 s29, s27, 0
	s_cmp_eq_u32 s19, 4
	s_cselect_b32 s35, s21, s29
	s_cselect_b32 s34, s20, s28
	s_cselect_b32 s31, s23, s17
	s_cselect_b32 s30, s22, s13
	v_lshl_add_u64 v[154:155], s[26:27], 0, v[146:147]
	s_add_i32 m0, s2, 0xc000
	ds_read_b128 v[170:173], v157
	ds_read_b128 v[178:181], v157 offset:1024
	ds_read_b128 v[182:185], v157 offset:2048
	ds_read_b128 v[186:189], v157 offset:3072
	ds_read_b128 v[190:193], v157 offset:4096
	ds_read_b128 v[194:197], v157 offset:5120
	ds_read_b128 v[198:201], v157 offset:6144
	ds_read_b128 v[202:205], v157 offset:7168
	global_load_lds_dwordx4 v[154:155], off
	v_lshl_add_u64 v[154:155], s[26:27], 0, v[148:149]
	s_add_i32 m0, s2, 0xe000
	s_nop 0
	global_load_lds_dwordx4 v[154:155], off
	s_waitcnt vmcnt(8)
	s_waitcnt lgkmcnt(0)
	s_barrier
	s_setprio 1
	s_waitcnt lgkmcnt(0)
	v_mfma_f32_16x16x32_bf16 v[140:143], v[112:115], v[170:173], 0
	v_mfma_f32_16x16x32_bf16 v[136:139], v[120:123], v[170:173], 0
	v_mfma_f32_16x16x32_bf16 v[108:111], v[112:115], v[182:185], 0
	v_mfma_f32_16x16x32_bf16 v[104:107], v[120:123], v[182:185], 0
	v_mfma_f32_16x16x32_bf16 v[92:95], v[112:115], v[190:193], 0
	v_mfma_f32_16x16x32_bf16 v[88:91], v[120:123], v[190:193], 0
	v_mfma_f32_16x16x32_bf16 v[76:79], v[112:115], v[198:201], 0
	v_mfma_f32_16x16x32_bf16 v[72:75], v[120:123], v[198:201], 0
	v_mfma_f32_16x16x32_bf16 v[140:143], v[116:119], v[178:181], v[140:143]
	v_mfma_f32_16x16x32_bf16 v[136:139], v[132:135], v[178:181], v[136:139]
	v_mfma_f32_16x16x32_bf16 v[108:111], v[116:119], v[186:189], v[108:111]
	v_mfma_f32_16x16x32_bf16 v[104:107], v[132:135], v[186:189], v[104:107]
	v_mfma_f32_16x16x32_bf16 v[92:95], v[116:119], v[194:197], v[92:95]
	v_mfma_f32_16x16x32_bf16 v[88:91], v[132:135], v[194:197], v[88:91]
	v_mfma_f32_16x16x32_bf16 v[76:79], v[116:119], v[202:205], v[76:79]
	v_mfma_f32_16x16x32_bf16 v[72:75], v[132:135], v[202:205], v[72:75]
	s_setprio 0
	s_setprio 1
	v_mfma_f32_16x16x32_bf16 v[128:131], v[150:153], v[170:173], 0
	v_mfma_f32_16x16x32_bf16 v[124:127], v[162:165], v[170:173], 0
	v_mfma_f32_16x16x32_bf16 v[100:103], v[150:153], v[182:185], 0
	v_mfma_f32_16x16x32_bf16 v[96:99], v[162:165], v[182:185], 0
	v_mfma_f32_16x16x32_bf16 v[84:87], v[150:153], v[190:193], 0
	v_mfma_f32_16x16x32_bf16 v[80:83], v[162:165], v[190:193], 0
	v_mfma_f32_16x16x32_bf16 v[68:71], v[150:153], v[198:201], 0
	v_mfma_f32_16x16x32_bf16 v[64:67], v[162:165], v[198:201], 0
	v_mfma_f32_16x16x32_bf16 v[128:131], v[158:161], v[178:181], v[128:131]
	v_mfma_f32_16x16x32_bf16 v[124:127], v[166:169], v[178:181], v[124:127]
	v_mfma_f32_16x16x32_bf16 v[100:103], v[158:161], v[186:189], v[100:103]
	v_mfma_f32_16x16x32_bf16 v[96:99], v[166:169], v[186:189], v[96:99]
	v_mfma_f32_16x16x32_bf16 v[84:87], v[158:161], v[194:197], v[84:87]
	v_mfma_f32_16x16x32_bf16 v[80:83], v[166:169], v[194:197], v[80:83]
	v_mfma_f32_16x16x32_bf16 v[68:71], v[158:161], v[202:205], v[68:71]
	v_mfma_f32_16x16x32_bf16 v[64:67], v[166:169], v[202:205], v[64:67]
	s_setprio 0
	s_barrier
	s_add_i32 s26, s90, s0
	v_lshl_add_u64 v[154:155], s[30:31], 0, v[176:177]
	s_mov_b32 m0, s26
	ds_read_b128 v[170:173], v157 offset:16384
	ds_read_b128 v[178:181], v157 offset:17408
	ds_read_b128 v[182:185], v157 offset:18432
	ds_read_b128 v[186:189], v157 offset:19456
	ds_read_b128 v[190:193], v157 offset:20480
	ds_read_b128 v[194:197], v157 offset:21504
	ds_read_b128 v[198:201], v157 offset:22528
	ds_read_b128 v[202:205], v157 offset:23552
	global_load_lds_dwordx4 v[154:155], off
	s_add_i32 m0, s26, 0x2000
	s_add_u32 s26, s30, 0x80000
	v_lshl_add_u64 v[174:175], s[30:31], 0, v[144:145]
	s_addc_u32 s27, s31, 0
	s_add_i32 s58, s65, s0
	global_load_lds_dwordx4 v[174:175], off
	v_lshl_add_u64 v[206:207], s[26:27], 0, v[176:177]
	s_mov_b32 m0, s58
	v_lshl_add_u64 v[208:209], s[34:35], 0, v[144:145]
	global_load_lds_dwordx4 v[206:207], off
	v_lshl_add_u64 v[206:207], s[26:27], 0, v[144:145]
	s_add_i32 m0, s58, 0x2000
	s_nop 0
	global_load_lds_dwordx4 v[206:207], off
	v_lshl_add_u64 v[206:207], s[34:35], 0, v[176:177]
	s_mov_b32 m0, s2
	s_nop 0
	global_load_lds_dwordx4 v[206:207], off
	s_mov_b32 m0, s3
	s_nop 0
	global_load_lds_dwordx4 v[208:209], off
	s_waitcnt vmcnt(8)
	s_waitcnt lgkmcnt(0)
	s_barrier
; #define PG8_STAGE(bufoff, gbase, voff) do { _Pragma("unroll") for (int _i = 0; _i < 2; ++_i) \
;         __builtin_amdgcn_global_load_lds((const unsigned*)((const char*)(gbase) + (voff)[_i]), (PG8_LAS unsigned*)(lds + (bufoff) + ldsw + _i * 8192), 16, 0, 0); } while (0)
; #define PG8_LDA(dst, b, h) do { _Pragma("unroll") for (int m = 0; m < 4; ++m) _Pragma("unroll") for (int k = 0; k < 2; ++k) dst[m][k] = *(const PG8_LAS bf16x8*)(lds + PG8_SA(b, h) + aoff + m * 2048 + k * 1024); } while (0)
; #define PG8_LDB(dst, b, h) do { _Pragma("unroll") for (int n = 0; n < 2; ++n) _Pragma("unroll") for (int k = 0; k < 2; ++k) dst[n][k] = *(const PG8_LAS bf16x8*)(lds + PG8_SB(b, h) + boff + n * 2048 + k * 1024); } while (0)
; #define PG8_MMA(ai, bj, At, Bt) do { __builtin_amdgcn_s_setprio(1); _Pragma("unroll") for (int m = 0; m < 4; ++m) _Pragma("unroll") for (int n = 0; n < 2; ++n) _Pragma("unroll") for (int k = 0; k < 2; ++k) \
;         acc[ai][bj][m][n] = __builtin_amdgcn_mfma_f32_16x16x32_bf16(Bt[n][k], At[m][k], acc[ai][bj][m][n], 0, 0, 0); __builtin_amdgcn_s_setprio(0); } while (0)
; #define PG8_WAIT_V(n) asm volatile("s_waitcnt vmcnt(" #n ")" ::: "memory")
; #define PG8_WAIT_L(n) asm volatile("s_waitcnt lgkmcnt(" #n ")" ::: "memory")
; #define PG8_BAR __builtin_amdgcn_s_barrier()
; #define PG8_SCHED __builtin_amdgcn_sched_barrier(0)
; template <class Epi, class Sched, bool ALIGN_EPI = false, bool SP2 = false>
; __device__ __forceinline__ void gemm_phase(PG8_LAS unsigned char* lds, const int Kdim  , const int Klen  , const Sched& S, const Epi& E, const int wave_s) {
;     ...
;             PG8_WAIT_V(8); PG8_WAIT_L(0); PG8_BAR; PG8_MMA(1, 0, At, B0); PG8_MMA(1, 1, At, B1); PG8_BAR; PG8_SCHED;
;             PG8_LDB(B0, 1, 0); PG8_LDB(B1, 1, 1); PG8_SCHED; PG8_LDA(At, 1, 0); PG8_STAGE(PG8_SA(0, 1), a2 + hstep, voffA);
;             PG8_WAIT_V(8); PG8_WAIT_L(0); PG8_BAR; PG8_MMA(0, 0, At, B0); PG8_MMA(0, 1, At, B1); PG8_BAR; PG8_SCHED;
	s_setprio 1
	s_waitcnt lgkmcnt(0)
	v_mfma_f32_16x16x32_bf16 v[60:63], v[112:115], v[170:173], 0
	v_mfma_f32_16x16x32_bf16 v[56:59], v[120:123], v[170:173], 0
	v_mfma_f32_16x16x32_bf16 v[52:55], v[112:115], v[182:185], 0
	v_mfma_f32_16x16x32_bf16 v[40:43], v[120:123], v[182:185], 0
	v_mfma_f32_16x16x32_bf16 v[36:39], v[112:115], v[190:193], 0
	v_mfma_f32_16x16x32_bf16 v[24:27], v[120:123], v[190:193], 0
	v_mfma_f32_16x16x32_bf16 v[20:23], v[112:115], v[198:201], 0
	v_mfma_f32_16x16x32_bf16 v[8:11], v[120:123], v[198:201], 0
	v_mfma_f32_16x16x32_bf16 v[60:63], v[116:119], v[178:181], v[60:63]
	v_mfma_f32_16x16x32_bf16 v[56:59], v[132:135], v[178:181], v[56:59]
	v_mfma_f32_16x16x32_bf16 v[52:55], v[116:119], v[186:189], v[52:55]
	v_mfma_f32_16x16x32_bf16 v[40:43], v[132:135], v[186:189], v[40:43]
	v_mfma_f32_16x16x32_bf16 v[36:39], v[116:119], v[194:197], v[36:39]
	v_mfma_f32_16x16x32_bf16 v[24:27], v[132:135], v[194:197], v[24:27]
	v_mfma_f32_16x16x32_bf16 v[20:23], v[116:119], v[202:205], v[20:23]
	v_mfma_f32_16x16x32_bf16 v[8:11], v[132:135], v[202:205], v[8:11]
	s_setprio 0
	s_setprio 1
	v_mfma_f32_16x16x32_bf16 v[48:51], v[150:153], v[170:173], 0
	v_mfma_f32_16x16x32_bf16 v[44:47], v[162:165], v[170:173], 0
	v_mfma_f32_16x16x32_bf16 v[32:35], v[150:153], v[182:185], 0
	v_mfma_f32_16x16x32_bf16 v[28:31], v[162:165], v[182:185], 0
	v_mfma_f32_16x16x32_bf16 v[16:19], v[150:153], v[190:193], 0
	v_mfma_f32_16x16x32_bf16 v[12:15], v[162:165], v[190:193], 0
	v_mfma_f32_16x16x32_bf16 v[4:7], v[150:153], v[198:201], 0
	v_mfma_f32_16x16x32_bf16 v[0:3], v[162:165], v[198:201], 0
	v_mfma_f32_16x16x32_bf16 v[48:51], v[158:161], v[178:181], v[48:51]
	v_mfma_f32_16x16x32_bf16 v[44:47], v[166:169], v[178:181], v[44:47]
	v_mfma_f32_16x16x32_bf16 v[32:35], v[158:161], v[186:189], v[32:35]
	v_mfma_f32_16x16x32_bf16 v[28:31], v[166:169], v[186:189], v[28:31]
	v_mfma_f32_16x16x32_bf16 v[16:19], v[158:161], v[194:197], v[16:19]
	v_mfma_f32_16x16x32_bf16 v[12:15], v[166:169], v[194:197], v[12:15]
	v_mfma_f32_16x16x32_bf16 v[4:7], v[158:161], v[202:205], v[4:7]
	v_mfma_f32_16x16x32_bf16 v[0:3], v[166:169], v[202:205], v[0:3]
	s_setprio 0
	s_barrier
	v_add_u32_e32 v132, s71, v156
	v_add_u32_e32 v166, s73, v156
	ds_read_b128 v[112:115], v132
	ds_read_b128 v[116:119], v132 offset:1024
	ds_read_b128 v[120:123], v132 offset:2048
	ds_read_b128 v[132:135], v132 offset:3072
	ds_read_b128 v[150:153], v166
	ds_read_b128 v[158:161], v166 offset:1024
	ds_read_b128 v[162:165], v166 offset:2048
	ds_read_b128 v[166:169], v166 offset:3072
	s_add_u32 s26, s34, 0x80000
	s_addc_u32 s27, s35, 0
	s_mov_b32 m0, s33
	v_lshl_add_u64 v[210:211], s[26:27], 0, v[176:177]
	ds_read_b128 v[170:173], v157 offset:32768
	ds_read_b128 v[178:181], v157 offset:33792
	ds_read_b128 v[182:185], v157 offset:34816
	ds_read_b128 v[186:189], v157 offset:35840
	ds_read_b128 v[190:193], v157 offset:36864
	ds_read_b128 v[194:197], v157 offset:37888
	ds_read_b128 v[198:201], v157 offset:38912
	ds_read_b128 v[202:205], v157 offset:39936
	global_load_lds_dwordx4 v[210:211], off
	v_lshl_add_u64 v[210:211], s[26:27], 0, v[144:145]
	s_mov_b32 m0, s36
	s_nop 0
	global_load_lds_dwordx4 v[210:211], off
	s_waitcnt vmcnt(8)
	s_waitcnt lgkmcnt(0)
	s_barrier
	s_setprio 1
	s_waitcnt lgkmcnt(0)
	v_mfma_f32_16x16x32_bf16 v[140:143], v[112:115], v[170:173], v[140:143]
	v_mfma_f32_16x16x32_bf16 v[136:139], v[120:123], v[170:173], v[136:139]
	v_mfma_f32_16x16x32_bf16 v[108:111], v[112:115], v[182:185], v[108:111]
	v_mfma_f32_16x16x32_bf16 v[104:107], v[120:123], v[182:185], v[104:107]
	v_mfma_f32_16x16x32_bf16 v[92:95], v[112:115], v[190:193], v[92:95]
	v_mfma_f32_16x16x32_bf16 v[88:91], v[120:123], v[190:193], v[88:91]
	v_mfma_f32_16x16x32_bf16 v[76:79], v[112:115], v[198:201], v[76:79]
	v_mfma_f32_16x16x32_bf16 v[72:75], v[120:123], v[198:201], v[72:75]
	v_mfma_f32_16x16x32_bf16 v[140:143], v[116:119], v[178:181], v[140:143]
	v_mfma_f32_16x16x32_bf16 v[136:139], v[132:135], v[178:181], v[136:139]
	v_mfma_f32_16x16x32_bf16 v[108:111], v[116:119], v[186:189], v[108:111]
	v_mfma_f32_16x16x32_bf16 v[104:107], v[132:135], v[186:189], v[104:107]
	v_mfma_f32_16x16x32_bf16 v[92:95], v[116:119], v[194:197], v[92:95]
	v_mfma_f32_16x16x32_bf16 v[88:91], v[132:135], v[194:197], v[88:91]
	v_mfma_f32_16x16x32_bf16 v[76:79], v[116:119], v[202:205], v[76:79]
	v_mfma_f32_16x16x32_bf16 v[72:75], v[132:135], v[202:205], v[72:75]
	s_setprio 0
	s_setprio 1
	v_mfma_f32_16x16x32_bf16 v[128:131], v[150:153], v[170:173], v[128:131]
	v_mfma_f32_16x16x32_bf16 v[124:127], v[162:165], v[170:173], v[124:127]
	v_mfma_f32_16x16x32_bf16 v[100:103], v[150:153], v[182:185], v[100:103]
	v_mfma_f32_16x16x32_bf16 v[96:99], v[162:165], v[182:185], v[96:99]
	v_mfma_f32_16x16x32_bf16 v[84:87], v[150:153], v[190:193], v[84:87]
	v_mfma_f32_16x16x32_bf16 v[80:83], v[162:165], v[190:193], v[80:83]
	v_mfma_f32_16x16x32_bf16 v[68:71], v[150:153], v[198:201], v[68:71]
	v_mfma_f32_16x16x32_bf16 v[64:67], v[162:165], v[198:201], v[64:67]
	v_mfma_f32_16x16x32_bf16 v[128:131], v[158:161], v[178:181], v[128:131]
	v_mfma_f32_16x16x32_bf16 v[124:127], v[166:169], v[178:181], v[124:127]
	v_mfma_f32_16x16x32_bf16 v[100:103], v[158:161], v[186:189], v[100:103]
	v_mfma_f32_16x16x32_bf16 v[96:99], v[166:169], v[186:189], v[96:99]
	v_mfma_f32_16x16x32_bf16 v[84:87], v[158:161], v[194:197], v[84:87]
	v_mfma_f32_16x16x32_bf16 v[80:83], v[166:169], v[194:197], v[80:83]
	v_mfma_f32_16x16x32_bf16 v[68:71], v[158:161], v[202:205], v[68:71]
	v_mfma_f32_16x16x32_bf16 v[64:67], v[166:169], v[202:205], v[64:67]
	s_setprio 0
	s_barrier
; #define PG8_STAGE(bufoff, gbase, voff) do { _Pragma("unroll") for (int _i = 0; _i < 2; ++_i) \
;         __builtin_amdgcn_global_load_lds((const unsigned*)((const char*)(gbase) + (voff)[_i]), (PG8_LAS unsigned*)(lds + (bufoff) + ldsw + _i * 8192), 16, 0, 0); } while (0)
; #define PG8_LDA(dst, b, h) do { _Pragma("unroll") for (int m = 0; m < 4; ++m) _Pragma("unroll") for (int k = 0; k < 2; ++k) dst[m][k] = *(const PG8_LAS bf16x8*)(lds + PG8_SA(b, h) + aoff + m * 2048 + k * 1024); } while (0)
; #define PG8_LDB(dst, b, h) do { _Pragma("unroll") for (int n = 0; n < 2; ++n) _Pragma("unroll") for (int k = 0; k < 2; ++k) dst[n][k] = *(const PG8_LAS bf16x8*)(lds + PG8_SB(b, h) + boff + n * 2048 + k * 1024); } while (0)
; #define PG8_MMA(ai, bj, At, Bt) do { __builtin_amdgcn_s_setprio(1); _Pragma("unroll") for (int m = 0; m < 4; ++m) _Pragma("unroll") for (int n = 0; n < 2; ++n) _Pragma("unroll") for (int k = 0; k < 2; ++k) \
;         acc[ai][bj][m][n] = __builtin_amdgcn_mfma_f32_16x16x32_bf16(Bt[n][k], At[m][k], acc[ai][bj][m][n], 0, 0, 0); __builtin_amdgcn_s_setprio(0); } while (0)
; #define PG8_WAIT_V(n) asm volatile("s_waitcnt vmcnt(" #n ")" ::: "memory")
; #define PG8_WAIT_L(n) asm volatile("s_waitcnt lgkmcnt(" #n ")" ::: "memory")
; #define PG8_BAR __builtin_amdgcn_s_barrier()
; #define PG8_SCHED __builtin_amdgcn_sched_barrier(0)
; template <class Epi, class Sched, bool ALIGN_EPI = false, bool SP2 = false>
; __device__ __forceinline__ void gemm_phase(PG8_LAS unsigned char* lds, const int Kdim  , const int Klen  , const Sched& S, const Epi& E, const int wave_s) {
;     ...
;             PG8_LDB(B0, 1, 0); PG8_LDB(B1, 1, 1); PG8_SCHED; PG8_LDA(At, 1, 0); PG8_STAGE(PG8_SA(0, 1), a2 + hstep, voffA);
;             PG8_WAIT_V(8); PG8_WAIT_L(0); PG8_BAR; PG8_MMA(0, 0, At, B0); PG8_MMA(0, 1, At, B1); PG8_BAR; PG8_SCHED;
;             PG8_LDA(At, 1, 1); PG8_STAGE(PG8_SB(1, 0), b3, voffB); PG8_STAGE(PG8_SB(1, 1), b3 + hstep, voffB); PG8_STAGE(PG8_SA(1, 0), a3, voffA);
;             PG8_WAIT_V(8); PG8_WAIT_L(0); PG8_BAR; PG8_MMA(1, 0, At, B0); PG8_MMA(1, 1, At, B1); PG8_BAR; PG8_SCHED;
	s_add_i32 s26, s71, s0
	v_lshl_add_u64 v[154:155], v[154:155], 0, s[96:97]
	s_mov_b32 m0, s26
	ds_read_b128 v[170:173], v157 offset:49152
	ds_read_b128 v[178:181], v157 offset:50176
	ds_read_b128 v[182:185], v157 offset:51200
	ds_read_b128 v[186:189], v157 offset:52224
	ds_read_b128 v[190:193], v157 offset:53248
	ds_read_b128 v[194:197], v157 offset:54272
	ds_read_b128 v[198:201], v157 offset:55296
	ds_read_b128 v[202:205], v157 offset:56320
	global_load_lds_dwordx4 v[154:155], off
	s_add_i32 m0, s26, 0x2000
	s_add_u32 s26, s30, 0x80080
	v_lshl_add_u64 v[154:155], v[174:175], 0, s[96:97]
	s_addc_u32 s27, s31, 0
	s_add_i32 s30, s73, s0
	global_load_lds_dwordx4 v[154:155], off
	v_lshl_add_u64 v[154:155], s[26:27], 0, v[176:177]
	s_mov_b32 m0, s30
	s_nop 0
	global_load_lds_dwordx4 v[154:155], off
	v_lshl_add_u64 v[154:155], s[26:27], 0, v[144:145]
	s_add_i32 m0, s30, 0x2000
	s_nop 0
	global_load_lds_dwordx4 v[154:155], off
	v_lshl_add_u64 v[154:155], v[206:207], 0, s[96:97]
	s_mov_b32 m0, s39
	s_nop 0
	global_load_lds_dwordx4 v[154:155], off
	v_lshl_add_u64 v[154:155], v[208:209], 0, s[96:97]
	s_mov_b32 m0, s41
	s_nop 0
	global_load_lds_dwordx4 v[154:155], off
	s_waitcnt vmcnt(8)
	s_waitcnt lgkmcnt(0)
	s_barrier
	s_setprio 1
	s_waitcnt lgkmcnt(0)
	v_mfma_f32_16x16x32_bf16 v[60:63], v[112:115], v[170:173], v[60:63]
	v_mfma_f32_16x16x32_bf16 v[56:59], v[120:123], v[170:173], v[56:59]
	v_mfma_f32_16x16x32_bf16 v[52:55], v[112:115], v[182:185], v[52:55]
	v_mfma_f32_16x16x32_bf16 v[40:43], v[120:123], v[182:185], v[40:43]
	v_mfma_f32_16x16x32_bf16 v[36:39], v[112:115], v[190:193], v[36:39]
	v_mfma_f32_16x16x32_bf16 v[24:27], v[120:123], v[190:193], v[24:27]
	v_mfma_f32_16x16x32_bf16 v[20:23], v[112:115], v[198:201], v[20:23]
	v_mfma_f32_16x16x32_bf16 v[8:11], v[120:123], v[198:201], v[8:11]
	v_mfma_f32_16x16x32_bf16 v[60:63], v[116:119], v[178:181], v[60:63]
	v_mfma_f32_16x16x32_bf16 v[56:59], v[132:135], v[178:181], v[56:59]
	v_mfma_f32_16x16x32_bf16 v[52:55], v[116:119], v[186:189], v[52:55]
	v_mfma_f32_16x16x32_bf16 v[40:43], v[132:135], v[186:189], v[40:43]
	v_mfma_f32_16x16x32_bf16 v[36:39], v[116:119], v[194:197], v[36:39]
	v_mfma_f32_16x16x32_bf16 v[24:27], v[132:135], v[194:197], v[24:27]
	v_mfma_f32_16x16x32_bf16 v[20:23], v[116:119], v[202:205], v[20:23]
	v_mfma_f32_16x16x32_bf16 v[8:11], v[132:135], v[202:205], v[8:11]
	s_setprio 0
	s_setprio 1
	v_mfma_f32_16x16x32_bf16 v[48:51], v[150:153], v[170:173], v[48:51]
	v_mfma_f32_16x16x32_bf16 v[44:47], v[162:165], v[170:173], v[44:47]
	v_mfma_f32_16x16x32_bf16 v[32:35], v[150:153], v[182:185], v[32:35]
	v_mfma_f32_16x16x32_bf16 v[28:31], v[162:165], v[182:185], v[28:31]
	v_mfma_f32_16x16x32_bf16 v[16:19], v[150:153], v[190:193], v[16:19]
	v_mfma_f32_16x16x32_bf16 v[12:15], v[162:165], v[190:193], v[12:15]
	v_mfma_f32_16x16x32_bf16 v[4:7], v[150:153], v[198:201], v[4:7]
	v_mfma_f32_16x16x32_bf16 v[0:3], v[162:165], v[198:201], v[0:3]
	v_mfma_f32_16x16x32_bf16 v[48:51], v[158:161], v[178:181], v[48:51]
	v_mfma_f32_16x16x32_bf16 v[44:47], v[166:169], v[178:181], v[44:47]
	v_mfma_f32_16x16x32_bf16 v[32:35], v[158:161], v[186:189], v[32:35]
	v_mfma_f32_16x16x32_bf16 v[28:31], v[166:169], v[186:189], v[28:31]
	v_mfma_f32_16x16x32_bf16 v[16:19], v[158:161], v[194:197], v[16:19]
	v_mfma_f32_16x16x32_bf16 v[12:15], v[166:169], v[194:197], v[12:15]
	v_mfma_f32_16x16x32_bf16 v[4:7], v[158:161], v[202:205], v[4:7]
	v_mfma_f32_16x16x32_bf16 v[0:3], v[166:169], v[202:205], v[0:3]
	s_setprio 0
	s_barrier
	s_add_i32 s19, s19, 2
	s_add_u32 s13, s13, 0x100
	s_addc_u32 s17, s17, 0
	s_cmp_gt_u32 s19, 5
	s_mov_b64 s[26:27], s[28:29]
	s_cbranch_scc1 .Lkdone_2

; #define PG8_BAR __builtin_amdgcn_s_barrier()
; template <class Epi, class Sched, bool ALIGN_EPI = false, bool SP2 = false>
; __device__ __forceinline__ void gemm_phase(PG8_LAS unsigned char* lds, const int Kdim  , const int Klen  , const Sched& S, const Epi& E, const int wave_s) {
;     ...
;         }
;         if constexpr (ALIGN_EPI) { if (wr == 0) PG8_BAR; }
.Lkdone_2:
	s_and_b64 vcc, exec, s[8:9]
	s_cbranch_vccz .LBB0_1331
	s_barrier

;     __device__ __forceinline__ const char* a_ptr(const Unit& u) const { return (u.type ? A2 : A1) + (size_t)u.pm * tstep; }
;     __device__ __forceinline__ const char* b_ptr(const Unit& u) const { return (u.type ? B2 : B1) + (size_t)u.pn * tstep; }
;     __device__ __forceinline__ bool next(int i, Unit& u) const { if (i >= 4) return false; const int x = c & 7, y = c >> 3; const int p = 32 * i + 4 * x + (y >> 3); u.pm = r ? 127 - p : p; u.pn = y & 7; u.type = 0; return true; }
; #define PG8_STAGE(bufoff, gbase, voff) do { _Pragma("unroll") for (int _i = 0; _i < 2; ++_i) \
;         __builtin_amdgcn_global_load_lds((const unsigned*)((const char*)(gbase) + (voff)[_i]), (PG8_LAS unsigned*)(lds + (bufoff) + ldsw + _i * 8192), 16, 0, 0); } while (0)
; #define PG8_LDA(dst, b, h) do { _Pragma("unroll") for (int m = 0; m < 4; ++m) _Pragma("unroll") for (int k = 0; k < 2; ++k) dst[m][k] = *(const PG8_LAS bf16x8*)(lds + PG8_SA(b, h) + aoff + m * 2048 + k * 1024); } while (0)
; #define PG8_BAR __builtin_amdgcn_s_barrier()
; template <class Epi, class Sched, bool ALIGN_EPI = false, bool SP2 = false>
; __device__ __forceinline__ void gemm_phase(PG8_LAS unsigned char* lds, const int Kdim  , const int Klen  , const Sched& S, const Epi& E, const int wave_s) {
;     ...
;         const bool has_next = S.next(ui + 1, nxt);
;         const char* nA = has_next ? S.a_ptr(nxt) : cA; const char* nB = has_next ? S.b_ptr(nxt) : cB;
;         for (int t = 0; t < nt; t += 2) {
;             const bool last = (t == nt - 2);
;             const char* a1 = cA + (size_t)(t + 1) * kstep;
;             const char* a2 = last ? nA : cA + (size_t)(t + 2) * kstep; const char* b2 = last ? nB : cB + (size_t)(t + 2) * kstep;
;             const char* a3 = a2 + kstep; const char* b3 = b2 + kstep;
;             if (last && has_next) S.a_ready(nxt);
;             if constexpr (SP2) {
;             PG8_LDB(B0, 0, 0); PG8_LDB(B1, 0, 1); PG8_SCHED; PG8_LDA(At, 0, 0); PG8_STAGE(PG8_SA(1, 1), a1 + hstep, voffA);
;             PG8_WAIT_V(8); PG8_WAIT_L(0); PG8_BAR; PG8_MMA(0, 0, At, B0); PG8_MMA(0, 1, At, B1); PG8_BAR; PG8_SCHED;
;             PG8_LDA(At, 0, 1); PG8_STAGE(PG8_SB(0, 0), b2, voffB); PG8_STAGE(PG8_SB(0, 1), b2 + hstep, voffB); PG8_STAGE(PG8_SA(0, 0), a2, voffA);
;             PG8_WAIT_V(8); PG8_WAIT_L(0); PG8_BAR; PG8_MMA(1, 0, At, B0); PG8_MMA(1, 1, At, B1); PG8_BAR; PG8_SCHED;
.LBB0_1450:
	s_ashr_i32 s39, s38, 31
	s_lshl_b64 s[4:5], s[38:39], 20
	s_add_u32 s78, s14, s4
	s_addc_u32 s79, s15, s5
	s_and_b64 s[4:5], s[6:7], exec
	s_cselect_b32 s9, s79, s13
	s_cselect_b32 s11, s78, s12
	s_ashr_i32 s37, s36, 31
	s_lshl_b64 s[4:5], s[36:37], 20
	s_add_u32 s4, s95, s4
	s_addc_u32 s5, s41, s5
	s_and_b64 s[58:59], s[6:7], exec
	s_cselect_b32 s37, s5, s63
	s_cselect_b32 s39, s4, s62
	s_add_u32 s12, s12, 0x80080
	s_addc_u32 s13, s13, 0
	s_add_u32 s58, s62, 0x100
	s_addc_u32 s59, s63, 0
	s_mov_b32 s92, -2
	v_add_u32_e32 v132, s90, v246
	v_add_u32_e32 v168, s65, v246
	ds_read_b128 v[120:123], v132
	ds_read_b128 v[124:127], v132 offset:1024
	ds_read_b128 v[128:131], v132 offset:2048
	ds_read_b128 v[132:135], v132 offset:3072
	ds_read_b128 v[144:147], v168
	ds_read_b128 v[148:151], v168 offset:1024
	ds_read_b128 v[164:167], v168 offset:2048
	ds_read_b128 v[168:171], v168 offset:3072
	s_add_u32 s30, s12, 0xfff80080
	s_addc_u32 s31, s13, -1
	s_cmp_eq_u32 s92, 28
	s_cselect_b32 vcc_hi, s9, s31
	s_cselect_b32 vcc_lo, s11, s30
	s_cselect_b32 s63, s37, s59
	s_cselect_b32 s62, s39, s58
	v_lshl_add_u64 v[206:207], s[12:13], 0, v[160:161]
	s_add_i32 m0, s2, 0xc000
	ds_read_b128 v[172:175], v247
	ds_read_b128 v[178:181], v247 offset:1024
	ds_read_b128 v[182:185], v247 offset:2048
	ds_read_b128 v[186:189], v247 offset:3072
	ds_read_b128 v[190:193], v247 offset:4096
	ds_read_b128 v[194:197], v247 offset:5120
	ds_read_b128 v[198:201], v247 offset:6144
	ds_read_b128 v[202:205], v247 offset:7168
	global_load_lds_dwordx4 v[206:207], off
	v_lshl_add_u64 v[206:207], s[12:13], 0, v[162:163]
	s_add_i32 m0, s2, 0xe000
	s_nop 0
	global_load_lds_dwordx4 v[206:207], off
	s_waitcnt vmcnt(8)
	s_waitcnt lgkmcnt(0)
	s_barrier
	s_setprio 1
	s_waitcnt lgkmcnt(0)
	v_mfma_f32_16x16x32_bf16 v[140:143], v[120:123], v[172:175], 0
	v_mfma_f32_16x16x32_bf16 v[116:119], v[128:131], v[172:175], 0
	v_mfma_f32_16x16x32_bf16 v[84:87], v[120:123], v[182:185], 0
	v_mfma_f32_16x16x32_bf16 v[100:103], v[128:131], v[182:185], 0
	v_mfma_f32_16x16x32_bf16 v[80:83], v[120:123], v[190:193], 0
	v_mfma_f32_16x16x32_bf16 v[96:99], v[128:131], v[190:193], 0
	v_mfma_f32_16x16x32_bf16 v[136:139], v[120:123], v[198:201], 0
	v_mfma_f32_16x16x32_bf16 v[112:115], v[128:131], v[198:201], 0
	v_mfma_f32_16x16x32_bf16 v[140:143], v[124:127], v[178:181], v[140:143]
	v_mfma_f32_16x16x32_bf16 v[116:119], v[132:135], v[178:181], v[116:119]
	v_mfma_f32_16x16x32_bf16 v[84:87], v[124:127], v[186:189], v[84:87]
	v_mfma_f32_16x16x32_bf16 v[100:103], v[132:135], v[186:189], v[100:103]
	v_mfma_f32_16x16x32_bf16 v[80:83], v[124:127], v[194:197], v[80:83]
	v_mfma_f32_16x16x32_bf16 v[96:99], v[132:135], v[194:197], v[96:99]
	v_mfma_f32_16x16x32_bf16 v[136:139], v[124:127], v[202:205], v[136:139]
	v_mfma_f32_16x16x32_bf16 v[112:115], v[132:135], v[202:205], v[112:115]
	s_setprio 0
	s_setprio 1
	v_mfma_f32_16x16x32_bf16 v[104:107], v[144:147], v[172:175], 0
	v_mfma_f32_16x16x32_bf16 v[108:111], v[164:167], v[172:175], 0
	v_mfma_f32_16x16x32_bf16 v[76:79], v[144:147], v[182:185], 0
	v_mfma_f32_16x16x32_bf16 v[92:95], v[164:167], v[182:185], 0
	v_mfma_f32_16x16x32_bf16 v[72:75], v[144:147], v[190:193], 0
	v_mfma_f32_16x16x32_bf16 v[88:91], v[164:167], v[190:193], 0
	v_mfma_f32_16x16x32_bf16 v[64:67], v[144:147], v[198:201], 0
	v_mfma_f32_16x16x32_bf16 v[68:71], v[164:167], v[198:201], 0
	v_mfma_f32_16x16x32_bf16 v[104:107], v[148:151], v[178:181], v[104:107]
	v_mfma_f32_16x16x32_bf16 v[108:111], v[168:171], v[178:181], v[108:111]
	v_mfma_f32_16x16x32_bf16 v[76:79], v[148:151], v[186:189], v[76:79]
	v_mfma_f32_16x16x32_bf16 v[92:95], v[168:171], v[186:189], v[92:95]
	v_mfma_f32_16x16x32_bf16 v[72:75], v[148:151], v[194:197], v[72:75]
	v_mfma_f32_16x16x32_bf16 v[88:91], v[168:171], v[194:197], v[88:91]
	v_mfma_f32_16x16x32_bf16 v[64:67], v[148:151], v[202:205], v[64:67]
	v_mfma_f32_16x16x32_bf16 v[68:71], v[168:171], v[202:205], v[68:71]
	s_setprio 0
	s_barrier
	s_add_i32 s30, s90, s83
	v_lshl_add_u64 v[206:207], s[62:63], 0, v[154:155]
	s_mov_b32 m0, s30
	ds_read_b128 v[172:175], v247 offset:16384
	ds_read_b128 v[178:181], v247 offset:17408
	ds_read_b128 v[182:185], v247 offset:18432
	ds_read_b128 v[186:189], v247 offset:19456
	ds_read_b128 v[190:193], v247 offset:20480
	ds_read_b128 v[194:197], v247 offset:21504
	ds_read_b128 v[198:201], v247 offset:22528
	ds_read_b128 v[202:205], v247 offset:23552
	global_load_lds_dwordx4 v[206:207], off
	s_add_i32 m0, s30, 0x2000
	s_add_u32 s30, s62, 0x80000
	v_lshl_add_u64 v[208:209], s[62:63], 0, v[158:159]
	s_addc_u32 s31, s63, 0
	s_add_i32 s93, s65, s83
	global_load_lds_dwordx4 v[208:209], off
	v_lshl_add_u64 v[210:211], s[30:31], 0, v[154:155]
	s_mov_b32 m0, s93
	v_lshl_add_u64 v[218:219], vcc, 0, v[156:157]
	global_load_lds_dwordx4 v[210:211], off
	v_lshl_add_u64 v[210:211], s[30:31], 0, v[158:159]
	s_add_i32 m0, s93, 0x2000
	s_nop 0
	global_load_lds_dwordx4 v[210:211], off
	v_lshl_add_u64 v[210:211], vcc, 0, v[152:153]
	s_mov_b32 m0, s2
	s_nop 0
	global_load_lds_dwordx4 v[210:211], off
	s_mov_b32 m0, s33
	s_nop 0
	global_load_lds_dwordx4 v[218:219], off
	s_waitcnt vmcnt(8)
	s_waitcnt lgkmcnt(0)
	s_barrier
; #define PG8_STAGE(bufoff, gbase, voff) do { _Pragma("unroll") for (int _i = 0; _i < 2; ++_i) \
;         __builtin_amdgcn_global_load_lds((const unsigned*)((const char*)(gbase) + (voff)[_i]), (PG8_LAS unsigned*)(lds + (bufoff) + ldsw + _i * 8192), 16, 0, 0); } while (0)
; #define PG8_LDA(dst, b, h) do { _Pragma("unroll") for (int m = 0; m < 4; ++m) _Pragma("unroll") for (int k = 0; k < 2; ++k) dst[m][k] = *(const PG8_LAS bf16x8*)(lds + PG8_SA(b, h) + aoff + m * 2048 + k * 1024); } while (0)
; #define PG8_LDB(dst, b, h) do { _Pragma("unroll") for (int n = 0; n < 2; ++n) _Pragma("unroll") for (int k = 0; k < 2; ++k) dst[n][k] = *(const PG8_LAS bf16x8*)(lds + PG8_SB(b, h) + boff + n * 2048 + k * 1024); } while (0)
; #define PG8_MMA(ai, bj, At, Bt) do { __builtin_amdgcn_s_setprio(1); _Pragma("unroll") for (int m = 0; m < 4; ++m) _Pragma("unroll") for (int n = 0; n < 2; ++n) _Pragma("unroll") for (int k = 0; k < 2; ++k) \
;         acc[ai][bj][m][n] = __builtin_amdgcn_mfma_f32_16x16x32_bf16(Bt[n][k], At[m][k], acc[ai][bj][m][n], 0, 0, 0); __builtin_amdgcn_s_setprio(0); } while (0)
; #define PG8_WAIT_V(n) asm volatile("s_waitcnt vmcnt(" #n ")" ::: "memory")
; #define PG8_WAIT_L(n) asm volatile("s_waitcnt lgkmcnt(" #n ")" ::: "memory")
; #define PG8_BAR __builtin_amdgcn_s_barrier()
; #define PG8_SCHED __builtin_amdgcn_sched_barrier(0)
; template <class Epi, class Sched, bool ALIGN_EPI = false, bool SP2 = false>
; __device__ __forceinline__ void gemm_phase(PG8_LAS unsigned char* lds, const int Kdim  , const int Klen  , const Sched& S, const Epi& E, const int wave_s) {
;     ...
;             PG8_WAIT_V(8); PG8_WAIT_L(0); PG8_BAR; PG8_MMA(1, 0, At, B0); PG8_MMA(1, 1, At, B1); PG8_BAR; PG8_SCHED;
;             PG8_LDB(B0, 1, 0); PG8_LDB(B1, 1, 1); PG8_SCHED; PG8_LDA(At, 1, 0); PG8_STAGE(PG8_SA(0, 1), a2 + hstep, voffA);
;             PG8_WAIT_V(8); PG8_WAIT_L(0); PG8_BAR; PG8_MMA(0, 0, At, B0); PG8_MMA(0, 1, At, B1); PG8_BAR; PG8_SCHED;
	s_setprio 1
	s_waitcnt lgkmcnt(0)
	v_mfma_f32_16x16x32_bf16 v[60:63], v[120:123], v[172:175], 0
	v_mfma_f32_16x16x32_bf16 v[52:55], v[128:131], v[172:175], 0
	v_mfma_f32_16x16x32_bf16 v[20:23], v[120:123], v[182:185], 0
	v_mfma_f32_16x16x32_bf16 v[36:39], v[128:131], v[182:185], 0
	v_mfma_f32_16x16x32_bf16 v[16:19], v[120:123], v[190:193], 0
	v_mfma_f32_16x16x32_bf16 v[32:35], v[128:131], v[190:193], 0
	v_mfma_f32_16x16x32_bf16 v[56:59], v[120:123], v[198:201], 0
	v_mfma_f32_16x16x32_bf16 v[48:51], v[128:131], v[198:201], 0
	v_mfma_f32_16x16x32_bf16 v[60:63], v[124:127], v[178:181], v[60:63]
	v_mfma_f32_16x16x32_bf16 v[52:55], v[132:135], v[178:181], v[52:55]
	v_mfma_f32_16x16x32_bf16 v[20:23], v[124:127], v[186:189], v[20:23]
	v_mfma_f32_16x16x32_bf16 v[36:39], v[132:135], v[186:189], v[36:39]
	v_mfma_f32_16x16x32_bf16 v[16:19], v[124:127], v[194:197], v[16:19]
	v_mfma_f32_16x16x32_bf16 v[32:35], v[132:135], v[194:197], v[32:35]
	v_mfma_f32_16x16x32_bf16 v[56:59], v[124:127], v[202:205], v[56:59]
	v_mfma_f32_16x16x32_bf16 v[48:51], v[132:135], v[202:205], v[48:51]
	s_setprio 0
	s_setprio 1
	v_mfma_f32_16x16x32_bf16 v[40:43], v[144:147], v[172:175], 0
	v_mfma_f32_16x16x32_bf16 v[44:47], v[164:167], v[172:175], 0
	v_mfma_f32_16x16x32_bf16 v[12:15], v[144:147], v[182:185], 0
	v_mfma_f32_16x16x32_bf16 v[28:31], v[164:167], v[182:185], 0
	v_mfma_f32_16x16x32_bf16 v[8:11], v[144:147], v[190:193], 0
	v_mfma_f32_16x16x32_bf16 v[24:27], v[164:167], v[190:193], 0
	v_mfma_f32_16x16x32_bf16 v[0:3], v[144:147], v[198:201], 0
	v_mfma_f32_16x16x32_bf16 v[4:7], v[164:167], v[198:201], 0
	v_mfma_f32_16x16x32_bf16 v[40:43], v[148:151], v[178:181], v[40:43]
	v_mfma_f32_16x16x32_bf16 v[44:47], v[168:171], v[178:181], v[44:47]
	v_mfma_f32_16x16x32_bf16 v[12:15], v[148:151], v[186:189], v[12:15]
	v_mfma_f32_16x16x32_bf16 v[28:31], v[168:171], v[186:189], v[28:31]
	v_mfma_f32_16x16x32_bf16 v[8:11], v[148:151], v[194:197], v[8:11]
	v_mfma_f32_16x16x32_bf16 v[24:27], v[168:171], v[194:197], v[24:27]
	v_mfma_f32_16x16x32_bf16 v[0:3], v[148:151], v[202:205], v[0:3]
	v_mfma_f32_16x16x32_bf16 v[4:7], v[168:171], v[202:205], v[4:7]
	s_setprio 0
	s_barrier
	v_add_u32_e32 v132, s71, v246
	v_add_u32_e32 v168, s73, v246
	ds_read_b128 v[120:123], v132
	ds_read_b128 v[124:127], v132 offset:1024
	ds_read_b128 v[128:131], v132 offset:2048
	ds_read_b128 v[132:135], v132 offset:3072
	ds_read_b128 v[144:147], v168
	ds_read_b128 v[148:151], v168 offset:1024
	ds_read_b128 v[164:167], v168 offset:2048
	ds_read_b128 v[168:171], v168 offset:3072
	s_add_u32 s30, vcc_lo, 0x80000
	s_addc_u32 s31, vcc_hi, 0
	s_mov_b32 m0, s0
	v_lshl_add_u64 v[232:233], s[30:31], 0, v[152:153]
	ds_read_b128 v[172:175], v247 offset:32768
	ds_read_b128 v[178:181], v247 offset:33792
	ds_read_b128 v[182:185], v247 offset:34816
	ds_read_b128 v[186:189], v247 offset:35840
	ds_read_b128 v[190:193], v247 offset:36864
	ds_read_b128 v[194:197], v247 offset:37888
	ds_read_b128 v[198:201], v247 offset:38912
	ds_read_b128 v[202:205], v247 offset:39936
	global_load_lds_dwordx4 v[232:233], off
	v_lshl_add_u64 v[232:233], s[30:31], 0, v[156:157]
	s_mov_b32 m0, s28
	s_nop 0
	global_load_lds_dwordx4 v[232:233], off
	s_waitcnt vmcnt(8)
	s_waitcnt lgkmcnt(0)
	s_barrier
	s_setprio 1
	s_waitcnt lgkmcnt(0)
	v_mfma_f32_16x16x32_bf16 v[140:143], v[120:123], v[172:175], v[140:143]
	v_mfma_f32_16x16x32_bf16 v[116:119], v[128:131], v[172:175], v[116:119]
	v_mfma_f32_16x16x32_bf16 v[84:87], v[120:123], v[182:185], v[84:87]
	v_mfma_f32_16x16x32_bf16 v[100:103], v[128:131], v[182:185], v[100:103]
	v_mfma_f32_16x16x32_bf16 v[80:83], v[120:123], v[190:193], v[80:83]
	v_mfma_f32_16x16x32_bf16 v[96:99], v[128:131], v[190:193], v[96:99]
	v_mfma_f32_16x16x32_bf16 v[136:139], v[120:123], v[198:201], v[136:139]
	v_mfma_f32_16x16x32_bf16 v[112:115], v[128:131], v[198:201], v[112:115]
	v_mfma_f32_16x16x32_bf16 v[140:143], v[124:127], v[178:181], v[140:143]
	v_mfma_f32_16x16x32_bf16 v[116:119], v[132:135], v[178:181], v[116:119]
	v_mfma_f32_16x16x32_bf16 v[84:87], v[124:127], v[186:189], v[84:87]
	v_mfma_f32_16x16x32_bf16 v[100:103], v[132:135], v[186:189], v[100:103]
	v_mfma_f32_16x16x32_bf16 v[80:83], v[124:127], v[194:197], v[80:83]
	v_mfma_f32_16x16x32_bf16 v[96:99], v[132:135], v[194:197], v[96:99]
	v_mfma_f32_16x16x32_bf16 v[136:139], v[124:127], v[202:205], v[136:139]
	v_mfma_f32_16x16x32_bf16 v[112:115], v[132:135], v[202:205], v[112:115]
	s_setprio 0
	s_setprio 1
	v_mfma_f32_16x16x32_bf16 v[104:107], v[144:147], v[172:175], v[104:107]
	v_mfma_f32_16x16x32_bf16 v[108:111], v[164:167], v[172:175], v[108:111]
	v_mfma_f32_16x16x32_bf16 v[76:79], v[144:147], v[182:185], v[76:79]
	v_mfma_f32_16x16x32_bf16 v[92:95], v[164:167], v[182:185], v[92:95]
	v_mfma_f32_16x16x32_bf16 v[72:75], v[144:147], v[190:193], v[72:75]
	v_mfma_f32_16x16x32_bf16 v[88:91], v[164:167], v[190:193], v[88:91]
	v_mfma_f32_16x16x32_bf16 v[64:67], v[144:147], v[198:201], v[64:67]
	v_mfma_f32_16x16x32_bf16 v[68:71], v[164:167], v[198:201], v[68:71]
	v_mfma_f32_16x16x32_bf16 v[104:107], v[148:151], v[178:181], v[104:107]
	v_mfma_f32_16x16x32_bf16 v[108:111], v[168:171], v[178:181], v[108:111]
	v_mfma_f32_16x16x32_bf16 v[76:79], v[148:151], v[186:189], v[76:79]
	v_mfma_f32_16x16x32_bf16 v[92:95], v[168:171], v[186:189], v[92:95]
	v_mfma_f32_16x16x32_bf16 v[72:75], v[148:151], v[194:197], v[72:75]
	v_mfma_f32_16x16x32_bf16 v[88:91], v[168:171], v[194:197], v[88:91]
	v_mfma_f32_16x16x32_bf16 v[64:67], v[148:151], v[202:205], v[64:67]
	v_mfma_f32_16x16x32_bf16 v[68:71], v[168:171], v[202:205], v[68:71]
	s_setprio 0
	s_barrier
; #define PG8_STAGE(bufoff, gbase, voff) do { _Pragma("unroll") for (int _i = 0; _i < 2; ++_i) \
;         __builtin_amdgcn_global_load_lds((const unsigned*)((const char*)(gbase) + (voff)[_i]), (PG8_LAS unsigned*)(lds + (bufoff) + ldsw + _i * 8192), 16, 0, 0); } while (0)
; #define PG8_LDA(dst, b, h) do { _Pragma("unroll") for (int m = 0; m < 4; ++m) _Pragma("unroll") for (int k = 0; k < 2; ++k) dst[m][k] = *(const PG8_LAS bf16x8*)(lds + PG8_SA(b, h) + aoff + m * 2048 + k * 1024); } while (0)
; #define PG8_LDB(dst, b, h) do { _Pragma("unroll") for (int n = 0; n < 2; ++n) _Pragma("unroll") for (int k = 0; k < 2; ++k) dst[n][k] = *(const PG8_LAS bf16x8*)(lds + PG8_SB(b, h) + boff + n * 2048 + k * 1024); } while (0)
; #define PG8_MMA(ai, bj, At, Bt) do { __builtin_amdgcn_s_setprio(1); _Pragma("unroll") for (int m = 0; m < 4; ++m) _Pragma("unroll") for (int n = 0; n < 2; ++n) _Pragma("unroll") for (int k = 0; k < 2; ++k) \
;         acc[ai][bj][m][n] = __builtin_amdgcn_mfma_f32_16x16x32_bf16(Bt[n][k], At[m][k], acc[ai][bj][m][n], 0, 0, 0); __builtin_amdgcn_s_setprio(0); } while (0)
; #define PG8_WAIT_V(n) asm volatile("s_waitcnt vmcnt(" #n ")" ::: "memory")
; #define PG8_WAIT_L(n) asm volatile("s_waitcnt lgkmcnt(" #n ")" ::: "memory")
; #define PG8_BAR __builtin_amdgcn_s_barrier()
; #define PG8_SCHED __builtin_amdgcn_sched_barrier(0)
; template <class Epi, class Sched, bool ALIGN_EPI = false, bool SP2 = false>
; __device__ __forceinline__ void gemm_phase(PG8_LAS unsigned char* lds, const int Kdim  , const int Klen  , const Sched& S, const Epi& E, const int wave_s) {
;     ...
;             PG8_LDB(B0, 1, 0); PG8_LDB(B1, 1, 1); PG8_SCHED; PG8_LDA(At, 1, 0); PG8_STAGE(PG8_SA(0, 1), a2 + hstep, voffA);
;             PG8_WAIT_V(8); PG8_WAIT_L(0); PG8_BAR; PG8_MMA(0, 0, At, B0); PG8_MMA(0, 1, At, B1); PG8_BAR; PG8_SCHED;
;             PG8_LDA(At, 1, 1); PG8_STAGE(PG8_SB(1, 0), b3, voffB); PG8_STAGE(PG8_SB(1, 1), b3 + hstep, voffB); PG8_STAGE(PG8_SA(1, 0), a3, voffA);
;             PG8_WAIT_V(8); PG8_WAIT_L(0); PG8_BAR; PG8_MMA(1, 0, At, B0); PG8_MMA(1, 1, At, B1); PG8_BAR; PG8_SCHED;
	s_add_i32 s30, s71, s83
	v_lshl_add_u64 v[206:207], v[206:207], 0, s[96:97]
	s_mov_b32 m0, s30
	ds_read_b128 v[172:175], v247 offset:49152
	ds_read_b128 v[178:181], v247 offset:50176
	ds_read_b128 v[182:185], v247 offset:51200
	ds_read_b128 v[186:189], v247 offset:52224
	ds_read_b128 v[190:193], v247 offset:53248
	ds_read_b128 v[194:197], v247 offset:54272
	ds_read_b128 v[198:201], v247 offset:55296
	ds_read_b128 v[202:205], v247 offset:56320
	global_load_lds_dwordx4 v[206:207], off
	s_add_i32 m0, s30, 0x2000
	s_add_u32 s30, s62, 0x80080
	v_lshl_add_u64 v[206:207], v[208:209], 0, s[96:97]
	s_addc_u32 s31, s63, 0
	s_add_i32 s62, s73, s83
	global_load_lds_dwordx4 v[206:207], off
	v_lshl_add_u64 v[206:207], s[30:31], 0, v[154:155]
	s_mov_b32 m0, s62
	s_nop 0
	global_load_lds_dwordx4 v[206:207], off
	v_lshl_add_u64 v[206:207], s[30:31], 0, v[158:159]
	s_add_i32 m0, s62, 0x2000
	s_nop 0
	global_load_lds_dwordx4 v[206:207], off
	v_lshl_add_u64 v[206:207], v[210:211], 0, s[96:97]
	s_mov_b32 m0, s29
	s_nop 0
	global_load_lds_dwordx4 v[206:207], off
	v_lshl_add_u64 v[206:207], v[218:219], 0, s[96:97]
	s_mov_b32 m0, s74
	s_nop 0
	global_load_lds_dwordx4 v[206:207], off
	s_waitcnt vmcnt(8)
	s_waitcnt lgkmcnt(0)
	s_barrier
	s_setprio 1
	s_waitcnt lgkmcnt(0)
	v_mfma_f32_16x16x32_bf16 v[60:63], v[120:123], v[172:175], v[60:63]
	v_mfma_f32_16x16x32_bf16 v[52:55], v[128:131], v[172:175], v[52:55]
	v_mfma_f32_16x16x32_bf16 v[20:23], v[120:123], v[182:185], v[20:23]
	v_mfma_f32_16x16x32_bf16 v[36:39], v[128:131], v[182:185], v[36:39]
	v_mfma_f32_16x16x32_bf16 v[16:19], v[120:123], v[190:193], v[16:19]
	v_mfma_f32_16x16x32_bf16 v[32:35], v[128:131], v[190:193], v[32:35]
	v_mfma_f32_16x16x32_bf16 v[56:59], v[120:123], v[198:201], v[56:59]
	v_mfma_f32_16x16x32_bf16 v[48:51], v[128:131], v[198:201], v[48:51]
	v_mfma_f32_16x16x32_bf16 v[60:63], v[124:127], v[178:181], v[60:63]
	v_mfma_f32_16x16x32_bf16 v[52:55], v[132:135], v[178:181], v[52:55]
	v_mfma_f32_16x16x32_bf16 v[20:23], v[124:127], v[186:189], v[20:23]
	v_mfma_f32_16x16x32_bf16 v[36:39], v[132:135], v[186:189], v[36:39]
	v_mfma_f32_16x16x32_bf16 v[16:19], v[124:127], v[194:197], v[16:19]
	v_mfma_f32_16x16x32_bf16 v[32:35], v[132:135], v[194:197], v[32:35]
	v_mfma_f32_16x16x32_bf16 v[56:59], v[124:127], v[202:205], v[56:59]
	v_mfma_f32_16x16x32_bf16 v[48:51], v[132:135], v[202:205], v[48:51]
	s_setprio 0
	s_setprio 1
	v_mfma_f32_16x16x32_bf16 v[40:43], v[144:147], v[172:175], v[40:43]
	v_mfma_f32_16x16x32_bf16 v[44:47], v[164:167], v[172:175], v[44:47]
	v_mfma_f32_16x16x32_bf16 v[12:15], v[144:147], v[182:185], v[12:15]
	v_mfma_f32_16x16x32_bf16 v[28:31], v[164:167], v[182:185], v[28:31]
	v_mfma_f32_16x16x32_bf16 v[8:11], v[144:147], v[190:193], v[8:11]
	v_mfma_f32_16x16x32_bf16 v[24:27], v[164:167], v[190:193], v[24:27]
	v_mfma_f32_16x16x32_bf16 v[0:3], v[144:147], v[198:201], v[0:3]
	v_mfma_f32_16x16x32_bf16 v[4:7], v[164:167], v[198:201], v[4:7]
	v_mfma_f32_16x16x32_bf16 v[40:43], v[148:151], v[178:181], v[40:43]
	v_mfma_f32_16x16x32_bf16 v[44:47], v[168:171], v[178:181], v[44:47]
	v_mfma_f32_16x16x32_bf16 v[12:15], v[148:151], v[186:189], v[12:15]
	v_mfma_f32_16x16x32_bf16 v[28:31], v[168:171], v[186:189], v[28:31]
	v_mfma_f32_16x16x32_bf16 v[8:11], v[148:151], v[194:197], v[8:11]
	v_mfma_f32_16x16x32_bf16 v[24:27], v[168:171], v[194:197], v[24:27]
	v_mfma_f32_16x16x32_bf16 v[0:3], v[148:151], v[202:205], v[0:3]
	v_mfma_f32_16x16x32_bf16 v[4:7], v[168:171], v[202:205], v[4:7]
	s_setprio 0
	s_barrier
	s_add_i32 s92, s92, 2
	s_add_u32 s12, s12, 0x100
	s_addc_u32 s13, s13, 0
	s_add_u32 s58, s58, 0x100
	s_addc_u32 s59, s59, 0
	s_cmp_gt_u32 s92, 29
	s_cbranch_scc1 .Lkdone_3

; #define PG8_BAR __builtin_amdgcn_s_barrier()
; template <class Epi, class Sched, bool ALIGN_EPI = false, bool SP2 = false>
; __device__ __forceinline__ void gemm_phase(PG8_LAS unsigned char* lds, const int Kdim  , const int Klen  , const Sched& S, const Epi& E, const int wave_s) {
;     ...
;         }
;         if constexpr (ALIGN_EPI) { if (wr == 0) PG8_BAR; }
.Lkdone_3:
	s_and_b64 vcc, exec, s[34:35]
	s_cbranch_vccz .LBB0_1454
	s_barrier

; template <int CTRL> __device__ __forceinline__ float dpp_ror(float v) { return __builtin_bit_cast(float, __builtin_amdgcn_update_dpp(0, __builtin_bit_cast(int, v), CTRL, 0xf, 0xf, false)); }
;     __device__ __forceinline__ void operator()(pg8::f32x4 (&acc)[2][2][4][2], const pg8::Unit& u, int wr_, int wc_, int fr_, int fq_) const {
;     ...
;                     for (int m = 0; m < 4; ++m) { gg[m] = acc[ai][0][m][n][j]; pr[m] = dpp_ror<0x121>(gg[m]); nx[m] = dpp_ror<0x12F>(gg[m]); }
; #pragma unroll
;                     for (int m = 0; m < 4; ++m) {
;                         const float pv = fr > 0 ? pr[m] : (m > 0 ? pr[m > 0 ? m - 1 : 0] : 0.f);
;                         const float nv = fr < 15 ? nx[m] : (m < 3 ? nx[m < 3 ? m + 1 : 3] : 0.f);
;                         const float cv = w0[j] * pv + w1[j] * gg[m] + w2[j] * nv + bb[j];
;                         if (m == 0) { if (e0) EP[eb0 + hc + (unsigned)j] = cv; } if (m == 3) { if (e3) EP[eb3 + hc + (unsigned)j] = cv; }
.LBB0_1458:
	s_or_b64 exec, exec, s[62:63]
	v_mov_b32_dpp v146, v140 row_ror:1 row_mask:0xf bank_mask:0xf
	v_cndmask_b32_e64 v147, v146, 0, s[12:13]
	v_mov_b32_dpp v145, v140 row_ror:15 row_mask:0xf bank_mask:0xf
	v_mov_b32_dpp v252, v84 row_ror:15 row_mask:0xf bank_mask:0xf
	s_waitcnt vmcnt(0)
	v_mul_f32_e32 v147, v124, v147
	v_cndmask_b32_e64 v145, v145, v252, s[8:9]
	v_fmac_f32_e32 v147, v140, v120
	v_fmac_f32_e32 v147, v128, v145
	v_mov_b32_dpp v185, v84 row_ror:1 row_mask:0xf bank_mask:0xf
	v_mov_b32_dpp v183, v80 row_ror:1 row_mask:0xf bank_mask:0xf
	v_mov_b32_dpp v250, v80 row_ror:15 row_mask:0xf bank_mask:0xf
	v_mov_b32_dpp v182, v136 row_ror:1 row_mask:0xf bank_mask:0xf
	v_mov_b32_dpp v251, v136 row_ror:15 row_mask:0xf bank_mask:0xf
	v_add_f32_e32 v235, v132, v147
	s_and_saveexec_b64 s[62:63], s[12:13]
	s_mov_b32 s93, s52
	s_cbranch_execz .LBB0_1460
	v_mov_b32_e32 v184, v183
	v_mov_b32_e32 v145, v177
	v_lshl_add_u64 v[148:149], v[144:145], 2, s[20:21]
	v_mov_b64_e32 v[182:183], v[184:185]
	v_mov_b32_e32 v185, v146
	global_store_dword v[148:149], v235, off

; template <int CTRL> __device__ __forceinline__ float dpp_ror(float v) { return __builtin_bit_cast(float, __builtin_amdgcn_update_dpp(0, __builtin_bit_cast(int, v), CTRL, 0xf, 0xf, false)); }
;     __device__ __forceinline__ void operator()(pg8::f32x4 (&acc)[2][2][4][2], const pg8::Unit& u, int wr_, int wc_, int fr_, int fq_) const {
;     ...
;                     for (int m = 0; m < 4; ++m) { gg[m] = acc[ai][0][m][n][j]; pr[m] = dpp_ror<0x121>(gg[m]); nx[m] = dpp_ror<0x12F>(gg[m]); }
; #pragma unroll
;                     for (int m = 0; m < 4; ++m) {
;                         const float pv = fr > 0 ? pr[m] : (m > 0 ? pr[m > 0 ? m - 1 : 0] : 0.f);
;                         const float nv = fr < 15 ? nx[m] : (m < 3 ? nx[m < 3 ? m + 1 : 3] : 0.f);
;                         const float cv = w0[j] * pv + w1[j] * gg[m] + w2[j] * nv + bb[j];
;                         if (m == 0) { if (e0) EP[eb0 + hc + (unsigned)j] = cv; } if (m == 3) { if (e3) EP[eb3 + hc + (unsigned)j] = cv; }
.LBB0_1462:
	s_or_b64 exec, exec, s[62:63]
	v_mov_b32_dpp v136, v141 row_ror:1 row_mask:0xf bank_mask:0xf
	v_cndmask_b32_e64 v145, v136, 0, s[12:13]
	v_mov_b32_dpp v140, v141 row_ror:15 row_mask:0xf bank_mask:0xf
	v_mov_b32_dpp v218, v85 row_ror:15 row_mask:0xf bank_mask:0xf
	v_mul_f32_e32 v145, v125, v145
	v_cndmask_b32_e64 v140, v140, v218, s[8:9]
	v_fmac_f32_e32 v145, v141, v121
	v_fmac_f32_e32 v145, v129, v140
	v_mov_b32_dpp v189, v85 row_ror:1 row_mask:0xf bank_mask:0xf
	v_mov_b32_dpp v187, v81 row_ror:1 row_mask:0xf bank_mask:0xf
	v_mov_b32_dpp v253, v81 row_ror:15 row_mask:0xf bank_mask:0xf
	v_mov_b32_dpp v186, v137 row_ror:1 row_mask:0xf bank_mask:0xf
	v_mov_b32_dpp v245, v137 row_ror:15 row_mask:0xf bank_mask:0xf
	v_add_f32_e32 v237, v133, v145
	s_and_saveexec_b64 s[62:63], s[12:13]
	s_cbranch_execz .LBB0_1464
	v_mov_b32_e32 v188, v187
	v_or_b32_e32 v140, 1, v144
	v_mov_b32_e32 v141, v177
	v_lshl_add_u64 v[140:141], v[140:141], 2, s[20:21]
	v_mov_b64_e32 v[186:187], v[188:189]
	v_mov_b32_e32 v189, v136
	global_store_dword v[140:141], v237, off

; template <int CTRL> __device__ __forceinline__ float dpp_ror(float v) { return __builtin_bit_cast(float, __builtin_amdgcn_update_dpp(0, __builtin_bit_cast(int, v), CTRL, 0xf, 0xf, false)); }
;     __device__ __forceinline__ void operator()(pg8::f32x4 (&acc)[2][2][4][2], const pg8::Unit& u, int wr_, int wc_, int fr_, int fq_) const {
;     ...
;                     for (int m = 0; m < 4; ++m) { gg[m] = acc[ai][0][m][n][j]; pr[m] = dpp_ror<0x121>(gg[m]); nx[m] = dpp_ror<0x12F>(gg[m]); }
; #pragma unroll
;                     for (int m = 0; m < 4; ++m) {
;                         const float pv = fr > 0 ? pr[m] : (m > 0 ? pr[m > 0 ? m - 1 : 0] : 0.f);
;                         const float nv = fr < 15 ? nx[m] : (m < 3 ? nx[m < 3 ? m + 1 : 3] : 0.f);
;                         const float cv = w0[j] * pv + w1[j] * gg[m] + w2[j] * nv + bb[j];
;                         if (m == 0) { if (e0) EP[eb0 + hc + (unsigned)j] = cv; } if (m == 3) { if (e3) EP[eb3 + hc + (unsigned)j] = cv; }
.LBB0_1466:
	s_or_b64 exec, exec, s[62:63]
	v_mov_b32_dpp v136, v142 row_ror:1 row_mask:0xf bank_mask:0xf
	v_cndmask_b32_e64 v140, v136, 0, s[12:13]
	v_mov_b32_dpp v137, v142 row_ror:15 row_mask:0xf bank_mask:0xf
	v_mov_b32_dpp v232, v86 row_ror:15 row_mask:0xf bank_mask:0xf
	v_mul_f32_e32 v140, v126, v140
	v_cndmask_b32_e64 v137, v137, v232, s[8:9]
	v_fmac_f32_e32 v140, v142, v122
	v_fmac_f32_e32 v140, v130, v137
	v_mov_b32_dpp v193, v86 row_ror:1 row_mask:0xf bank_mask:0xf
	v_mov_b32_dpp v191, v82 row_ror:1 row_mask:0xf bank_mask:0xf
	v_mov_b32_dpp v219, v82 row_ror:15 row_mask:0xf bank_mask:0xf
	v_mov_b32_dpp v190, v138 row_ror:1 row_mask:0xf bank_mask:0xf
	v_mov_b32_dpp v231, v138 row_ror:15 row_mask:0xf bank_mask:0xf
	v_add_f32_e32 v239, v134, v140
	s_and_saveexec_b64 s[62:63], s[12:13]
	s_cbranch_execz .LBB0_1468
	v_mov_b32_e32 v192, v191
	v_or_b32_e32 v140, 2, v144
	v_mov_b32_e32 v141, v177
	v_lshl_add_u64 v[140:141], v[140:141], 2, s[20:21]
	v_mov_b64_e32 v[190:191], v[192:193]
	v_mov_b32_e32 v193, v136
	global_store_dword v[140:141], v239, off

; template <int CTRL> __device__ __forceinline__ float dpp_ror(float v) { return __builtin_bit_cast(float, __builtin_amdgcn_update_dpp(0, __builtin_bit_cast(int, v), CTRL, 0xf, 0xf, false)); }
;     __device__ __forceinline__ void operator()(pg8::f32x4 (&acc)[2][2][4][2], const pg8::Unit& u, int wr_, int wc_, int fr_, int fq_) const {
;     ...
;                     for (int m = 0; m < 4; ++m) { gg[m] = acc[ai][0][m][n][j]; pr[m] = dpp_ror<0x121>(gg[m]); nx[m] = dpp_ror<0x12F>(gg[m]); }
; #pragma unroll
;                     for (int m = 0; m < 4; ++m) {
;                         const float pv = fr > 0 ? pr[m] : (m > 0 ? pr[m > 0 ? m - 1 : 0] : 0.f);
;                         const float nv = fr < 15 ? nx[m] : (m < 3 ? nx[m < 3 ? m + 1 : 3] : 0.f);
;                         const float cv = w0[j] * pv + w1[j] * gg[m] + w2[j] * nv + bb[j];
;                         if (m == 0) { if (e0) EP[eb0 + hc + (unsigned)j] = cv; } if (m == 3) { if (e3) EP[eb3 + hc + (unsigned)j] = cv; }
.LBB0_1470:
	s_or_b64 exec, exec, s[62:63]
	v_mov_b32_dpp v136, v143 row_ror:1 row_mask:0xf bank_mask:0xf
	v_cndmask_b32_e64 v138, v136, 0, s[12:13]
	v_mov_b32_dpp v137, v143 row_ror:15 row_mask:0xf bank_mask:0xf
	v_mov_b32_dpp v236, v87 row_ror:15 row_mask:0xf bank_mask:0xf
	v_mul_f32_e32 v138, v127, v138
	v_cndmask_b32_e64 v137, v137, v236, s[8:9]
	v_fmac_f32_e32 v138, v143, v123
	v_fmac_f32_e32 v138, v131, v137
	v_mov_b32_dpp v197, v87 row_ror:1 row_mask:0xf bank_mask:0xf
	v_mov_b32_dpp v195, v83 row_ror:1 row_mask:0xf bank_mask:0xf
	v_mov_b32_dpp v233, v83 row_ror:15 row_mask:0xf bank_mask:0xf
	v_mov_b32_dpp v194, v139 row_ror:1 row_mask:0xf bank_mask:0xf
	v_mov_b32_dpp v234, v139 row_ror:15 row_mask:0xf bank_mask:0xf
	v_add_f32_e32 v240, v135, v138
	s_and_saveexec_b64 s[62:63], s[12:13]
	s_cbranch_execz .LBB0_1472
	v_mov_b32_e32 v196, v195
	v_or_b32_e32 v140, 3, v144
	v_mov_b32_e32 v141, v177
	v_lshl_add_u64 v[140:141], v[140:141], 2, s[20:21]
	v_mov_b64_e32 v[194:195], v[196:197]
	v_mov_b32_e32 v197, v136
	global_store_dword v[140:141], v240, off

; template <int CTRL> __device__ __forceinline__ float dpp_ror(float v) { return __builtin_bit_cast(float, __builtin_amdgcn_update_dpp(0, __builtin_bit_cast(int, v), CTRL, 0xf, 0xf, false)); }
;     __device__ __forceinline__ void operator()(pg8::f32x4 (&acc)[2][2][4][2], const pg8::Unit& u, int wr_, int wc_, int fr_, int fq_) const {
;     ...
;                     for (int m = 0; m < 4; ++m) { gg[m] = acc[ai][0][m][n][j]; pr[m] = dpp_ror<0x121>(gg[m]); nx[m] = dpp_ror<0x12F>(gg[m]); }
; #pragma unroll
;                     for (int m = 0; m < 4; ++m) {
;                         const float pv = fr > 0 ? pr[m] : (m > 0 ? pr[m > 0 ? m - 1 : 0] : 0.f);
;                         const float nv = fr < 15 ? nx[m] : (m < 3 ? nx[m < 3 ? m + 1 : 3] : 0.f);
;                         const float cv = w0[j] * pv + w1[j] * gg[m] + w2[j] * nv + bb[j];
;                         if (m == 0) { if (e0) EP[eb0 + hc + (unsigned)j] = cv; } if (m == 3) { if (e3) EP[eb3 + hc + (unsigned)j] = cv; }
.LBB0_1478:
	s_or_b64 exec, exec, s[62:63]
	v_mov_b32_dpp v178, v116 row_ror:1 row_mask:0xf bank_mask:0xf
	v_cndmask_b32_e64 v190, v178, 0, s[12:13]
	v_mov_b32_dpp v179, v116 row_ror:15 row_mask:0xf bank_mask:0xf
	v_mov_b32_dpp v238, v100 row_ror:15 row_mask:0xf bank_mask:0xf
	s_waitcnt vmcnt(3)
	v_mul_f32_e32 v190, v136, v190
	v_cndmask_b32_e64 v179, v179, v238, s[8:9]
	s_waitcnt vmcnt(2)
	v_fmac_f32_e32 v190, v116, v148
	s_waitcnt vmcnt(1)
	v_fmac_f32_e32 v190, v140, v179
	v_mov_b32_dpp v201, v100 row_ror:1 row_mask:0xf bank_mask:0xf
	v_mov_b32_dpp v199, v96 row_ror:1 row_mask:0xf bank_mask:0xf
	v_mov_b32_dpp v194, v96 row_ror:15 row_mask:0xf bank_mask:0xf
	v_mov_b32_dpp v198, v112 row_ror:1 row_mask:0xf bank_mask:0xf
	v_mov_b32_dpp v196, v112 row_ror:15 row_mask:0xf bank_mask:0xf
	s_waitcnt vmcnt(0)
	v_add_f32_e32 v242, v144, v190
	s_and_saveexec_b64 s[62:63], s[12:13]
	s_cbranch_execz .LBB0_1480
	v_mov_b32_e32 v211, v177
	v_mov_b32_e32 v200, v199
	v_lshl_add_u64 v[198:199], v[210:211], 2, s[20:21]
	global_store_dword v[198:199], v242, off
	v_mov_b64_e32 v[198:199], v[200:201]
	v_mov_b32_e32 v201, v178

; template <int CTRL> __device__ __forceinline__ float dpp_ror(float v) { return __builtin_bit_cast(float, __builtin_amdgcn_update_dpp(0, __builtin_bit_cast(int, v), CTRL, 0xf, 0xf, false)); }
;     __device__ __forceinline__ void operator()(pg8::f32x4 (&acc)[2][2][4][2], const pg8::Unit& u, int wr_, int wc_, int fr_, int fq_) const {
;     ...
;                     for (int m = 0; m < 4; ++m) { gg[m] = acc[ai][0][m][n][j]; pr[m] = dpp_ror<0x121>(gg[m]); nx[m] = dpp_ror<0x12F>(gg[m]); }
; #pragma unroll
;                     for (int m = 0; m < 4; ++m) {
;                         const float pv = fr > 0 ? pr[m] : (m > 0 ? pr[m > 0 ? m - 1 : 0] : 0.f);
;                         const float nv = fr < 15 ? nx[m] : (m < 3 ? nx[m < 3 ? m + 1 : 3] : 0.f);
;                         const float cv = w0[j] * pv + w1[j] * gg[m] + w2[j] * nv + bb[j];
;                         if (m == 0) { if (e0) EP[eb0 + hc + (unsigned)j] = cv; } if (m == 3) { if (e3) EP[eb3 + hc + (unsigned)j] = cv; }
.LBB0_1482:
	s_or_b64 exec, exec, s[62:63]
	v_mov_b32_dpp v112, v117 row_ror:1 row_mask:0xf bank_mask:0xf
	v_cndmask_b32_e64 v178, v112, 0, s[12:13]
	v_mov_b32_dpp v116, v117 row_ror:15 row_mask:0xf bank_mask:0xf
	v_mov_b32_dpp v211, v101 row_ror:15 row_mask:0xf bank_mask:0xf
	v_mul_f32_e32 v178, v137, v178
	v_cndmask_b32_e64 v116, v116, v211, s[8:9]
	v_fmac_f32_e32 v178, v117, v149
	v_fmac_f32_e32 v178, v141, v116
	v_mov_b32_dpp v205, v101 row_ror:1 row_mask:0xf bank_mask:0xf
	v_mov_b32_dpp v203, v97 row_ror:1 row_mask:0xf bank_mask:0xf
	v_mov_b32_dpp v198, v97 row_ror:15 row_mask:0xf bank_mask:0xf
	v_mov_b32_dpp v202, v113 row_ror:1 row_mask:0xf bank_mask:0xf
	v_mov_b32_dpp v200, v113 row_ror:15 row_mask:0xf bank_mask:0xf
	v_add_f32_e32 v244, v145, v178
	s_and_saveexec_b64 s[62:63], s[12:13]
	s_cbranch_execz .LBB0_1484
	v_mov_b32_e32 v204, v203
	v_or_b32_e32 v116, 1, v210
	v_mov_b32_e32 v117, v177
	v_lshl_add_u64 v[116:117], v[116:117], 2, s[20:21]
	v_mov_b64_e32 v[202:203], v[204:205]
	v_mov_b32_e32 v205, v112
	global_store_dword v[116:117], v244, off

; template <int CTRL> __device__ __forceinline__ float dpp_ror(float v) { return __builtin_bit_cast(float, __builtin_amdgcn_update_dpp(0, __builtin_bit_cast(int, v), CTRL, 0xf, 0xf, false)); }
;     __device__ __forceinline__ void operator()(pg8::f32x4 (&acc)[2][2][4][2], const pg8::Unit& u, int wr_, int wc_, int fr_, int fq_) const {
;     ...
;                     for (int m = 0; m < 4; ++m) { gg[m] = acc[ai][0][m][n][j]; pr[m] = dpp_ror<0x121>(gg[m]); nx[m] = dpp_ror<0x12F>(gg[m]); }
; #pragma unroll
;                     for (int m = 0; m < 4; ++m) {
;                         const float pv = fr > 0 ? pr[m] : (m > 0 ? pr[m > 0 ? m - 1 : 0] : 0.f);
;                         const float nv = fr < 15 ? nx[m] : (m < 3 ? nx[m < 3 ? m + 1 : 3] : 0.f);
;                         const float cv = w0[j] * pv + w1[j] * gg[m] + w2[j] * nv + bb[j];
;                         if (m == 0) { if (e0) EP[eb0 + hc + (unsigned)j] = cv; } if (m == 3) { if (e3) EP[eb3 + hc + (unsigned)j] = cv; }
.LBB0_1486:
	s_or_b64 exec, exec, s[62:63]
	v_mov_b32_dpp v179, v118 row_ror:1 row_mask:0xf bank_mask:0xf
	v_cndmask_b32_e64 v178, v179, 0, s[12:13]
	v_mov_b32_dpp v116, v118 row_ror:15 row_mask:0xf bank_mask:0xf
	v_mov_b32_dpp v241, v102 row_ror:15 row_mask:0xf bank_mask:0xf
	v_mul_f32_e32 v178, v138, v178
	v_cndmask_b32_e64 v116, v116, v241, s[8:9]
	v_fmac_f32_e32 v178, v118, v150
	v_fmac_f32_e32 v178, v142, v116
	v_mov_b32_dpp v117, v102 row_ror:1 row_mask:0xf bank_mask:0xf
	v_mov_b32_dpp v113, v98 row_ror:1 row_mask:0xf bank_mask:0xf
	v_mov_b32_dpp v202, v98 row_ror:15 row_mask:0xf bank_mask:0xf
	v_mov_b32_dpp v112, v114 row_ror:1 row_mask:0xf bank_mask:0xf
	v_mov_b32_dpp v204, v114 row_ror:15 row_mask:0xf bank_mask:0xf
	v_add_f32_e32 v178, v146, v178
	s_and_saveexec_b64 s[62:63], s[12:13]
	s_cbranch_execz .LBB0_1488
	v_mov_b32_e32 v116, v113
	v_or_b32_e32 v112, 2, v210
	v_mov_b32_e32 v113, v177
	v_lshl_add_u64 v[112:113], v[112:113], 2, s[20:21]
	global_store_dword v[112:113], v178, off
	v_mov_b64_e32 v[112:113], v[116:117]
	v_mov_b32_e32 v117, v179

; template <int CTRL> __device__ __forceinline__ float dpp_ror(float v) { return __builtin_bit_cast(float, __builtin_amdgcn_update_dpp(0, __builtin_bit_cast(int, v), CTRL, 0xf, 0xf, false)); }
;     __device__ __forceinline__ void operator()(pg8::f32x4 (&acc)[2][2][4][2], const pg8::Unit& u, int wr_, int wc_, int fr_, int fq_) const {
;     ...
;                     for (int m = 0; m < 4; ++m) { gg[m] = acc[ai][0][m][n][j]; pr[m] = dpp_ror<0x121>(gg[m]); nx[m] = dpp_ror<0x12F>(gg[m]); }
; #pragma unroll
;                     for (int m = 0; m < 4; ++m) {
;                         const float pv = fr > 0 ? pr[m] : (m > 0 ? pr[m > 0 ? m - 1 : 0] : 0.f);
;                         const float nv = fr < 15 ? nx[m] : (m < 3 ? nx[m < 3 ? m + 1 : 3] : 0.f);
;                         const float cv = w0[j] * pv + w1[j] * gg[m] + w2[j] * nv + bb[j];
;                         if (m == 0) { if (e0) EP[eb0 + hc + (unsigned)j] = cv; } if (m == 3) { if (e3) EP[eb3 + hc + (unsigned)j] = cv; }
.LBB0_1490:
	s_or_b64 exec, exec, s[62:63]
	v_mov_b32_dpp v114, v119 row_ror:1 row_mask:0xf bank_mask:0xf
	v_cndmask_b32_e64 v208, v114, 0, s[12:13]
	v_mov_b32_dpp v179, v119 row_ror:15 row_mask:0xf bank_mask:0xf
	v_mov_b32_dpp v243, v103 row_ror:15 row_mask:0xf bank_mask:0xf
	v_mul_f32_e32 v208, v139, v208
	v_cndmask_b32_e64 v179, v179, v243, s[8:9]
	v_fmac_f32_e32 v208, v119, v151
	v_fmac_f32_e32 v208, v143, v179
	v_mov_b32_dpp v209, v103 row_ror:1 row_mask:0xf bank_mask:0xf
	v_mov_b32_dpp v207, v99 row_ror:1 row_mask:0xf bank_mask:0xf
	v_mov_b32_dpp v116, v99 row_ror:15 row_mask:0xf bank_mask:0xf
	v_mov_b32_dpp v206, v115 row_ror:1 row_mask:0xf bank_mask:0xf
	v_mov_b32_dpp v118, v115 row_ror:15 row_mask:0xf bank_mask:0xf
	v_add_f32_e32 v179, v147, v208
	s_and_saveexec_b64 s[62:63], s[12:13]
	s_cbranch_execz .LBB0_1492
	v_mov_b32_e32 v208, v207
	v_or_b32_e32 v206, 3, v210
	v_mov_b32_e32 v207, v177
	v_lshl_add_u64 v[206:207], v[206:207], 2, s[20:21]
	global_store_dword v[206:207], v179, off
	v_mov_b64_e32 v[206:207], v[208:209]
	v_mov_b32_e32 v209, v114

; template <int CTRL> __device__ __forceinline__ float dpp_ror(float v) { return __builtin_bit_cast(float, __builtin_amdgcn_update_dpp(0, __builtin_bit_cast(int, v), CTRL, 0xf, 0xf, false)); }
;     __device__ __forceinline__ void operator()(pg8::f32x4 (&acc)[2][2][4][2], const pg8::Unit& u, int wr_, int wc_, int fr_, int fq_) const {
;     ...
;                     for (int m = 0; m < 4; ++m) { gg[m] = acc[ai][0][m][n][j]; pr[m] = dpp_ror<0x121>(gg[m]); nx[m] = dpp_ror<0x12F>(gg[m]); }
; #pragma unroll
;                     for (int m = 0; m < 4; ++m) {
;                         const float pv = fr > 0 ? pr[m] : (m > 0 ? pr[m > 0 ? m - 1 : 0] : 0.f);
;                         const float nv = fr < 15 ? nx[m] : (m < 3 ? nx[m < 3 ? m + 1 : 3] : 0.f);
;                         const float cv = w0[j] * pv + w1[j] * gg[m] + w2[j] * nv + bb[j];
;                         if (m == 0) { if (e0) EP[eb0 + hc + (unsigned)j] = cv; } if (m == 3) { if (e3) EP[eb3 + hc + (unsigned)j] = cv; }
.LBB0_1502:
	s_or_b64 exec, exec, s[62:63]
	v_mov_b32_dpp v82, v60 row_ror:1 row_mask:0xf bank_mask:0xf
	v_cndmask_b32_e64 v83, v82, 0, s[12:13]
	v_mov_b32_dpp v81, v60 row_ror:15 row_mask:0xf bank_mask:0xf
	v_mov_b32_dpp v122, v20 row_ror:15 row_mask:0xf bank_mask:0xf
	s_waitcnt vmcnt(3)
	v_mul_f32_e32 v83, v76, v83
	v_cndmask_b32_e64 v81, v81, v122, s[8:9]
	s_waitcnt vmcnt(2)
	v_fmac_f32_e32 v83, v60, v72
	s_waitcnt vmcnt(1)
	v_fmac_f32_e32 v83, v64, v81
	v_mov_b32_dpp v91, v20 row_ror:1 row_mask:0xf bank_mask:0xf
	v_mov_b32_dpp v89, v16 row_ror:1 row_mask:0xf bank_mask:0xf
	v_mov_b32_dpp v120, v16 row_ror:15 row_mask:0xf bank_mask:0xf
	v_mov_b32_dpp v88, v56 row_ror:1 row_mask:0xf bank_mask:0xf
	v_mov_b32_dpp v121, v56 row_ror:15 row_mask:0xf bank_mask:0xf
	s_waitcnt vmcnt(0)
	v_add_f32_e32 v132, v68, v83
	s_and_saveexec_b64 s[62:63], s[12:13]
	s_cbranch_execz .LBB0_1504
	v_mov_b32_e32 v90, v89
	v_mov_b32_e32 v81, v177
	v_lshl_add_u64 v[84:85], v[80:81], 2, s[20:21]
	v_mov_b64_e32 v[88:89], v[90:91]
	v_mov_b32_e32 v91, v82
	global_store_dword v[84:85], v132, off

; template <int CTRL> __device__ __forceinline__ float dpp_ror(float v) { return __builtin_bit_cast(float, __builtin_amdgcn_update_dpp(0, __builtin_bit_cast(int, v), CTRL, 0xf, 0xf, false)); }
;     __device__ __forceinline__ void operator()(pg8::f32x4 (&acc)[2][2][4][2], const pg8::Unit& u, int wr_, int wc_, int fr_, int fq_) const {
;     ...
;                     for (int m = 0; m < 4; ++m) { gg[m] = acc[ai][0][m][n][j]; pr[m] = dpp_ror<0x121>(gg[m]); nx[m] = dpp_ror<0x12F>(gg[m]); }
; #pragma unroll
;                     for (int m = 0; m < 4; ++m) {
;                         const float pv = fr > 0 ? pr[m] : (m > 0 ? pr[m > 0 ? m - 1 : 0] : 0.f);
;                         const float nv = fr < 15 ? nx[m] : (m < 3 ? nx[m < 3 ? m + 1 : 3] : 0.f);
;                         const float cv = w0[j] * pv + w1[j] * gg[m] + w2[j] * nv + bb[j];
;                         if (m == 0) { if (e0) EP[eb0 + hc + (unsigned)j] = cv; } if (m == 3) { if (e3) EP[eb3 + hc + (unsigned)j] = cv; }
.LBB0_1506:
	s_or_b64 exec, exec, s[62:63]
	v_mov_b32_dpp v56, v61 row_ror:1 row_mask:0xf bank_mask:0xf
	v_cndmask_b32_e64 v81, v56, 0, s[12:13]
	v_mov_b32_dpp v60, v61 row_ror:15 row_mask:0xf bank_mask:0xf
	v_mov_b32_dpp v125, v21 row_ror:15 row_mask:0xf bank_mask:0xf
	v_mul_f32_e32 v81, v77, v81
	v_cndmask_b32_e64 v60, v60, v125, s[8:9]
	v_fmac_f32_e32 v81, v61, v73
	v_fmac_f32_e32 v81, v65, v60
	v_mov_b32_dpp v95, v21 row_ror:1 row_mask:0xf bank_mask:0xf
	v_mov_b32_dpp v93, v17 row_ror:1 row_mask:0xf bank_mask:0xf
	v_mov_b32_dpp v123, v17 row_ror:15 row_mask:0xf bank_mask:0xf
	v_mov_b32_dpp v92, v57 row_ror:1 row_mask:0xf bank_mask:0xf
	v_mov_b32_dpp v124, v57 row_ror:15 row_mask:0xf bank_mask:0xf
	v_add_f32_e32 v133, v69, v81
	s_and_saveexec_b64 s[62:63], s[12:13]
	s_cbranch_execz .LBB0_1508
	v_mov_b32_e32 v94, v93
	v_or_b32_e32 v60, 1, v80
	v_mov_b32_e32 v61, v177
	v_lshl_add_u64 v[60:61], v[60:61], 2, s[20:21]
	v_mov_b64_e32 v[92:93], v[94:95]
	v_mov_b32_e32 v95, v56
	global_store_dword v[60:61], v133, off

; template <int CTRL> __device__ __forceinline__ float dpp_ror(float v) { return __builtin_bit_cast(float, __builtin_amdgcn_update_dpp(0, __builtin_bit_cast(int, v), CTRL, 0xf, 0xf, false)); }
;     __device__ __forceinline__ void operator()(pg8::f32x4 (&acc)[2][2][4][2], const pg8::Unit& u, int wr_, int wc_, int fr_, int fq_) const {
;     ...
;                     for (int m = 0; m < 4; ++m) { gg[m] = acc[ai][0][m][n][j]; pr[m] = dpp_ror<0x121>(gg[m]); nx[m] = dpp_ror<0x12F>(gg[m]); }
; #pragma unroll
;                     for (int m = 0; m < 4; ++m) {
;                         const float pv = fr > 0 ? pr[m] : (m > 0 ? pr[m > 0 ? m - 1 : 0] : 0.f);
;                         const float nv = fr < 15 ? nx[m] : (m < 3 ? nx[m < 3 ? m + 1 : 3] : 0.f);
;                         const float cv = w0[j] * pv + w1[j] * gg[m] + w2[j] * nv + bb[j];
;                         if (m == 0) { if (e0) EP[eb0 + hc + (unsigned)j] = cv; } if (m == 3) { if (e3) EP[eb3 + hc + (unsigned)j] = cv; }
.LBB0_1510:
	s_or_b64 exec, exec, s[62:63]
	v_mov_b32_dpp v56, v62 row_ror:1 row_mask:0xf bank_mask:0xf
	v_cndmask_b32_e64 v60, v56, 0, s[12:13]
	v_mov_b32_dpp v57, v62 row_ror:15 row_mask:0xf bank_mask:0xf
	v_mov_b32_dpp v128, v22 row_ror:15 row_mask:0xf bank_mask:0xf
	v_mul_f32_e32 v60, v78, v60
	v_cndmask_b32_e64 v57, v57, v128, s[8:9]
	v_fmac_f32_e32 v60, v62, v74
	v_fmac_f32_e32 v60, v66, v57
	v_mov_b32_dpp v99, v22 row_ror:1 row_mask:0xf bank_mask:0xf
	v_mov_b32_dpp v97, v18 row_ror:1 row_mask:0xf bank_mask:0xf
	v_mov_b32_dpp v126, v18 row_ror:15 row_mask:0xf bank_mask:0xf
	v_mov_b32_dpp v96, v58 row_ror:1 row_mask:0xf bank_mask:0xf
	v_mov_b32_dpp v127, v58 row_ror:15 row_mask:0xf bank_mask:0xf
	v_add_f32_e32 v136, v70, v60
	s_and_saveexec_b64 s[62:63], s[12:13]
	s_cbranch_execz .LBB0_1512
	v_mov_b32_e32 v98, v97
	v_or_b32_e32 v60, 2, v80
	v_mov_b32_e32 v61, v177
	v_lshl_add_u64 v[60:61], v[60:61], 2, s[20:21]
	v_mov_b64_e32 v[96:97], v[98:99]
	v_mov_b32_e32 v99, v56
	global_store_dword v[60:61], v136, off

; template <int CTRL> __device__ __forceinline__ float dpp_ror(float v) { return __builtin_bit_cast(float, __builtin_amdgcn_update_dpp(0, __builtin_bit_cast(int, v), CTRL, 0xf, 0xf, false)); }
;     __device__ __forceinline__ void operator()(pg8::f32x4 (&acc)[2][2][4][2], const pg8::Unit& u, int wr_, int wc_, int fr_, int fq_) const {
;     ...
;                     for (int m = 0; m < 4; ++m) { gg[m] = acc[ai][0][m][n][j]; pr[m] = dpp_ror<0x121>(gg[m]); nx[m] = dpp_ror<0x12F>(gg[m]); }
; #pragma unroll
;                     for (int m = 0; m < 4; ++m) {
;                         const float pv = fr > 0 ? pr[m] : (m > 0 ? pr[m > 0 ? m - 1 : 0] : 0.f);
;                         const float nv = fr < 15 ? nx[m] : (m < 3 ? nx[m < 3 ? m + 1 : 3] : 0.f);
;                         const float cv = w0[j] * pv + w1[j] * gg[m] + w2[j] * nv + bb[j];
;                         if (m == 0) { if (e0) EP[eb0 + hc + (unsigned)j] = cv; } if (m == 3) { if (e3) EP[eb3 + hc + (unsigned)j] = cv; }
.LBB0_1514:
	s_or_b64 exec, exec, s[62:63]
	v_mov_b32_dpp v56, v63 row_ror:1 row_mask:0xf bank_mask:0xf
	v_cndmask_b32_e64 v58, v56, 0, s[12:13]
	v_mov_b32_dpp v57, v63 row_ror:15 row_mask:0xf bank_mask:0xf
	v_mov_b32_dpp v131, v23 row_ror:15 row_mask:0xf bank_mask:0xf
	v_mul_f32_e32 v58, v79, v58
	v_cndmask_b32_e64 v57, v57, v131, s[8:9]
	v_fmac_f32_e32 v58, v63, v75
	v_fmac_f32_e32 v58, v67, v57
	v_mov_b32_dpp v103, v23 row_ror:1 row_mask:0xf bank_mask:0xf
	v_mov_b32_dpp v101, v19 row_ror:1 row_mask:0xf bank_mask:0xf
	v_mov_b32_dpp v129, v19 row_ror:15 row_mask:0xf bank_mask:0xf
	v_mov_b32_dpp v100, v59 row_ror:1 row_mask:0xf bank_mask:0xf
	v_mov_b32_dpp v130, v59 row_ror:15 row_mask:0xf bank_mask:0xf
	v_add_f32_e32 v137, v71, v58
	s_and_saveexec_b64 s[62:63], s[12:13]
	s_cbranch_execz .LBB0_1516
	v_mov_b32_e32 v102, v101
	v_or_b32_e32 v60, 3, v80
	v_mov_b32_e32 v61, v177
	v_lshl_add_u64 v[60:61], v[60:61], 2, s[20:21]
	v_mov_b64_e32 v[100:101], v[102:103]
	v_mov_b32_e32 v103, v56
	global_store_dword v[60:61], v137, off

; template <int CTRL> __device__ __forceinline__ float dpp_ror(float v) { return __builtin_bit_cast(float, __builtin_amdgcn_update_dpp(0, __builtin_bit_cast(int, v), CTRL, 0xf, 0xf, false)); }
;     __device__ __forceinline__ void operator()(pg8::f32x4 (&acc)[2][2][4][2], const pg8::Unit& u, int wr_, int wc_, int fr_, int fq_) const {
;     ...
;                     for (int m = 0; m < 4; ++m) { gg[m] = acc[ai][0][m][n][j]; pr[m] = dpp_ror<0x121>(gg[m]); nx[m] = dpp_ror<0x12F>(gg[m]); }
; #pragma unroll
;                     for (int m = 0; m < 4; ++m) {
;                         const float pv = fr > 0 ? pr[m] : (m > 0 ? pr[m > 0 ? m - 1 : 0] : 0.f);
;                         const float nv = fr < 15 ? nx[m] : (m < 3 ? nx[m < 3 ? m + 1 : 3] : 0.f);
;                         const float cv = w0[j] * pv + w1[j] * gg[m] + w2[j] * nv + bb[j];
;                         if (m == 0) { if (e0) EP[eb0 + hc + (unsigned)j] = cv; } if (m == 3) { if (e3) EP[eb3 + hc + (unsigned)j] = cv; }
.LBB0_1522:
	s_or_b64 exec, exec, s[62:63]
	v_mov_b32_dpp v96, v52 row_ror:1 row_mask:0xf bank_mask:0xf
	v_cndmask_b32_e64 v106, v96, 0, s[12:13]
	v_mov_b32_dpp v98, v52 row_ror:15 row_mask:0xf bank_mask:0xf
	v_mov_b32_dpp v134, v36 row_ror:15 row_mask:0xf bank_mask:0xf
	s_waitcnt vmcnt(3)
	v_mul_f32_e32 v106, v84, v106
	v_cndmask_b32_e64 v98, v98, v134, s[8:9]
	s_waitcnt vmcnt(2)
	v_fmac_f32_e32 v106, v52, v80
	s_waitcnt vmcnt(1)
	v_fmac_f32_e32 v106, v56, v98
	v_mov_b32_dpp v107, v36 row_ror:1 row_mask:0xf bank_mask:0xf
	v_mov_b32_dpp v105, v32 row_ror:1 row_mask:0xf bank_mask:0xf
	v_mov_b32_dpp v100, v32 row_ror:15 row_mask:0xf bank_mask:0xf
	v_mov_b32_dpp v104, v48 row_ror:1 row_mask:0xf bank_mask:0xf
	v_mov_b32_dpp v102, v48 row_ror:15 row_mask:0xf bank_mask:0xf
	s_waitcnt vmcnt(0)
	v_add_f32_e32 v139, v60, v106
	s_and_saveexec_b64 s[62:63], s[12:13]
	s_cbranch_execz .LBB0_1524
	v_mov_b32_e32 v117, v177
	v_mov_b32_e32 v106, v105
	v_lshl_add_u64 v[104:105], v[116:117], 2, s[20:21]
	global_store_dword v[104:105], v139, off
	v_mov_b64_e32 v[104:105], v[106:107]
	v_mov_b32_e32 v107, v96

; template <int CTRL> __device__ __forceinline__ float dpp_ror(float v) { return __builtin_bit_cast(float, __builtin_amdgcn_update_dpp(0, __builtin_bit_cast(int, v), CTRL, 0xf, 0xf, false)); }
;     __device__ __forceinline__ void operator()(pg8::f32x4 (&acc)[2][2][4][2], const pg8::Unit& u, int wr_, int wc_, int fr_, int fq_) const {
;     ...
;                     for (int m = 0; m < 4; ++m) { gg[m] = acc[ai][0][m][n][j]; pr[m] = dpp_ror<0x121>(gg[m]); nx[m] = dpp_ror<0x12F>(gg[m]); }
; #pragma unroll
;                     for (int m = 0; m < 4; ++m) {
;                         const float pv = fr > 0 ? pr[m] : (m > 0 ? pr[m > 0 ? m - 1 : 0] : 0.f);
;                         const float nv = fr < 15 ? nx[m] : (m < 3 ? nx[m < 3 ? m + 1 : 3] : 0.f);
;                         const float cv = w0[j] * pv + w1[j] * gg[m] + w2[j] * nv + bb[j];
;                         if (m == 0) { if (e0) EP[eb0 + hc + (unsigned)j] = cv; } if (m == 3) { if (e3) EP[eb3 + hc + (unsigned)j] = cv; }
.LBB0_1526:
	s_or_b64 exec, exec, s[62:63]
	v_mov_b32_dpp v48, v53 row_ror:1 row_mask:0xf bank_mask:0xf
	v_cndmask_b32_e64 v98, v48, 0, s[12:13]
	v_mov_b32_dpp v52, v53 row_ror:15 row_mask:0xf bank_mask:0xf
	v_mov_b32_dpp v117, v37 row_ror:15 row_mask:0xf bank_mask:0xf
	v_mul_f32_e32 v98, v85, v98
	v_cndmask_b32_e64 v52, v52, v117, s[8:9]
	v_fmac_f32_e32 v98, v53, v81
	v_fmac_f32_e32 v98, v57, v52
	v_mov_b32_dpp v111, v37 row_ror:1 row_mask:0xf bank_mask:0xf
	v_mov_b32_dpp v109, v33 row_ror:1 row_mask:0xf bank_mask:0xf
	v_mov_b32_dpp v104, v33 row_ror:15 row_mask:0xf bank_mask:0xf
	v_mov_b32_dpp v108, v49 row_ror:1 row_mask:0xf bank_mask:0xf
	v_mov_b32_dpp v106, v49 row_ror:15 row_mask:0xf bank_mask:0xf
	v_add_f32_e32 v141, v61, v98
	s_and_saveexec_b64 s[62:63], s[12:13]
	s_cbranch_execz .LBB0_1528
	v_mov_b32_e32 v110, v109
	v_or_b32_e32 v52, 1, v116
	v_mov_b32_e32 v53, v177
	v_lshl_add_u64 v[52:53], v[52:53], 2, s[20:21]
	v_mov_b64_e32 v[108:109], v[110:111]
	v_mov_b32_e32 v111, v48
	global_store_dword v[52:53], v141, off

; template <int CTRL> __device__ __forceinline__ float dpp_ror(float v) { return __builtin_bit_cast(float, __builtin_amdgcn_update_dpp(0, __builtin_bit_cast(int, v), CTRL, 0xf, 0xf, false)); }
;     __device__ __forceinline__ void operator()(pg8::f32x4 (&acc)[2][2][4][2], const pg8::Unit& u, int wr_, int wc_, int fr_, int fq_) const {
;     ...
;                     for (int m = 0; m < 4; ++m) { gg[m] = acc[ai][0][m][n][j]; pr[m] = dpp_ror<0x121>(gg[m]); nx[m] = dpp_ror<0x12F>(gg[m]); }
; #pragma unroll
;                     for (int m = 0; m < 4; ++m) {
;                         const float pv = fr > 0 ? pr[m] : (m > 0 ? pr[m > 0 ? m - 1 : 0] : 0.f);
;                         const float nv = fr < 15 ? nx[m] : (m < 3 ? nx[m < 3 ? m + 1 : 3] : 0.f);
;                         const float cv = w0[j] * pv + w1[j] * gg[m] + w2[j] * nv + bb[j];
;                         if (m == 0) { if (e0) EP[eb0 + hc + (unsigned)j] = cv; } if (m == 3) { if (e3) EP[eb3 + hc + (unsigned)j] = cv; }
.LBB0_1530:
	s_or_b64 exec, exec, s[62:63]
	v_mov_b32_dpp v112, v54 row_ror:1 row_mask:0xf bank_mask:0xf
	v_cndmask_b32_e64 v113, v112, 0, s[12:13]
	v_mov_b32_dpp v52, v54 row_ror:15 row_mask:0xf bank_mask:0xf
	v_mov_b32_dpp v138, v38 row_ror:15 row_mask:0xf bank_mask:0xf
	v_mul_f32_e32 v113, v86, v113
	v_cndmask_b32_e64 v52, v52, v138, s[8:9]
	v_fmac_f32_e32 v113, v54, v82
	v_fmac_f32_e32 v113, v58, v52
	v_mov_b32_dpp v53, v38 row_ror:1 row_mask:0xf bank_mask:0xf
	v_mov_b32_dpp v49, v34 row_ror:1 row_mask:0xf bank_mask:0xf
	v_mov_b32_dpp v108, v34 row_ror:15 row_mask:0xf bank_mask:0xf
	v_mov_b32_dpp v48, v50 row_ror:1 row_mask:0xf bank_mask:0xf
	v_mov_b32_dpp v110, v50 row_ror:15 row_mask:0xf bank_mask:0xf
	v_add_f32_e32 v142, v62, v113
	s_and_saveexec_b64 s[62:63], s[12:13]
	s_cbranch_execz .LBB0_1532
	v_mov_b32_e32 v52, v49
	v_or_b32_e32 v48, 2, v116
	v_mov_b32_e32 v49, v177
	v_lshl_add_u64 v[48:49], v[48:49], 2, s[20:21]
	global_store_dword v[48:49], v142, off
	v_mov_b64_e32 v[48:49], v[52:53]
	v_mov_b32_e32 v53, v112

; template <int CTRL> __device__ __forceinline__ float dpp_ror(float v) { return __builtin_bit_cast(float, __builtin_amdgcn_update_dpp(0, __builtin_bit_cast(int, v), CTRL, 0xf, 0xf, false)); }
;     __device__ __forceinline__ void operator()(pg8::f32x4 (&acc)[2][2][4][2], const pg8::Unit& u, int wr_, int wc_, int fr_, int fq_) const {
;     ...
;                     for (int m = 0; m < 4; ++m) { gg[m] = acc[ai][0][m][n][j]; pr[m] = dpp_ror<0x121>(gg[m]); nx[m] = dpp_ror<0x12F>(gg[m]); }
; #pragma unroll
;                     for (int m = 0; m < 4; ++m) {
;                         const float pv = fr > 0 ? pr[m] : (m > 0 ? pr[m > 0 ? m - 1 : 0] : 0.f);
;                         const float nv = fr < 15 ? nx[m] : (m < 3 ? nx[m < 3 ? m + 1 : 3] : 0.f);
;                         const float cv = w0[j] * pv + w1[j] * gg[m] + w2[j] * nv + bb[j];
;                         if (m == 0) { if (e0) EP[eb0 + hc + (unsigned)j] = cv; } if (m == 3) { if (e3) EP[eb3 + hc + (unsigned)j] = cv; }
.LBB0_1534:
	s_or_b64 exec, exec, s[62:63]
	v_mov_b32_dpp v50, v55 row_ror:1 row_mask:0xf bank_mask:0xf
	v_cndmask_b32_e64 v143, v50, 0, s[12:13]
	v_mov_b32_dpp v114, v55 row_ror:15 row_mask:0xf bank_mask:0xf
	v_mov_b32_dpp v140, v39 row_ror:15 row_mask:0xf bank_mask:0xf
	v_mul_f32_e32 v143, v87, v143
	v_cndmask_b32_e64 v114, v114, v140, s[8:9]
	v_fmac_f32_e32 v143, v55, v83
	v_fmac_f32_e32 v143, v59, v114
	v_mov_b32_dpp v115, v39 row_ror:1 row_mask:0xf bank_mask:0xf
	v_mov_b32_dpp v113, v35 row_ror:1 row_mask:0xf bank_mask:0xf
	v_mov_b32_dpp v52, v35 row_ror:15 row_mask:0xf bank_mask:0xf
	v_mov_b32_dpp v112, v51 row_ror:1 row_mask:0xf bank_mask:0xf
	v_mov_b32_dpp v54, v51 row_ror:15 row_mask:0xf bank_mask:0xf
	v_add_f32_e32 v143, v63, v143
	s_and_saveexec_b64 s[62:63], s[12:13]
	s_cbranch_execz .LBB0_1536
	v_mov_b32_e32 v114, v113
	v_or_b32_e32 v112, 3, v116
	v_mov_b32_e32 v113, v177
	v_lshl_add_u64 v[112:113], v[112:113], 2, s[20:21]
	global_store_dword v[112:113], v143, off
	v_mov_b64_e32 v[112:113], v[114:115]
	v_mov_b32_e32 v115, v50

; #define PG8_STAGE(bufoff, gbase, voff) do { _Pragma("unroll") for (int _i = 0; _i < 2; ++_i) \
;         __builtin_amdgcn_global_load_lds((const unsigned*)((const char*)(gbase) + (voff)[_i]), (PG8_LAS unsigned*)(lds + (bufoff) + ldsw + _i * 8192), 16, 0, 0); } while (0)
; #define PG8_LDA(dst, b, h) do { _Pragma("unroll") for (int m = 0; m < 4; ++m) _Pragma("unroll") for (int k = 0; k < 2; ++k) dst[m][k] = *(const PG8_LAS bf16x8*)(lds + PG8_SA(b, h) + aoff + m * 2048 + k * 1024); } while (0)
; #define PG8_LDB(dst, b, h) do { _Pragma("unroll") for (int n = 0; n < 2; ++n) _Pragma("unroll") for (int k = 0; k < 2; ++k) dst[n][k] = *(const PG8_LAS bf16x8*)(lds + PG8_SB(b, h) + boff + n * 2048 + k * 1024); } while (0)
; #define PG8_MMA(ai, bj, At, Bt) do { __builtin_amdgcn_s_setprio(1); _Pragma("unroll") for (int m = 0; m < 4; ++m) _Pragma("unroll") for (int n = 0; n < 2; ++n) _Pragma("unroll") for (int k = 0; k < 2; ++k) \
;         acc[ai][bj][m][n] = __builtin_amdgcn_mfma_f32_16x16x32_bf16(Bt[n][k], At[m][k], acc[ai][bj][m][n], 0, 0, 0); __builtin_amdgcn_s_setprio(0); } while (0)
; #define PG8_WAIT_V(n) asm volatile("s_waitcnt vmcnt(" #n ")" ::: "memory")
; #define PG8_WAIT_L(n) asm volatile("s_waitcnt lgkmcnt(" #n ")" ::: "memory")
; template <class Epi, class Sched, bool ALIGN_EPI = false, bool SP2 = false>
; __device__ __forceinline__ void gemm_phase(PG8_LAS unsigned char* lds, const int Kdim  , const int Klen  , const Sched& S, const Epi& E, const int wave_s) {
;     ...
;             const bool last = (t == nt - 2);
;             const char* a1 = cA + (size_t)(t + 1) * kstep;
;             const char* a2 = last ? nA : cA + (size_t)(t + 2) * kstep; const char* b2 = last ? nB : cB + (size_t)(t + 2) * kstep;
;             const char* a3 = a2 + kstep; const char* b3 = b2 + kstep;
;             if (last && has_next) S.a_ready(nxt);
;             if constexpr (SP2) {
;             PG8_LDB(B0, 0, 0); PG8_LDB(B1, 0, 1); PG8_SCHED; PG8_LDA(At, 0, 0); PG8_STAGE(PG8_SA(1, 1), a1 + hstep, voffA);
;             PG8_WAIT_V(8); PG8_WAIT_L(0); PG8_BAR; PG8_MMA(0, 0, At, B0); PG8_MMA(0, 1, At, B1); PG8_BAR; PG8_SCHED;
;             PG8_LDA(At, 0, 1); PG8_STAGE(PG8_SB(0, 0), b2, voffB); PG8_STAGE(PG8_SB(0, 1), b2 + hstep, voffB); PG8_STAGE(PG8_SA(0, 0), a2, voffA);
;             PG8_WAIT_V(8); PG8_WAIT_L(0); PG8_BAR; PG8_MMA(1, 0, At, B0); PG8_MMA(1, 1, At, B1); PG8_BAR; PG8_SCHED;
.LBB0_1669:
	s_add_u32 s21, s14, 0x100
	s_addc_u32 s28, s15, 0
	s_mov_b32 s29, -2
	v_add_u32_e32 v140, s90, v186
	v_add_u32_e32 v156, s65, v186
	ds_read_b128 v[128:131], v140
	ds_read_b128 v[132:135], v140 offset:1024
	ds_read_b128 v[136:139], v140 offset:2048
	ds_read_b128 v[140:143], v140 offset:3072
	ds_read_b128 v[144:147], v156
	ds_read_b128 v[148:151], v156 offset:1024
	ds_read_b128 v[152:155], v156 offset:2048
	ds_read_b128 v[156:159], v156 offset:3072
	s_add_u32 s8, s6, 0x100
	s_addc_u32 s9, s7, 0
	s_cmpk_eq_i32 s29, 0x54
	s_cselect_b32 s27, s23, s9
	s_cselect_b32 s26, s22, s8
	s_cselect_b32 s11, s15, s28
	s_cselect_b32 s10, s14, s21
	v_lshl_add_u64 v[174:175], s[6:7], 0, v[162:163]
	s_add_i32 m0, s2, 0xc000
	ds_read_b128 v[166:169], v187
	ds_read_b128 v[170:173], v187 offset:1024
	ds_read_b128 v[178:181], v187 offset:2048
	ds_read_b128 v[182:185], v187 offset:3072
	ds_read_b128 v[188:191], v187 offset:4096
	ds_read_b128 v[192:195], v187 offset:5120
	ds_read_b128 v[196:199], v187 offset:6144
	ds_read_b128 v[200:203], v187 offset:7168
	global_load_lds_dwordx4 v[174:175], off
	v_lshl_add_u64 v[174:175], s[6:7], 0, v[164:165]
	s_add_i32 m0, s2, 0xe000
	s_nop 0
	global_load_lds_dwordx4 v[174:175], off
	s_waitcnt vmcnt(8)
	s_waitcnt lgkmcnt(0)
	s_barrier
	s_setprio 1
	s_waitcnt lgkmcnt(0)
	v_mfma_f32_16x16x32_bf16 v[116:119], v[128:131], v[166:169], 0
	v_mfma_f32_16x16x32_bf16 v[112:115], v[136:139], v[166:169], 0
	v_mfma_f32_16x16x32_bf16 v[36:39], v[128:131], v[178:181], 0
	v_mfma_f32_16x16x32_bf16 v[40:43], v[136:139], v[178:181], 0
	v_mfma_f32_16x16x32_bf16 v[68:71], v[128:131], v[188:191], 0
	v_mfma_f32_16x16x32_bf16 v[72:75], v[136:139], v[188:191], 0
	v_mfma_f32_16x16x32_bf16 v[92:95], v[128:131], v[196:199], 0
	v_mfma_f32_16x16x32_bf16 v[96:99], v[136:139], v[196:199], 0
	v_mfma_f32_16x16x32_bf16 v[116:119], v[132:135], v[170:173], v[116:119]
	v_mfma_f32_16x16x32_bf16 v[112:115], v[140:143], v[170:173], v[112:115]
	v_mfma_f32_16x16x32_bf16 v[36:39], v[132:135], v[182:185], v[36:39]
	v_mfma_f32_16x16x32_bf16 v[40:43], v[140:143], v[182:185], v[40:43]
	v_mfma_f32_16x16x32_bf16 v[68:71], v[132:135], v[192:195], v[68:71]
	v_mfma_f32_16x16x32_bf16 v[72:75], v[140:143], v[192:195], v[72:75]
	v_mfma_f32_16x16x32_bf16 v[92:95], v[132:135], v[200:203], v[92:95]
	v_mfma_f32_16x16x32_bf16 v[96:99], v[140:143], v[200:203], v[96:99]
	s_setprio 0
	s_setprio 1
	v_mfma_f32_16x16x32_bf16 v[120:123], v[144:147], v[166:169], 0
	v_mfma_f32_16x16x32_bf16 v[124:127], v[152:155], v[166:169], 0
	v_mfma_f32_16x16x32_bf16 v[48:51], v[144:147], v[178:181], 0
	v_mfma_f32_16x16x32_bf16 v[52:55], v[152:155], v[178:181], 0
	v_mfma_f32_16x16x32_bf16 v[80:83], v[144:147], v[188:191], 0
	v_mfma_f32_16x16x32_bf16 v[84:87], v[152:155], v[188:191], 0
	v_mfma_f32_16x16x32_bf16 v[104:107], v[144:147], v[196:199], 0
	v_mfma_f32_16x16x32_bf16 v[108:111], v[152:155], v[196:199], 0
	v_mfma_f32_16x16x32_bf16 v[120:123], v[148:151], v[170:173], v[120:123]
	v_mfma_f32_16x16x32_bf16 v[124:127], v[156:159], v[170:173], v[124:127]
	v_mfma_f32_16x16x32_bf16 v[48:51], v[148:151], v[182:185], v[48:51]
	v_mfma_f32_16x16x32_bf16 v[52:55], v[156:159], v[182:185], v[52:55]
	v_mfma_f32_16x16x32_bf16 v[80:83], v[148:151], v[192:195], v[80:83]
	v_mfma_f32_16x16x32_bf16 v[84:87], v[156:159], v[192:195], v[84:87]
	v_mfma_f32_16x16x32_bf16 v[104:107], v[148:151], v[200:203], v[104:107]
	v_mfma_f32_16x16x32_bf16 v[108:111], v[156:159], v[200:203], v[108:111]
	s_setprio 0
	s_barrier
	s_add_i32 s6, s90, s0
	v_lshl_add_u64 v[174:175], s[10:11], 0, v[176:177]
	s_mov_b32 m0, s6
	ds_read_b128 v[166:169], v187 offset:16384
	ds_read_b128 v[170:173], v187 offset:17408
	ds_read_b128 v[178:181], v187 offset:18432
	ds_read_b128 v[182:185], v187 offset:19456
	ds_read_b128 v[188:191], v187 offset:20480
	ds_read_b128 v[192:195], v187 offset:21504
	ds_read_b128 v[196:199], v187 offset:22528
	ds_read_b128 v[200:203], v187 offset:23552
	global_load_lds_dwordx4 v[174:175], off
	s_add_i32 m0, s6, 0x2000
	s_add_u32 s6, s10, 0x160000
	v_lshl_add_u64 v[204:205], s[10:11], 0, v[160:161]
	s_addc_u32 s7, s11, 0
	s_add_i32 s30, s65, s0
	global_load_lds_dwordx4 v[204:205], off
	v_lshl_add_u64 v[206:207], s[6:7], 0, v[176:177]
	s_mov_b32 m0, s30
	v_lshl_add_u64 v[208:209], s[26:27], 0, v[160:161]
	global_load_lds_dwordx4 v[206:207], off
	v_lshl_add_u64 v[206:207], s[6:7], 0, v[160:161]
	s_add_i32 m0, s30, 0x2000
	s_nop 0
	global_load_lds_dwordx4 v[206:207], off
	v_lshl_add_u64 v[206:207], s[26:27], 0, v[176:177]
	s_mov_b32 m0, s2
	s_nop 0
	global_load_lds_dwordx4 v[206:207], off
	s_mov_b32 m0, s3
	s_nop 0
	global_load_lds_dwordx4 v[208:209], off
	s_waitcnt vmcnt(8)
	s_waitcnt lgkmcnt(0)
	s_barrier
; #define PG8_STAGE(bufoff, gbase, voff) do { _Pragma("unroll") for (int _i = 0; _i < 2; ++_i) \
;         __builtin_amdgcn_global_load_lds((const unsigned*)((const char*)(gbase) + (voff)[_i]), (PG8_LAS unsigned*)(lds + (bufoff) + ldsw + _i * 8192), 16, 0, 0); } while (0)
; #define PG8_LDA(dst, b, h) do { _Pragma("unroll") for (int m = 0; m < 4; ++m) _Pragma("unroll") for (int k = 0; k < 2; ++k) dst[m][k] = *(const PG8_LAS bf16x8*)(lds + PG8_SA(b, h) + aoff + m * 2048 + k * 1024); } while (0)
; #define PG8_LDB(dst, b, h) do { _Pragma("unroll") for (int n = 0; n < 2; ++n) _Pragma("unroll") for (int k = 0; k < 2; ++k) dst[n][k] = *(const PG8_LAS bf16x8*)(lds + PG8_SB(b, h) + boff + n * 2048 + k * 1024); } while (0)
; #define PG8_MMA(ai, bj, At, Bt) do { __builtin_amdgcn_s_setprio(1); _Pragma("unroll") for (int m = 0; m < 4; ++m) _Pragma("unroll") for (int n = 0; n < 2; ++n) _Pragma("unroll") for (int k = 0; k < 2; ++k) \
;         acc[ai][bj][m][n] = __builtin_amdgcn_mfma_f32_16x16x32_bf16(Bt[n][k], At[m][k], acc[ai][bj][m][n], 0, 0, 0); __builtin_amdgcn_s_setprio(0); } while (0)
; #define PG8_WAIT_V(n) asm volatile("s_waitcnt vmcnt(" #n ")" ::: "memory")
; #define PG8_WAIT_L(n) asm volatile("s_waitcnt lgkmcnt(" #n ")" ::: "memory")
; #define PG8_BAR __builtin_amdgcn_s_barrier()
; #define PG8_SCHED __builtin_amdgcn_sched_barrier(0)
; template <class Epi, class Sched, bool ALIGN_EPI = false, bool SP2 = false>
; __device__ __forceinline__ void gemm_phase(PG8_LAS unsigned char* lds, const int Kdim  , const int Klen  , const Sched& S, const Epi& E, const int wave_s) {
;     ...
;             PG8_WAIT_V(8); PG8_WAIT_L(0); PG8_BAR; PG8_MMA(1, 0, At, B0); PG8_MMA(1, 1, At, B1); PG8_BAR; PG8_SCHED;
;             PG8_LDB(B0, 1, 0); PG8_LDB(B1, 1, 1); PG8_SCHED; PG8_LDA(At, 1, 0); PG8_STAGE(PG8_SA(0, 1), a2 + hstep, voffA);
;             PG8_WAIT_V(8); PG8_WAIT_L(0); PG8_BAR; PG8_MMA(0, 0, At, B0); PG8_MMA(0, 1, At, B1); PG8_BAR; PG8_SCHED;
	s_setprio 1
	s_waitcnt lgkmcnt(0)
	v_mfma_f32_16x16x32_bf16 v[100:103], v[128:131], v[166:169], 0
	v_mfma_f32_16x16x32_bf16 v[88:91], v[136:139], v[166:169], 0
	v_mfma_f32_16x16x32_bf16 v[60:63], v[128:131], v[178:181], 0
	v_mfma_f32_16x16x32_bf16 v[56:59], v[136:139], v[178:181], 0
	v_mfma_f32_16x16x32_bf16 v[28:31], v[128:131], v[188:191], 0
	v_mfma_f32_16x16x32_bf16 v[24:27], v[136:139], v[188:191], 0
	v_mfma_f32_16x16x32_bf16 v[12:15], v[128:131], v[196:199], 0
	v_mfma_f32_16x16x32_bf16 v[8:11], v[136:139], v[196:199], 0
	v_mfma_f32_16x16x32_bf16 v[100:103], v[132:135], v[170:173], v[100:103]
	v_mfma_f32_16x16x32_bf16 v[88:91], v[140:143], v[170:173], v[88:91]
	v_mfma_f32_16x16x32_bf16 v[60:63], v[132:135], v[182:185], v[60:63]
	v_mfma_f32_16x16x32_bf16 v[56:59], v[140:143], v[182:185], v[56:59]
	v_mfma_f32_16x16x32_bf16 v[28:31], v[132:135], v[192:195], v[28:31]
	v_mfma_f32_16x16x32_bf16 v[24:27], v[140:143], v[192:195], v[24:27]
	v_mfma_f32_16x16x32_bf16 v[12:15], v[132:135], v[200:203], v[12:15]
	v_mfma_f32_16x16x32_bf16 v[8:11], v[140:143], v[200:203], v[8:11]
	s_setprio 0
	s_setprio 1
	v_mfma_f32_16x16x32_bf16 v[76:79], v[144:147], v[166:169], 0
	v_mfma_f32_16x16x32_bf16 v[64:67], v[152:155], v[166:169], 0
	v_mfma_f32_16x16x32_bf16 v[44:47], v[144:147], v[178:181], 0
	v_mfma_f32_16x16x32_bf16 v[32:35], v[152:155], v[178:181], 0
	v_mfma_f32_16x16x32_bf16 v[20:23], v[144:147], v[188:191], 0
	v_mfma_f32_16x16x32_bf16 v[16:19], v[152:155], v[188:191], 0
	v_mfma_f32_16x16x32_bf16 v[4:7], v[144:147], v[196:199], 0
	v_mfma_f32_16x16x32_bf16 v[0:3], v[152:155], v[196:199], 0
	v_mfma_f32_16x16x32_bf16 v[76:79], v[148:151], v[170:173], v[76:79]
	v_mfma_f32_16x16x32_bf16 v[64:67], v[156:159], v[170:173], v[64:67]
	v_mfma_f32_16x16x32_bf16 v[44:47], v[148:151], v[182:185], v[44:47]
	v_mfma_f32_16x16x32_bf16 v[32:35], v[156:159], v[182:185], v[32:35]
	v_mfma_f32_16x16x32_bf16 v[20:23], v[148:151], v[192:195], v[20:23]
	v_mfma_f32_16x16x32_bf16 v[16:19], v[156:159], v[192:195], v[16:19]
	v_mfma_f32_16x16x32_bf16 v[4:7], v[148:151], v[200:203], v[4:7]
	v_mfma_f32_16x16x32_bf16 v[0:3], v[156:159], v[200:203], v[0:3]
	s_setprio 0
	s_barrier
	v_add_u32_e32 v140, s71, v186
	v_add_u32_e32 v156, s73, v186
	ds_read_b128 v[128:131], v140
	ds_read_b128 v[132:135], v140 offset:1024
	ds_read_b128 v[136:139], v140 offset:2048
	ds_read_b128 v[140:143], v140 offset:3072
	ds_read_b128 v[144:147], v156
	ds_read_b128 v[148:151], v156 offset:1024
	ds_read_b128 v[152:155], v156 offset:2048
	ds_read_b128 v[156:159], v156 offset:3072
	s_add_u32 s6, s26, 0x160000
	s_addc_u32 s7, s27, 0
	s_mov_b32 m0, s33
	v_lshl_add_u64 v[210:211], s[6:7], 0, v[176:177]
	ds_read_b128 v[166:169], v187 offset:32768
	ds_read_b128 v[170:173], v187 offset:33792
	ds_read_b128 v[178:181], v187 offset:34816
	ds_read_b128 v[182:185], v187 offset:35840
	ds_read_b128 v[188:191], v187 offset:36864
	ds_read_b128 v[192:195], v187 offset:37888
	ds_read_b128 v[196:199], v187 offset:38912
	ds_read_b128 v[200:203], v187 offset:39936
	global_load_lds_dwordx4 v[210:211], off
	v_lshl_add_u64 v[210:211], s[6:7], 0, v[160:161]
	s_mov_b32 m0, s36
	s_nop 0
	global_load_lds_dwordx4 v[210:211], off
	s_waitcnt vmcnt(8)
	s_waitcnt lgkmcnt(0)
	s_barrier
	s_setprio 1
	s_waitcnt lgkmcnt(0)
	v_mfma_f32_16x16x32_bf16 v[116:119], v[128:131], v[166:169], v[116:119]
	v_mfma_f32_16x16x32_bf16 v[112:115], v[136:139], v[166:169], v[112:115]
	v_mfma_f32_16x16x32_bf16 v[36:39], v[128:131], v[178:181], v[36:39]
	v_mfma_f32_16x16x32_bf16 v[40:43], v[136:139], v[178:181], v[40:43]
	v_mfma_f32_16x16x32_bf16 v[68:71], v[128:131], v[188:191], v[68:71]
	v_mfma_f32_16x16x32_bf16 v[72:75], v[136:139], v[188:191], v[72:75]
	v_mfma_f32_16x16x32_bf16 v[92:95], v[128:131], v[196:199], v[92:95]
	v_mfma_f32_16x16x32_bf16 v[96:99], v[136:139], v[196:199], v[96:99]
	v_mfma_f32_16x16x32_bf16 v[116:119], v[132:135], v[170:173], v[116:119]
	v_mfma_f32_16x16x32_bf16 v[112:115], v[140:143], v[170:173], v[112:115]
	v_mfma_f32_16x16x32_bf16 v[36:39], v[132:135], v[182:185], v[36:39]
	v_mfma_f32_16x16x32_bf16 v[40:43], v[140:143], v[182:185], v[40:43]
	v_mfma_f32_16x16x32_bf16 v[68:71], v[132:135], v[192:195], v[68:71]
	v_mfma_f32_16x16x32_bf16 v[72:75], v[140:143], v[192:195], v[72:75]
	v_mfma_f32_16x16x32_bf16 v[92:95], v[132:135], v[200:203], v[92:95]
	v_mfma_f32_16x16x32_bf16 v[96:99], v[140:143], v[200:203], v[96:99]
	s_setprio 0
	s_setprio 1
	v_mfma_f32_16x16x32_bf16 v[120:123], v[144:147], v[166:169], v[120:123]
	v_mfma_f32_16x16x32_bf16 v[124:127], v[152:155], v[166:169], v[124:127]
	v_mfma_f32_16x16x32_bf16 v[48:51], v[144:147], v[178:181], v[48:51]
	v_mfma_f32_16x16x32_bf16 v[52:55], v[152:155], v[178:181], v[52:55]
	v_mfma_f32_16x16x32_bf16 v[80:83], v[144:147], v[188:191], v[80:83]
	v_mfma_f32_16x16x32_bf16 v[84:87], v[152:155], v[188:191], v[84:87]
	v_mfma_f32_16x16x32_bf16 v[104:107], v[144:147], v[196:199], v[104:107]
	v_mfma_f32_16x16x32_bf16 v[108:111], v[152:155], v[196:199], v[108:111]
	v_mfma_f32_16x16x32_bf16 v[120:123], v[148:151], v[170:173], v[120:123]
	v_mfma_f32_16x16x32_bf16 v[124:127], v[156:159], v[170:173], v[124:127]
	v_mfma_f32_16x16x32_bf16 v[48:51], v[148:151], v[182:185], v[48:51]
	v_mfma_f32_16x16x32_bf16 v[52:55], v[156:159], v[182:185], v[52:55]
	v_mfma_f32_16x16x32_bf16 v[80:83], v[148:151], v[192:195], v[80:83]
	v_mfma_f32_16x16x32_bf16 v[84:87], v[156:159], v[192:195], v[84:87]
	v_mfma_f32_16x16x32_bf16 v[104:107], v[148:151], v[200:203], v[104:107]
	v_mfma_f32_16x16x32_bf16 v[108:111], v[156:159], v[200:203], v[108:111]
	s_setprio 0
	s_barrier
; #define PG8_STAGE(bufoff, gbase, voff) do { _Pragma("unroll") for (int _i = 0; _i < 2; ++_i) \
;         __builtin_amdgcn_global_load_lds((const unsigned*)((const char*)(gbase) + (voff)[_i]), (PG8_LAS unsigned*)(lds + (bufoff) + ldsw + _i * 8192), 16, 0, 0); } while (0)
; #define PG8_LDA(dst, b, h) do { _Pragma("unroll") for (int m = 0; m < 4; ++m) _Pragma("unroll") for (int k = 0; k < 2; ++k) dst[m][k] = *(const PG8_LAS bf16x8*)(lds + PG8_SA(b, h) + aoff + m * 2048 + k * 1024); } while (0)
; #define PG8_LDB(dst, b, h) do { _Pragma("unroll") for (int n = 0; n < 2; ++n) _Pragma("unroll") for (int k = 0; k < 2; ++k) dst[n][k] = *(const PG8_LAS bf16x8*)(lds + PG8_SB(b, h) + boff + n * 2048 + k * 1024); } while (0)
; #define PG8_MMA(ai, bj, At, Bt) do { __builtin_amdgcn_s_setprio(1); _Pragma("unroll") for (int m = 0; m < 4; ++m) _Pragma("unroll") for (int n = 0; n < 2; ++n) _Pragma("unroll") for (int k = 0; k < 2; ++k) \
;         acc[ai][bj][m][n] = __builtin_amdgcn_mfma_f32_16x16x32_bf16(Bt[n][k], At[m][k], acc[ai][bj][m][n], 0, 0, 0); __builtin_amdgcn_s_setprio(0); } while (0)
; #define PG8_WAIT_V(n) asm volatile("s_waitcnt vmcnt(" #n ")" ::: "memory")
; #define PG8_WAIT_L(n) asm volatile("s_waitcnt lgkmcnt(" #n ")" ::: "memory")
; #define PG8_BAR __builtin_amdgcn_s_barrier()
; #define PG8_SCHED __builtin_amdgcn_sched_barrier(0)
; template <class Epi, class Sched, bool ALIGN_EPI = false, bool SP2 = false>
; __device__ __forceinline__ void gemm_phase(PG8_LAS unsigned char* lds, const int Kdim  , const int Klen  , const Sched& S, const Epi& E, const int wave_s) {
;     ...
;             PG8_LDB(B0, 1, 0); PG8_LDB(B1, 1, 1); PG8_SCHED; PG8_LDA(At, 1, 0); PG8_STAGE(PG8_SA(0, 1), a2 + hstep, voffA);
;             PG8_WAIT_V(8); PG8_WAIT_L(0); PG8_BAR; PG8_MMA(0, 0, At, B0); PG8_MMA(0, 1, At, B1); PG8_BAR; PG8_SCHED;
;             PG8_LDA(At, 1, 1); PG8_STAGE(PG8_SB(1, 0), b3, voffB); PG8_STAGE(PG8_SB(1, 1), b3 + hstep, voffB); PG8_STAGE(PG8_SA(1, 0), a3, voffA);
;             PG8_WAIT_V(8); PG8_WAIT_L(0); PG8_BAR; PG8_MMA(1, 0, At, B0); PG8_MMA(1, 1, At, B1); PG8_BAR; PG8_SCHED;
	s_add_i32 s6, s71, s0
	v_lshl_add_u64 v[174:175], v[174:175], 0, s[96:97]
	s_mov_b32 m0, s6
	ds_read_b128 v[166:169], v187 offset:49152
	ds_read_b128 v[170:173], v187 offset:50176
	ds_read_b128 v[178:181], v187 offset:51200
	ds_read_b128 v[182:185], v187 offset:52224
	ds_read_b128 v[188:191], v187 offset:53248
	ds_read_b128 v[192:195], v187 offset:54272
	ds_read_b128 v[196:199], v187 offset:55296
	ds_read_b128 v[200:203], v187 offset:56320
	global_load_lds_dwordx4 v[174:175], off
	s_add_i32 m0, s6, 0x2000
	s_add_u32 s6, s10, 0x160080
	v_lshl_add_u64 v[174:175], v[204:205], 0, s[96:97]
	s_addc_u32 s7, s11, 0
	s_add_i32 s10, s73, s0
	global_load_lds_dwordx4 v[174:175], off
	v_lshl_add_u64 v[174:175], s[6:7], 0, v[176:177]
	s_mov_b32 m0, s10
	s_nop 0
	global_load_lds_dwordx4 v[174:175], off
	v_lshl_add_u64 v[174:175], s[6:7], 0, v[160:161]
	s_add_i32 m0, s10, 0x2000
	s_nop 0
	global_load_lds_dwordx4 v[174:175], off
	v_lshl_add_u64 v[174:175], v[206:207], 0, s[96:97]
	s_mov_b32 m0, s37
	s_nop 0
	global_load_lds_dwordx4 v[174:175], off
	v_lshl_add_u64 v[174:175], v[208:209], 0, s[96:97]
	s_mov_b32 m0, s41
	s_nop 0
	global_load_lds_dwordx4 v[174:175], off
	s_waitcnt vmcnt(8)
	s_waitcnt lgkmcnt(0)
	s_barrier
	s_setprio 1
	s_waitcnt lgkmcnt(0)
	v_mfma_f32_16x16x32_bf16 v[100:103], v[128:131], v[166:169], v[100:103]
	v_mfma_f32_16x16x32_bf16 v[88:91], v[136:139], v[166:169], v[88:91]
	v_mfma_f32_16x16x32_bf16 v[60:63], v[128:131], v[178:181], v[60:63]
	v_mfma_f32_16x16x32_bf16 v[56:59], v[136:139], v[178:181], v[56:59]
	v_mfma_f32_16x16x32_bf16 v[28:31], v[128:131], v[188:191], v[28:31]
	v_mfma_f32_16x16x32_bf16 v[24:27], v[136:139], v[188:191], v[24:27]
	v_mfma_f32_16x16x32_bf16 v[12:15], v[128:131], v[196:199], v[12:15]
	v_mfma_f32_16x16x32_bf16 v[8:11], v[136:139], v[196:199], v[8:11]
	v_mfma_f32_16x16x32_bf16 v[100:103], v[132:135], v[170:173], v[100:103]
	v_mfma_f32_16x16x32_bf16 v[88:91], v[140:143], v[170:173], v[88:91]
	v_mfma_f32_16x16x32_bf16 v[60:63], v[132:135], v[182:185], v[60:63]
	v_mfma_f32_16x16x32_bf16 v[56:59], v[140:143], v[182:185], v[56:59]
	v_mfma_f32_16x16x32_bf16 v[28:31], v[132:135], v[192:195], v[28:31]
	v_mfma_f32_16x16x32_bf16 v[24:27], v[140:143], v[192:195], v[24:27]
	v_mfma_f32_16x16x32_bf16 v[12:15], v[132:135], v[200:203], v[12:15]
	v_mfma_f32_16x16x32_bf16 v[8:11], v[140:143], v[200:203], v[8:11]
	s_setprio 0
	s_setprio 1
	v_mfma_f32_16x16x32_bf16 v[76:79], v[144:147], v[166:169], v[76:79]
	v_mfma_f32_16x16x32_bf16 v[64:67], v[152:155], v[166:169], v[64:67]
	v_mfma_f32_16x16x32_bf16 v[44:47], v[144:147], v[178:181], v[44:47]
	v_mfma_f32_16x16x32_bf16 v[32:35], v[152:155], v[178:181], v[32:35]
	v_mfma_f32_16x16x32_bf16 v[20:23], v[144:147], v[188:191], v[20:23]
	v_mfma_f32_16x16x32_bf16 v[16:19], v[152:155], v[188:191], v[16:19]
	v_mfma_f32_16x16x32_bf16 v[4:7], v[144:147], v[196:199], v[4:7]
	v_mfma_f32_16x16x32_bf16 v[0:3], v[152:155], v[196:199], v[0:3]
	v_mfma_f32_16x16x32_bf16 v[76:79], v[148:151], v[170:173], v[76:79]
	v_mfma_f32_16x16x32_bf16 v[64:67], v[156:159], v[170:173], v[64:67]
	v_mfma_f32_16x16x32_bf16 v[44:47], v[148:151], v[182:185], v[44:47]
	v_mfma_f32_16x16x32_bf16 v[32:35], v[156:159], v[182:185], v[32:35]
	v_mfma_f32_16x16x32_bf16 v[20:23], v[148:151], v[192:195], v[20:23]
	v_mfma_f32_16x16x32_bf16 v[16:19], v[156:159], v[192:195], v[16:19]
	v_mfma_f32_16x16x32_bf16 v[4:7], v[148:151], v[200:203], v[4:7]
	v_mfma_f32_16x16x32_bf16 v[0:3], v[156:159], v[200:203], v[0:3]
	s_setprio 0
	s_barrier
	s_add_i32 s29, s29, 2
	s_add_u32 s21, s21, 0x100
	s_addc_u32 s28, s28, 0
	s_cmpk_gt_u32 s29, 0x55
	s_mov_b64 s[6:7], s[8:9]
	s_cbranch_scc1 .Lkdone_4

; #define PG8_BAR __builtin_amdgcn_s_barrier()
; template <class Epi, class Sched, bool ALIGN_EPI = false, bool SP2 = false>
; __device__ __forceinline__ void gemm_phase(PG8_LAS unsigned char* lds, const int Kdim  , const int Klen  , const Sched& S, const Epi& E, const int wave_s) {
;     ...
;         }
;         if constexpr (ALIGN_EPI) { if (wr == 0) PG8_BAR; }
.Lkdone_4:
	s_and_b64 vcc, exec, s[18:19]
	s_cbranch_vccz .LBB0_1673
	s_barrier

; #define PG8_STAGE(bufoff, gbase, voff) do { _Pragma("unroll") for (int _i = 0; _i < 2; ++_i) \
;         __builtin_amdgcn_global_load_lds((const unsigned*)((const char*)(gbase) + (voff)[_i]), (PG8_LAS unsigned*)(lds + (bufoff) + ldsw + _i * 8192), 16, 0, 0); } while (0)
; #define PG8_LDA(dst, b, h) do { _Pragma("unroll") for (int m = 0; m < 4; ++m) _Pragma("unroll") for (int k = 0; k < 2; ++k) dst[m][k] = *(const PG8_LAS bf16x8*)(lds + PG8_SA(b, h) + aoff + m * 2048 + k * 1024); } while (0)
; #define PG8_LDB(dst, b, h) do { _Pragma("unroll") for (int n = 0; n < 2; ++n) _Pragma("unroll") for (int k = 0; k < 2; ++k) dst[n][k] = *(const PG8_LAS bf16x8*)(lds + PG8_SB(b, h) + boff + n * 2048 + k * 1024); } while (0)
; #define PG8_MMA(ai, bj, At, Bt) do { __builtin_amdgcn_s_setprio(1); _Pragma("unroll") for (int m = 0; m < 4; ++m) _Pragma("unroll") for (int n = 0; n < 2; ++n) _Pragma("unroll") for (int k = 0; k < 2; ++k) \
;         acc[ai][bj][m][n] = __builtin_amdgcn_mfma_f32_16x16x32_bf16(Bt[n][k], At[m][k], acc[ai][bj][m][n], 0, 0, 0); __builtin_amdgcn_s_setprio(0); } while (0)
; #define PG8_WAIT_V(n) asm volatile("s_waitcnt vmcnt(" #n ")" ::: "memory")
; #define PG8_WAIT_L(n) asm volatile("s_waitcnt lgkmcnt(" #n ")" ::: "memory")
; template <class Epi, class Sched, bool ALIGN_EPI = false, bool SP2 = false>
; __device__ __forceinline__ void gemm_phase(PG8_LAS unsigned char* lds, const int Kdim  , const int Klen  , const Sched& S, const Epi& E, const int wave_s) {
;     ...
;             const bool last = (t == nt - 2);
;             const char* a1 = cA + (size_t)(t + 1) * kstep;
;             const char* a2 = last ? nA : cA + (size_t)(t + 2) * kstep; const char* b2 = last ? nB : cB + (size_t)(t + 2) * kstep;
;             const char* a3 = a2 + kstep; const char* b3 = b2 + kstep;
;             if (last && has_next) S.a_ready(nxt);
;             if constexpr (SP2) {
;             PG8_LDB(B0, 0, 0); PG8_LDB(B1, 0, 1); PG8_SCHED; PG8_LDA(At, 0, 0); PG8_STAGE(PG8_SA(1, 1), a1 + hstep, voffA);
;             PG8_WAIT_V(8); PG8_WAIT_L(0); PG8_BAR; PG8_MMA(0, 0, At, B0); PG8_MMA(0, 1, At, B1); PG8_BAR; PG8_SCHED;
;             PG8_LDA(At, 0, 1); PG8_STAGE(PG8_SB(0, 0), b2, voffB); PG8_STAGE(PG8_SB(0, 1), b2 + hstep, voffB); PG8_STAGE(PG8_SA(0, 0), a2, voffA);
;             PG8_WAIT_V(8); PG8_WAIT_L(0); PG8_BAR; PG8_MMA(1, 0, At, B0); PG8_MMA(1, 1, At, B1); PG8_BAR; PG8_SCHED;
.LBB0_1727:
	s_add_u32 s23, s4, 0x100
	s_addc_u32 s30, s5, 0
	s_mov_b32 s31, -2
	v_add_u32_e32 v140, s90, v208
	v_add_u32_e32 v156, s65, v208
	ds_read_b128 v[128:131], v140
	ds_read_b128 v[132:135], v140 offset:1024
	ds_read_b128 v[136:139], v140 offset:2048
	ds_read_b128 v[140:143], v140 offset:3072
	ds_read_b128 v[144:147], v156
	ds_read_b128 v[148:151], v156 offset:1024
	ds_read_b128 v[152:155], v156 offset:2048
	ds_read_b128 v[156:159], v156 offset:3072
	s_add_u32 s8, s6, 0x100
	s_addc_u32 s9, s7, 0
	s_cmpk_eq_i32 s31, 0x54
	s_cselect_b32 s29, s25, s9
	s_cselect_b32 s28, s24, s8
	s_cselect_b32 s11, s5, s30
	s_cselect_b32 s10, s4, s23
	v_lshl_add_u64 v[178:179], s[6:7], 0, v[182:183]
	s_add_i32 m0, s2, 0xc000
	ds_read_b128 v[160:163], v209
	ds_read_b128 v[164:167], v209 offset:1024
	ds_read_b128 v[168:171], v209 offset:2048
	ds_read_b128 v[172:175], v209 offset:3072
	ds_read_b128 v[186:189], v209 offset:4096
	ds_read_b128 v[190:193], v209 offset:5120
	ds_read_b128 v[194:197], v209 offset:6144
	ds_read_b128 v[198:201], v209 offset:7168
	global_load_lds_dwordx4 v[178:179], off
	v_lshl_add_u64 v[178:179], s[6:7], 0, v[184:185]
	s_add_i32 m0, s2, 0xe000
	s_nop 0
	global_load_lds_dwordx4 v[178:179], off
	s_waitcnt vmcnt(8)
	s_waitcnt lgkmcnt(0)
	s_barrier
	s_setprio 1
	s_waitcnt lgkmcnt(0)
	v_mfma_f32_16x16x32_bf16 v[76:79], v[128:131], v[160:163], 0
	v_mfma_f32_16x16x32_bf16 v[68:71], v[136:139], v[160:163], 0
	v_mfma_f32_16x16x32_bf16 v[92:95], v[128:131], v[168:171], 0
	v_mfma_f32_16x16x32_bf16 v[88:91], v[136:139], v[168:171], 0
	v_mfma_f32_16x16x32_bf16 v[104:107], v[128:131], v[186:189], 0
	v_mfma_f32_16x16x32_bf16 v[96:99], v[136:139], v[186:189], 0
	v_mfma_f32_16x16x32_bf16 v[124:127], v[128:131], v[194:197], 0
	v_mfma_f32_16x16x32_bf16 v[120:123], v[136:139], v[194:197], 0
	v_mfma_f32_16x16x32_bf16 v[76:79], v[132:135], v[164:167], v[76:79]
	v_mfma_f32_16x16x32_bf16 v[68:71], v[140:143], v[164:167], v[68:71]
	v_mfma_f32_16x16x32_bf16 v[92:95], v[132:135], v[172:175], v[92:95]
	v_mfma_f32_16x16x32_bf16 v[88:91], v[140:143], v[172:175], v[88:91]
	v_mfma_f32_16x16x32_bf16 v[104:107], v[132:135], v[190:193], v[104:107]
	v_mfma_f32_16x16x32_bf16 v[96:99], v[140:143], v[190:193], v[96:99]
	v_mfma_f32_16x16x32_bf16 v[124:127], v[132:135], v[198:201], v[124:127]
	v_mfma_f32_16x16x32_bf16 v[120:123], v[140:143], v[198:201], v[120:123]
	s_setprio 0
	s_setprio 1
	v_mfma_f32_16x16x32_bf16 v[64:67], v[144:147], v[160:163], 0
	v_mfma_f32_16x16x32_bf16 v[60:63], v[152:155], v[160:163], 0
	v_mfma_f32_16x16x32_bf16 v[84:87], v[144:147], v[168:171], 0
	v_mfma_f32_16x16x32_bf16 v[80:83], v[152:155], v[168:171], 0
	v_mfma_f32_16x16x32_bf16 v[100:103], v[144:147], v[186:189], 0
	v_mfma_f32_16x16x32_bf16 v[108:111], v[152:155], v[186:189], 0
	v_mfma_f32_16x16x32_bf16 v[116:119], v[144:147], v[194:197], 0
	v_mfma_f32_16x16x32_bf16 v[112:115], v[152:155], v[194:197], 0
	v_mfma_f32_16x16x32_bf16 v[64:67], v[148:151], v[164:167], v[64:67]
	v_mfma_f32_16x16x32_bf16 v[60:63], v[156:159], v[164:167], v[60:63]
	v_mfma_f32_16x16x32_bf16 v[84:87], v[148:151], v[172:175], v[84:87]
	v_mfma_f32_16x16x32_bf16 v[80:83], v[156:159], v[172:175], v[80:83]
	v_mfma_f32_16x16x32_bf16 v[100:103], v[148:151], v[190:193], v[100:103]
	v_mfma_f32_16x16x32_bf16 v[108:111], v[156:159], v[190:193], v[108:111]
	v_mfma_f32_16x16x32_bf16 v[116:119], v[148:151], v[198:201], v[116:119]
	v_mfma_f32_16x16x32_bf16 v[112:115], v[156:159], v[198:201], v[112:115]
	s_setprio 0
	s_barrier
	s_add_i32 s6, s90, s0
	v_lshl_add_u64 v[178:179], s[10:11], 0, v[176:177]
	s_mov_b32 m0, s6
	ds_read_b128 v[160:163], v209 offset:16384
	ds_read_b128 v[164:167], v209 offset:17408
	ds_read_b128 v[168:171], v209 offset:18432
	ds_read_b128 v[172:175], v209 offset:19456
	ds_read_b128 v[186:189], v209 offset:20480
	ds_read_b128 v[190:193], v209 offset:21504
	ds_read_b128 v[194:197], v209 offset:22528
	ds_read_b128 v[198:201], v209 offset:23552
	global_load_lds_dwordx4 v[178:179], off
	s_add_i32 m0, s6, 0x2000
	s_add_u32 s6, s10, 0x160000
	v_lshl_add_u64 v[202:203], s[10:11], 0, v[180:181]
	s_addc_u32 s7, s11, 0
	s_add_i32 s34, s65, s0
	global_load_lds_dwordx4 v[202:203], off
	v_lshl_add_u64 v[204:205], s[6:7], 0, v[176:177]
	s_mov_b32 m0, s34
	v_lshl_add_u64 v[206:207], s[28:29], 0, v[180:181]
	global_load_lds_dwordx4 v[204:205], off
	v_lshl_add_u64 v[204:205], s[6:7], 0, v[180:181]
	s_add_i32 m0, s34, 0x2000
	s_nop 0
	global_load_lds_dwordx4 v[204:205], off
	v_lshl_add_u64 v[204:205], s[28:29], 0, v[176:177]
	s_mov_b32 m0, s2
	s_nop 0
	global_load_lds_dwordx4 v[204:205], off
	s_mov_b32 m0, s3
	s_nop 0
	global_load_lds_dwordx4 v[206:207], off
	s_waitcnt vmcnt(8)
	s_waitcnt lgkmcnt(0)
	s_barrier
; #define PG8_STAGE(bufoff, gbase, voff) do { _Pragma("unroll") for (int _i = 0; _i < 2; ++_i) \
;         __builtin_amdgcn_global_load_lds((const unsigned*)((const char*)(gbase) + (voff)[_i]), (PG8_LAS unsigned*)(lds + (bufoff) + ldsw + _i * 8192), 16, 0, 0); } while (0)
; #define PG8_LDA(dst, b, h) do { _Pragma("unroll") for (int m = 0; m < 4; ++m) _Pragma("unroll") for (int k = 0; k < 2; ++k) dst[m][k] = *(const PG8_LAS bf16x8*)(lds + PG8_SA(b, h) + aoff + m * 2048 + k * 1024); } while (0)
; #define PG8_LDB(dst, b, h) do { _Pragma("unroll") for (int n = 0; n < 2; ++n) _Pragma("unroll") for (int k = 0; k < 2; ++k) dst[n][k] = *(const PG8_LAS bf16x8*)(lds + PG8_SB(b, h) + boff + n * 2048 + k * 1024); } while (0)
; #define PG8_MMA(ai, bj, At, Bt) do { __builtin_amdgcn_s_setprio(1); _Pragma("unroll") for (int m = 0; m < 4; ++m) _Pragma("unroll") for (int n = 0; n < 2; ++n) _Pragma("unroll") for (int k = 0; k < 2; ++k) \
;         acc[ai][bj][m][n] = __builtin_amdgcn_mfma_f32_16x16x32_bf16(Bt[n][k], At[m][k], acc[ai][bj][m][n], 0, 0, 0); __builtin_amdgcn_s_setprio(0); } while (0)
; #define PG8_WAIT_V(n) asm volatile("s_waitcnt vmcnt(" #n ")" ::: "memory")
; #define PG8_WAIT_L(n) asm volatile("s_waitcnt lgkmcnt(" #n ")" ::: "memory")
; #define PG8_BAR __builtin_amdgcn_s_barrier()
; #define PG8_SCHED __builtin_amdgcn_sched_barrier(0)
; template <class Epi, class Sched, bool ALIGN_EPI = false, bool SP2 = false>
; __device__ __forceinline__ void gemm_phase(PG8_LAS unsigned char* lds, const int Kdim  , const int Klen  , const Sched& S, const Epi& E, const int wave_s) {
;     ...
;             PG8_WAIT_V(8); PG8_WAIT_L(0); PG8_BAR; PG8_MMA(1, 0, At, B0); PG8_MMA(1, 1, At, B1); PG8_BAR; PG8_SCHED;
;             PG8_LDB(B0, 1, 0); PG8_LDB(B1, 1, 1); PG8_SCHED; PG8_LDA(At, 1, 0); PG8_STAGE(PG8_SA(0, 1), a2 + hstep, voffA);
;             PG8_WAIT_V(8); PG8_WAIT_L(0); PG8_BAR; PG8_MMA(0, 0, At, B0); PG8_MMA(0, 1, At, B1); PG8_BAR; PG8_SCHED;
	s_setprio 1
	s_waitcnt lgkmcnt(0)
	v_mfma_f32_16x16x32_bf16 v[72:75], v[128:131], v[160:163], 0
	v_mfma_f32_16x16x32_bf16 v[56:59], v[136:139], v[160:163], 0
	v_mfma_f32_16x16x32_bf16 v[44:47], v[128:131], v[168:171], 0
	v_mfma_f32_16x16x32_bf16 v[40:43], v[136:139], v[168:171], 0
	v_mfma_f32_16x16x32_bf16 v[28:31], v[128:131], v[186:189], 0
	v_mfma_f32_16x16x32_bf16 v[24:27], v[136:139], v[186:189], 0
	v_mfma_f32_16x16x32_bf16 v[12:15], v[128:131], v[194:197], 0
	v_mfma_f32_16x16x32_bf16 v[8:11], v[136:139], v[194:197], 0
	v_mfma_f32_16x16x32_bf16 v[72:75], v[132:135], v[164:167], v[72:75]
	v_mfma_f32_16x16x32_bf16 v[56:59], v[140:143], v[164:167], v[56:59]
	v_mfma_f32_16x16x32_bf16 v[44:47], v[132:135], v[172:175], v[44:47]
	v_mfma_f32_16x16x32_bf16 v[40:43], v[140:143], v[172:175], v[40:43]
	v_mfma_f32_16x16x32_bf16 v[28:31], v[132:135], v[190:193], v[28:31]
	v_mfma_f32_16x16x32_bf16 v[24:27], v[140:143], v[190:193], v[24:27]
	v_mfma_f32_16x16x32_bf16 v[12:15], v[132:135], v[198:201], v[12:15]
	v_mfma_f32_16x16x32_bf16 v[8:11], v[140:143], v[198:201], v[8:11]
	s_setprio 0
	s_setprio 1
	v_mfma_f32_16x16x32_bf16 v[52:55], v[144:147], v[160:163], 0
	v_mfma_f32_16x16x32_bf16 v[48:51], v[152:155], v[160:163], 0
	v_mfma_f32_16x16x32_bf16 v[36:39], v[144:147], v[168:171], 0
	v_mfma_f32_16x16x32_bf16 v[32:35], v[152:155], v[168:171], 0
	v_mfma_f32_16x16x32_bf16 v[20:23], v[144:147], v[186:189], 0
	v_mfma_f32_16x16x32_bf16 v[16:19], v[152:155], v[186:189], 0
	v_mfma_f32_16x16x32_bf16 v[4:7], v[144:147], v[194:197], 0
	v_mfma_f32_16x16x32_bf16 v[0:3], v[152:155], v[194:197], 0
	v_mfma_f32_16x16x32_bf16 v[52:55], v[148:151], v[164:167], v[52:55]
	v_mfma_f32_16x16x32_bf16 v[48:51], v[156:159], v[164:167], v[48:51]
	v_mfma_f32_16x16x32_bf16 v[36:39], v[148:151], v[172:175], v[36:39]
	v_mfma_f32_16x16x32_bf16 v[32:35], v[156:159], v[172:175], v[32:35]
	v_mfma_f32_16x16x32_bf16 v[20:23], v[148:151], v[190:193], v[20:23]
	v_mfma_f32_16x16x32_bf16 v[16:19], v[156:159], v[190:193], v[16:19]
	v_mfma_f32_16x16x32_bf16 v[4:7], v[148:151], v[198:201], v[4:7]
	v_mfma_f32_16x16x32_bf16 v[0:3], v[156:159], v[198:201], v[0:3]
	s_setprio 0
	s_barrier
	v_add_u32_e32 v140, s71, v208
	v_add_u32_e32 v156, s73, v208
	ds_read_b128 v[128:131], v140
	ds_read_b128 v[132:135], v140 offset:1024
	ds_read_b128 v[136:139], v140 offset:2048
	ds_read_b128 v[140:143], v140 offset:3072
	ds_read_b128 v[144:147], v156
	ds_read_b128 v[148:151], v156 offset:1024
	ds_read_b128 v[152:155], v156 offset:2048
	ds_read_b128 v[156:159], v156 offset:3072
	s_add_u32 s6, s28, 0x160000
	s_addc_u32 s7, s29, 0
	s_mov_b32 m0, s33
	v_lshl_add_u64 v[210:211], s[6:7], 0, v[176:177]
	ds_read_b128 v[160:163], v209 offset:32768
	ds_read_b128 v[164:167], v209 offset:33792
	ds_read_b128 v[168:171], v209 offset:34816
	ds_read_b128 v[172:175], v209 offset:35840
	ds_read_b128 v[186:189], v209 offset:36864
	ds_read_b128 v[190:193], v209 offset:37888
	ds_read_b128 v[194:197], v209 offset:38912
	ds_read_b128 v[198:201], v209 offset:39936
	global_load_lds_dwordx4 v[210:211], off
	v_lshl_add_u64 v[210:211], s[6:7], 0, v[180:181]
	s_mov_b32 m0, s41
	s_nop 0
	global_load_lds_dwordx4 v[210:211], off
	s_waitcnt vmcnt(8)
	s_waitcnt lgkmcnt(0)
	s_barrier
	s_setprio 1
	s_waitcnt lgkmcnt(0)
	v_mfma_f32_16x16x32_bf16 v[76:79], v[128:131], v[160:163], v[76:79]
	v_mfma_f32_16x16x32_bf16 v[68:71], v[136:139], v[160:163], v[68:71]
	v_mfma_f32_16x16x32_bf16 v[92:95], v[128:131], v[168:171], v[92:95]
	v_mfma_f32_16x16x32_bf16 v[88:91], v[136:139], v[168:171], v[88:91]
	v_mfma_f32_16x16x32_bf16 v[104:107], v[128:131], v[186:189], v[104:107]
	v_mfma_f32_16x16x32_bf16 v[96:99], v[136:139], v[186:189], v[96:99]
	v_mfma_f32_16x16x32_bf16 v[124:127], v[128:131], v[194:197], v[124:127]
	v_mfma_f32_16x16x32_bf16 v[120:123], v[136:139], v[194:197], v[120:123]
	v_mfma_f32_16x16x32_bf16 v[76:79], v[132:135], v[164:167], v[76:79]
	v_mfma_f32_16x16x32_bf16 v[68:71], v[140:143], v[164:167], v[68:71]
	v_mfma_f32_16x16x32_bf16 v[92:95], v[132:135], v[172:175], v[92:95]
	v_mfma_f32_16x16x32_bf16 v[88:91], v[140:143], v[172:175], v[88:91]
	v_mfma_f32_16x16x32_bf16 v[104:107], v[132:135], v[190:193], v[104:107]
	v_mfma_f32_16x16x32_bf16 v[96:99], v[140:143], v[190:193], v[96:99]
	v_mfma_f32_16x16x32_bf16 v[124:127], v[132:135], v[198:201], v[124:127]
	v_mfma_f32_16x16x32_bf16 v[120:123], v[140:143], v[198:201], v[120:123]
	s_setprio 0
	s_setprio 1
	v_mfma_f32_16x16x32_bf16 v[64:67], v[144:147], v[160:163], v[64:67]
	v_mfma_f32_16x16x32_bf16 v[60:63], v[152:155], v[160:163], v[60:63]
	v_mfma_f32_16x16x32_bf16 v[84:87], v[144:147], v[168:171], v[84:87]
	v_mfma_f32_16x16x32_bf16 v[80:83], v[152:155], v[168:171], v[80:83]
	v_mfma_f32_16x16x32_bf16 v[100:103], v[144:147], v[186:189], v[100:103]
	v_mfma_f32_16x16x32_bf16 v[108:111], v[152:155], v[186:189], v[108:111]
	v_mfma_f32_16x16x32_bf16 v[116:119], v[144:147], v[194:197], v[116:119]
	v_mfma_f32_16x16x32_bf16 v[112:115], v[152:155], v[194:197], v[112:115]
	v_mfma_f32_16x16x32_bf16 v[64:67], v[148:151], v[164:167], v[64:67]
	v_mfma_f32_16x16x32_bf16 v[60:63], v[156:159], v[164:167], v[60:63]
	v_mfma_f32_16x16x32_bf16 v[84:87], v[148:151], v[172:175], v[84:87]
	v_mfma_f32_16x16x32_bf16 v[80:83], v[156:159], v[172:175], v[80:83]
	v_mfma_f32_16x16x32_bf16 v[100:103], v[148:151], v[190:193], v[100:103]
	v_mfma_f32_16x16x32_bf16 v[108:111], v[156:159], v[190:193], v[108:111]
	v_mfma_f32_16x16x32_bf16 v[116:119], v[148:151], v[198:201], v[116:119]
	v_mfma_f32_16x16x32_bf16 v[112:115], v[156:159], v[198:201], v[112:115]
	s_setprio 0
	s_barrier
; #define PG8_STAGE(bufoff, gbase, voff) do { _Pragma("unroll") for (int _i = 0; _i < 2; ++_i) \
;         __builtin_amdgcn_global_load_lds((const unsigned*)((const char*)(gbase) + (voff)[_i]), (PG8_LAS unsigned*)(lds + (bufoff) + ldsw + _i * 8192), 16, 0, 0); } while (0)
; #define PG8_LDA(dst, b, h) do { _Pragma("unroll") for (int m = 0; m < 4; ++m) _Pragma("unroll") for (int k = 0; k < 2; ++k) dst[m][k] = *(const PG8_LAS bf16x8*)(lds + PG8_SA(b, h) + aoff + m * 2048 + k * 1024); } while (0)
; #define PG8_MMA(ai, bj, At, Bt) do { __builtin_amdgcn_s_setprio(1); _Pragma("unroll") for (int m = 0; m < 4; ++m) _Pragma("unroll") for (int n = 0; n < 2; ++n) _Pragma("unroll") for (int k = 0; k < 2; ++k) \
;         acc[ai][bj][m][n] = __builtin_amdgcn_mfma_f32_16x16x32_bf16(Bt[n][k], At[m][k], acc[ai][bj][m][n], 0, 0, 0); __builtin_amdgcn_s_setprio(0); } while (0)
; #define PG8_WAIT_V(n) asm volatile("s_waitcnt vmcnt(" #n ")" ::: "memory")
; #define PG8_WAIT_L(n) asm volatile("s_waitcnt lgkmcnt(" #n ")" ::: "memory")
; #define PG8_BAR __builtin_amdgcn_s_barrier()
; #define PG8_SCHED __builtin_amdgcn_sched_barrier(0)
; template <class Epi, class Sched, bool ALIGN_EPI = false, bool SP2 = false>
; __device__ __forceinline__ void gemm_phase(PG8_LAS unsigned char* lds, const int Kdim  , const int Klen  , const Sched& S, const Epi& E, const int wave_s) {
;     ...
;         for (int t = 0; t < nt; t += 2) {
;             const bool last = (t == nt - 2);
;     ...
;             PG8_LDA(At, 1, 1); PG8_STAGE(PG8_SB(1, 0), b3, voffB); PG8_STAGE(PG8_SB(1, 1), b3 + hstep, voffB); PG8_STAGE(PG8_SA(1, 0), a3, voffA);
;             PG8_WAIT_V(8); PG8_WAIT_L(0); PG8_BAR; PG8_MMA(1, 0, At, B0); PG8_MMA(1, 1, At, B1); PG8_BAR; PG8_SCHED;
	s_add_i32 s6, s71, s0
	v_lshl_add_u64 v[178:179], v[178:179], 0, s[96:97]
	s_mov_b32 m0, s6
	ds_read_b128 v[160:163], v209 offset:49152
	ds_read_b128 v[164:167], v209 offset:50176
	ds_read_b128 v[168:171], v209 offset:51200
	ds_read_b128 v[172:175], v209 offset:52224
	ds_read_b128 v[186:189], v209 offset:53248
	ds_read_b128 v[190:193], v209 offset:54272
	ds_read_b128 v[194:197], v209 offset:55296
	ds_read_b128 v[198:201], v209 offset:56320
	global_load_lds_dwordx4 v[178:179], off
	s_add_i32 m0, s6, 0x2000
	s_add_u32 s6, s10, 0x160080
	v_lshl_add_u64 v[178:179], v[202:203], 0, s[96:97]
	s_addc_u32 s7, s11, 0
	s_add_i32 s10, s73, s0
	global_load_lds_dwordx4 v[178:179], off
	v_lshl_add_u64 v[178:179], s[6:7], 0, v[176:177]
	s_mov_b32 m0, s10
	s_nop 0
	global_load_lds_dwordx4 v[178:179], off
	v_lshl_add_u64 v[178:179], s[6:7], 0, v[180:181]
	s_add_i32 m0, s10, 0x2000
	s_nop 0
	global_load_lds_dwordx4 v[178:179], off
	v_lshl_add_u64 v[178:179], v[204:205], 0, s[96:97]
	s_mov_b32 m0, s67
	s_nop 0
	global_load_lds_dwordx4 v[178:179], off
	v_lshl_add_u64 v[178:179], v[206:207], 0, s[96:97]
	s_mov_b32 m0, s74
	s_nop 0
	global_load_lds_dwordx4 v[178:179], off
	s_waitcnt vmcnt(8)
	s_waitcnt lgkmcnt(0)
	s_barrier
	s_setprio 1
	s_waitcnt lgkmcnt(0)
	v_mfma_f32_16x16x32_bf16 v[72:75], v[128:131], v[160:163], v[72:75]
	v_mfma_f32_16x16x32_bf16 v[56:59], v[136:139], v[160:163], v[56:59]
	v_mfma_f32_16x16x32_bf16 v[44:47], v[128:131], v[168:171], v[44:47]
	v_mfma_f32_16x16x32_bf16 v[40:43], v[136:139], v[168:171], v[40:43]
	v_mfma_f32_16x16x32_bf16 v[28:31], v[128:131], v[186:189], v[28:31]
	v_mfma_f32_16x16x32_bf16 v[24:27], v[136:139], v[186:189], v[24:27]
	v_mfma_f32_16x16x32_bf16 v[12:15], v[128:131], v[194:197], v[12:15]
	v_mfma_f32_16x16x32_bf16 v[8:11], v[136:139], v[194:197], v[8:11]
	v_mfma_f32_16x16x32_bf16 v[72:75], v[132:135], v[164:167], v[72:75]
	v_mfma_f32_16x16x32_bf16 v[56:59], v[140:143], v[164:167], v[56:59]
	v_mfma_f32_16x16x32_bf16 v[44:47], v[132:135], v[172:175], v[44:47]
	v_mfma_f32_16x16x32_bf16 v[40:43], v[140:143], v[172:175], v[40:43]
	v_mfma_f32_16x16x32_bf16 v[28:31], v[132:135], v[190:193], v[28:31]
	v_mfma_f32_16x16x32_bf16 v[24:27], v[140:143], v[190:193], v[24:27]
	v_mfma_f32_16x16x32_bf16 v[12:15], v[132:135], v[198:201], v[12:15]
	v_mfma_f32_16x16x32_bf16 v[8:11], v[140:143], v[198:201], v[8:11]
	s_setprio 0
	s_setprio 1
	v_mfma_f32_16x16x32_bf16 v[52:55], v[144:147], v[160:163], v[52:55]
	v_mfma_f32_16x16x32_bf16 v[48:51], v[152:155], v[160:163], v[48:51]
	v_mfma_f32_16x16x32_bf16 v[36:39], v[144:147], v[168:171], v[36:39]
	v_mfma_f32_16x16x32_bf16 v[32:35], v[152:155], v[168:171], v[32:35]
	v_mfma_f32_16x16x32_bf16 v[20:23], v[144:147], v[186:189], v[20:23]
	v_mfma_f32_16x16x32_bf16 v[16:19], v[152:155], v[186:189], v[16:19]
	v_mfma_f32_16x16x32_bf16 v[4:7], v[144:147], v[194:197], v[4:7]
	v_mfma_f32_16x16x32_bf16 v[0:3], v[152:155], v[194:197], v[0:3]
	v_mfma_f32_16x16x32_bf16 v[52:55], v[148:151], v[164:167], v[52:55]
	v_mfma_f32_16x16x32_bf16 v[48:51], v[156:159], v[164:167], v[48:51]
	v_mfma_f32_16x16x32_bf16 v[36:39], v[148:151], v[172:175], v[36:39]
	v_mfma_f32_16x16x32_bf16 v[32:35], v[156:159], v[172:175], v[32:35]
	v_mfma_f32_16x16x32_bf16 v[20:23], v[148:151], v[190:193], v[20:23]
	v_mfma_f32_16x16x32_bf16 v[16:19], v[156:159], v[190:193], v[16:19]
	v_mfma_f32_16x16x32_bf16 v[4:7], v[148:151], v[198:201], v[4:7]
	v_mfma_f32_16x16x32_bf16 v[0:3], v[156:159], v[198:201], v[0:3]
	s_setprio 0
	s_barrier
	s_add_i32 s31, s31, 2
	s_add_u32 s23, s23, 0x100
	s_addc_u32 s30, s30, 0
	s_cmpk_gt_u32 s31, 0x55
	s_mov_b64 s[6:7], s[8:9]
	s_cbranch_scc1 .Lkdone_5

; #define PG8_BAR __builtin_amdgcn_s_barrier()
; template <class Epi, class Sched, bool ALIGN_EPI = false, bool SP2 = false>
; __device__ __forceinline__ void gemm_phase(PG8_LAS unsigned char* lds, const int Kdim  , const int Klen  , const Sched& S, const Epi& E, const int wave_s) {
;     ...
;         if constexpr (ALIGN_EPI) { if (wr == 0) PG8_BAR; }
.Lkdone_5:
	s_and_b64 vcc, exec, s[20:21]
	s_cbranch_vccz .LBB0_1731
	s_barrier

; #define PG8_STAGE(bufoff, gbase, voff) do { _Pragma("unroll") for (int _i = 0; _i < 2; ++_i) \
;         __builtin_amdgcn_global_load_lds((const unsigned*)((const char*)(gbase) + (voff)[_i]), (PG8_LAS unsigned*)(lds + (bufoff) + ldsw + _i * 8192), 16, 0, 0); } while (0)
; #define PG8_LDA(dst, b, h) do { _Pragma("unroll") for (int m = 0; m < 4; ++m) _Pragma("unroll") for (int k = 0; k < 2; ++k) dst[m][k] = *(const PG8_LAS bf16x8*)(lds + PG8_SA(b, h) + aoff + m * 2048 + k * 1024); } while (0)
; #define PG8_LDB(dst, b, h) do { _Pragma("unroll") for (int n = 0; n < 2; ++n) _Pragma("unroll") for (int k = 0; k < 2; ++k) dst[n][k] = *(const PG8_LAS bf16x8*)(lds + PG8_SB(b, h) + boff + n * 2048 + k * 1024); } while (0)
; #define PG8_MMA(ai, bj, At, Bt) do { __builtin_amdgcn_s_setprio(1); _Pragma("unroll") for (int m = 0; m < 4; ++m) _Pragma("unroll") for (int n = 0; n < 2; ++n) _Pragma("unroll") for (int k = 0; k < 2; ++k) \
;         acc[ai][bj][m][n] = __builtin_amdgcn_mfma_f32_16x16x32_bf16(Bt[n][k], At[m][k], acc[ai][bj][m][n], 0, 0, 0); __builtin_amdgcn_s_setprio(0); } while (0)
; #define PG8_WAIT_V(n) asm volatile("s_waitcnt vmcnt(" #n ")" ::: "memory")
; #define PG8_WAIT_L(n) asm volatile("s_waitcnt lgkmcnt(" #n ")" ::: "memory")
; #define PG8_BAR __builtin_amdgcn_s_barrier()
; #define PG8_SCHED __builtin_amdgcn_sched_barrier(0)
; template <class Epi, class Sched, bool ALIGN_EPI = false, bool SP2 = false>
; __device__ __forceinline__ void gemm_phase(PG8_LAS unsigned char* lds, const int Kdim  , const int Klen  , const Sched& S, const Epi& E, const int wave_s) {
;     ...
;     for (int a = 0; a < 2; ++a)
; #pragma unroll
;         for (int b = 0; b < 2; ++b)
; #pragma unroll
;             for (int m = 0; m < 4; ++m)
; #pragma unroll
;                 for (int n = 0; n < 2; ++n) acc[a][b][m][n] = (f32x4){0.f, 0.f, 0.f, 0.f};
;     ...
;             PG8_LDB(B0, 0, 0); PG8_LDB(B1, 0, 1); PG8_SCHED; PG8_LDA(At, 0, 0); PG8_STAGE(PG8_SA(1, 1), a1 + hstep, voffA);
;             PG8_WAIT_V(8); PG8_WAIT_L(0); PG8_BAR; PG8_MMA(0, 0, At, B0); PG8_MMA(0, 1, At, B1); PG8_BAR; PG8_SCHED;
;             PG8_LDA(At, 0, 1); PG8_STAGE(PG8_SB(0, 0), b2, voffB); PG8_STAGE(PG8_SB(0, 1), b2 + hstep, voffB); PG8_STAGE(PG8_SA(0, 0), a2, voffA);
.LBB0_1790:
	s_add_u32 s49, s20, 0x100
	s_addc_u32 s50, s21, 0
	s_mov_b32 s58, -2
	v_add_u32_e32 v132, s90, v156
	v_add_u32_e32 v154, s65, v156
	ds_read_b128 v[112:115], v132
	ds_read_b128 v[116:119], v132 offset:1024
	ds_read_b128 v[120:123], v132 offset:2048
	ds_read_b128 v[132:135], v132 offset:3072
	ds_read_b128 v[150:153], v154
	ds_read_b128 v[158:161], v154 offset:1024
	ds_read_b128 v[162:165], v154 offset:2048
	ds_read_b128 v[166:169], v154 offset:3072
	s_add_u32 s20, s18, 0x100
	s_addc_u32 s21, s19, 0
	s_cmp_eq_u32 s58, 18
	s_cselect_b32 s25, s13, s21
	s_cselect_b32 s24, s12, s20
	s_cselect_b32 s23, s15, s50
	s_cselect_b32 s22, s14, s49
	v_lshl_add_u64 v[154:155], s[18:19], 0, v[146:147]
	s_add_i32 m0, s2, 0xc000
	ds_read_b128 v[170:173], v157
	ds_read_b128 v[178:181], v157 offset:1024
	ds_read_b128 v[182:185], v157 offset:2048
	ds_read_b128 v[186:189], v157 offset:3072
	ds_read_b128 v[190:193], v157 offset:4096
	ds_read_b128 v[194:197], v157 offset:5120
	ds_read_b128 v[198:201], v157 offset:6144
	ds_read_b128 v[202:205], v157 offset:7168
	global_load_lds_dwordx4 v[154:155], off
	v_lshl_add_u64 v[154:155], s[18:19], 0, v[148:149]
	s_add_i32 m0, s2, 0xe000
	s_nop 0
	global_load_lds_dwordx4 v[154:155], off
	s_waitcnt vmcnt(8)
	s_waitcnt lgkmcnt(0)
	s_barrier
	s_setprio 1
	s_waitcnt lgkmcnt(0)
	v_mfma_f32_16x16x32_bf16 v[140:143], v[112:115], v[170:173], 0
	v_mfma_f32_16x16x32_bf16 v[136:139], v[120:123], v[170:173], 0
	v_mfma_f32_16x16x32_bf16 v[108:111], v[112:115], v[182:185], 0
	v_mfma_f32_16x16x32_bf16 v[104:107], v[120:123], v[182:185], 0
	v_mfma_f32_16x16x32_bf16 v[92:95], v[112:115], v[190:193], 0
	v_mfma_f32_16x16x32_bf16 v[88:91], v[120:123], v[190:193], 0
	v_mfma_f32_16x16x32_bf16 v[76:79], v[112:115], v[198:201], 0
	v_mfma_f32_16x16x32_bf16 v[72:75], v[120:123], v[198:201], 0
	v_mfma_f32_16x16x32_bf16 v[140:143], v[116:119], v[178:181], v[140:143]
	v_mfma_f32_16x16x32_bf16 v[136:139], v[132:135], v[178:181], v[136:139]
	v_mfma_f32_16x16x32_bf16 v[108:111], v[116:119], v[186:189], v[108:111]
	v_mfma_f32_16x16x32_bf16 v[104:107], v[132:135], v[186:189], v[104:107]
	v_mfma_f32_16x16x32_bf16 v[92:95], v[116:119], v[194:197], v[92:95]
	v_mfma_f32_16x16x32_bf16 v[88:91], v[132:135], v[194:197], v[88:91]
	v_mfma_f32_16x16x32_bf16 v[76:79], v[116:119], v[202:205], v[76:79]
	v_mfma_f32_16x16x32_bf16 v[72:75], v[132:135], v[202:205], v[72:75]
	s_setprio 0
	s_setprio 1
	v_mfma_f32_16x16x32_bf16 v[128:131], v[150:153], v[170:173], 0
	v_mfma_f32_16x16x32_bf16 v[124:127], v[162:165], v[170:173], 0
	v_mfma_f32_16x16x32_bf16 v[100:103], v[150:153], v[182:185], 0
	v_mfma_f32_16x16x32_bf16 v[96:99], v[162:165], v[182:185], 0
	v_mfma_f32_16x16x32_bf16 v[84:87], v[150:153], v[190:193], 0
	v_mfma_f32_16x16x32_bf16 v[80:83], v[162:165], v[190:193], 0
	v_mfma_f32_16x16x32_bf16 v[68:71], v[150:153], v[198:201], 0
	v_mfma_f32_16x16x32_bf16 v[64:67], v[162:165], v[198:201], 0
	v_mfma_f32_16x16x32_bf16 v[128:131], v[158:161], v[178:181], v[128:131]
	v_mfma_f32_16x16x32_bf16 v[124:127], v[166:169], v[178:181], v[124:127]
	v_mfma_f32_16x16x32_bf16 v[100:103], v[158:161], v[186:189], v[100:103]
	v_mfma_f32_16x16x32_bf16 v[96:99], v[166:169], v[186:189], v[96:99]
	v_mfma_f32_16x16x32_bf16 v[84:87], v[158:161], v[194:197], v[84:87]
	v_mfma_f32_16x16x32_bf16 v[80:83], v[166:169], v[194:197], v[80:83]
	v_mfma_f32_16x16x32_bf16 v[68:71], v[158:161], v[202:205], v[68:71]
	v_mfma_f32_16x16x32_bf16 v[64:67], v[166:169], v[202:205], v[64:67]
	s_setprio 0
	s_barrier
	s_add_i32 s18, s90, s0
	v_lshl_add_u64 v[154:155], s[22:23], 0, v[176:177]
	s_mov_b32 m0, s18
	ds_read_b128 v[170:173], v157 offset:16384
	ds_read_b128 v[178:181], v157 offset:17408
	ds_read_b128 v[182:185], v157 offset:18432
	ds_read_b128 v[186:189], v157 offset:19456
	ds_read_b128 v[190:193], v157 offset:20480
	ds_read_b128 v[194:197], v157 offset:21504
	ds_read_b128 v[198:201], v157 offset:22528
	ds_read_b128 v[202:205], v157 offset:23552
	global_load_lds_dwordx4 v[154:155], off
	s_add_i32 m0, s18, 0x2000
	s_add_u32 s18, s22, 0x160000
	v_lshl_add_u64 v[174:175], s[22:23], 0, v[144:145]
	s_addc_u32 s19, s23, 0
	s_add_i32 s62, s65, s0
	global_load_lds_dwordx4 v[174:175], off
	v_lshl_add_u64 v[206:207], s[18:19], 0, v[176:177]
	s_mov_b32 m0, s62
	v_lshl_add_u64 v[208:209], s[24:25], 0, v[144:145]
	global_load_lds_dwordx4 v[206:207], off
	v_lshl_add_u64 v[206:207], s[18:19], 0, v[144:145]
	s_add_i32 m0, s62, 0x2000
	s_nop 0
	global_load_lds_dwordx4 v[206:207], off
	v_lshl_add_u64 v[206:207], s[24:25], 0, v[176:177]
	s_mov_b32 m0, s2
	s_nop 0
	global_load_lds_dwordx4 v[206:207], off
	s_mov_b32 m0, s3
	s_nop 0
	global_load_lds_dwordx4 v[208:209], off
	s_waitcnt vmcnt(8)
	s_waitcnt lgkmcnt(0)
	s_barrier
; #define PG8_STAGE(bufoff, gbase, voff) do { _Pragma("unroll") for (int _i = 0; _i < 2; ++_i) \
;         __builtin_amdgcn_global_load_lds((const unsigned*)((const char*)(gbase) + (voff)[_i]), (PG8_LAS unsigned*)(lds + (bufoff) + ldsw + _i * 8192), 16, 0, 0); } while (0)
; #define PG8_LDA(dst, b, h) do { _Pragma("unroll") for (int m = 0; m < 4; ++m) _Pragma("unroll") for (int k = 0; k < 2; ++k) dst[m][k] = *(const PG8_LAS bf16x8*)(lds + PG8_SA(b, h) + aoff + m * 2048 + k * 1024); } while (0)
; #define PG8_LDB(dst, b, h) do { _Pragma("unroll") for (int n = 0; n < 2; ++n) _Pragma("unroll") for (int k = 0; k < 2; ++k) dst[n][k] = *(const PG8_LAS bf16x8*)(lds + PG8_SB(b, h) + boff + n * 2048 + k * 1024); } while (0)
; #define PG8_MMA(ai, bj, At, Bt) do { __builtin_amdgcn_s_setprio(1); _Pragma("unroll") for (int m = 0; m < 4; ++m) _Pragma("unroll") for (int n = 0; n < 2; ++n) _Pragma("unroll") for (int k = 0; k < 2; ++k) \
;         acc[ai][bj][m][n] = __builtin_amdgcn_mfma_f32_16x16x32_bf16(Bt[n][k], At[m][k], acc[ai][bj][m][n], 0, 0, 0); __builtin_amdgcn_s_setprio(0); } while (0)
; #define PG8_WAIT_V(n) asm volatile("s_waitcnt vmcnt(" #n ")" ::: "memory")
; #define PG8_WAIT_L(n) asm volatile("s_waitcnt lgkmcnt(" #n ")" ::: "memory")
; #define PG8_BAR __builtin_amdgcn_s_barrier()
; #define PG8_SCHED __builtin_amdgcn_sched_barrier(0)
; template <class Epi, class Sched, bool ALIGN_EPI = false, bool SP2 = false>
; __device__ __forceinline__ void gemm_phase(PG8_LAS unsigned char* lds, const int Kdim  , const int Klen  , const Sched& S, const Epi& E, const int wave_s) {
;     ...
;             PG8_WAIT_V(8); PG8_WAIT_L(0); PG8_BAR; PG8_MMA(1, 0, At, B0); PG8_MMA(1, 1, At, B1); PG8_BAR; PG8_SCHED;
;             PG8_LDB(B0, 1, 0); PG8_LDB(B1, 1, 1); PG8_SCHED; PG8_LDA(At, 1, 0); PG8_STAGE(PG8_SA(0, 1), a2 + hstep, voffA);
;             PG8_WAIT_V(8); PG8_WAIT_L(0); PG8_BAR; PG8_MMA(0, 0, At, B0); PG8_MMA(0, 1, At, B1); PG8_BAR; PG8_SCHED;
	s_setprio 1
	s_waitcnt lgkmcnt(0)
	v_mfma_f32_16x16x32_bf16 v[60:63], v[112:115], v[170:173], 0
	v_mfma_f32_16x16x32_bf16 v[56:59], v[120:123], v[170:173], 0
	v_mfma_f32_16x16x32_bf16 v[52:55], v[112:115], v[182:185], 0
	v_mfma_f32_16x16x32_bf16 v[40:43], v[120:123], v[182:185], 0
	v_mfma_f32_16x16x32_bf16 v[36:39], v[112:115], v[190:193], 0
	v_mfma_f32_16x16x32_bf16 v[24:27], v[120:123], v[190:193], 0
	v_mfma_f32_16x16x32_bf16 v[20:23], v[112:115], v[198:201], 0
	v_mfma_f32_16x16x32_bf16 v[8:11], v[120:123], v[198:201], 0
	v_mfma_f32_16x16x32_bf16 v[60:63], v[116:119], v[178:181], v[60:63]
	v_mfma_f32_16x16x32_bf16 v[56:59], v[132:135], v[178:181], v[56:59]
	v_mfma_f32_16x16x32_bf16 v[52:55], v[116:119], v[186:189], v[52:55]
	v_mfma_f32_16x16x32_bf16 v[40:43], v[132:135], v[186:189], v[40:43]
	v_mfma_f32_16x16x32_bf16 v[36:39], v[116:119], v[194:197], v[36:39]
	v_mfma_f32_16x16x32_bf16 v[24:27], v[132:135], v[194:197], v[24:27]
	v_mfma_f32_16x16x32_bf16 v[20:23], v[116:119], v[202:205], v[20:23]
	v_mfma_f32_16x16x32_bf16 v[8:11], v[132:135], v[202:205], v[8:11]
	s_setprio 0
	s_setprio 1
	v_mfma_f32_16x16x32_bf16 v[48:51], v[150:153], v[170:173], 0
	v_mfma_f32_16x16x32_bf16 v[44:47], v[162:165], v[170:173], 0
	v_mfma_f32_16x16x32_bf16 v[32:35], v[150:153], v[182:185], 0
	v_mfma_f32_16x16x32_bf16 v[28:31], v[162:165], v[182:185], 0
	v_mfma_f32_16x16x32_bf16 v[16:19], v[150:153], v[190:193], 0
	v_mfma_f32_16x16x32_bf16 v[12:15], v[162:165], v[190:193], 0
	v_mfma_f32_16x16x32_bf16 v[4:7], v[150:153], v[198:201], 0
	v_mfma_f32_16x16x32_bf16 v[0:3], v[162:165], v[198:201], 0
	v_mfma_f32_16x16x32_bf16 v[48:51], v[158:161], v[178:181], v[48:51]
	v_mfma_f32_16x16x32_bf16 v[44:47], v[166:169], v[178:181], v[44:47]
	v_mfma_f32_16x16x32_bf16 v[32:35], v[158:161], v[186:189], v[32:35]
	v_mfma_f32_16x16x32_bf16 v[28:31], v[166:169], v[186:189], v[28:31]
	v_mfma_f32_16x16x32_bf16 v[16:19], v[158:161], v[194:197], v[16:19]
	v_mfma_f32_16x16x32_bf16 v[12:15], v[166:169], v[194:197], v[12:15]
	v_mfma_f32_16x16x32_bf16 v[4:7], v[158:161], v[202:205], v[4:7]
	v_mfma_f32_16x16x32_bf16 v[0:3], v[166:169], v[202:205], v[0:3]
	s_setprio 0
	s_barrier
	v_add_u32_e32 v132, s71, v156
	v_add_u32_e32 v166, s73, v156
	ds_read_b128 v[112:115], v132
	ds_read_b128 v[116:119], v132 offset:1024
	ds_read_b128 v[120:123], v132 offset:2048
	ds_read_b128 v[132:135], v132 offset:3072
	ds_read_b128 v[150:153], v166
	ds_read_b128 v[158:161], v166 offset:1024
	ds_read_b128 v[162:165], v166 offset:2048
	ds_read_b128 v[166:169], v166 offset:3072
	s_add_u32 s18, s24, 0x160000
	s_addc_u32 s19, s25, 0
	s_mov_b32 m0, s26
	v_lshl_add_u64 v[210:211], s[18:19], 0, v[176:177]
	ds_read_b128 v[170:173], v157 offset:32768
	ds_read_b128 v[178:181], v157 offset:33792
	ds_read_b128 v[182:185], v157 offset:34816
	ds_read_b128 v[186:189], v157 offset:35840
	ds_read_b128 v[190:193], v157 offset:36864
	ds_read_b128 v[194:197], v157 offset:37888
	ds_read_b128 v[198:201], v157 offset:38912
	ds_read_b128 v[202:205], v157 offset:39936
	global_load_lds_dwordx4 v[210:211], off
	v_lshl_add_u64 v[210:211], s[18:19], 0, v[144:145]
	s_mov_b32 m0, s27
	s_nop 0
	global_load_lds_dwordx4 v[210:211], off
	s_waitcnt vmcnt(8)
	s_waitcnt lgkmcnt(0)
	s_barrier
	s_setprio 1
	s_waitcnt lgkmcnt(0)
	v_mfma_f32_16x16x32_bf16 v[140:143], v[112:115], v[170:173], v[140:143]
	v_mfma_f32_16x16x32_bf16 v[136:139], v[120:123], v[170:173], v[136:139]
	v_mfma_f32_16x16x32_bf16 v[108:111], v[112:115], v[182:185], v[108:111]
	v_mfma_f32_16x16x32_bf16 v[104:107], v[120:123], v[182:185], v[104:107]
	v_mfma_f32_16x16x32_bf16 v[92:95], v[112:115], v[190:193], v[92:95]
	v_mfma_f32_16x16x32_bf16 v[88:91], v[120:123], v[190:193], v[88:91]
	v_mfma_f32_16x16x32_bf16 v[76:79], v[112:115], v[198:201], v[76:79]
	v_mfma_f32_16x16x32_bf16 v[72:75], v[120:123], v[198:201], v[72:75]
	v_mfma_f32_16x16x32_bf16 v[140:143], v[116:119], v[178:181], v[140:143]
	v_mfma_f32_16x16x32_bf16 v[136:139], v[132:135], v[178:181], v[136:139]
	v_mfma_f32_16x16x32_bf16 v[108:111], v[116:119], v[186:189], v[108:111]
	v_mfma_f32_16x16x32_bf16 v[104:107], v[132:135], v[186:189], v[104:107]
	v_mfma_f32_16x16x32_bf16 v[92:95], v[116:119], v[194:197], v[92:95]
	v_mfma_f32_16x16x32_bf16 v[88:91], v[132:135], v[194:197], v[88:91]
	v_mfma_f32_16x16x32_bf16 v[76:79], v[116:119], v[202:205], v[76:79]
	v_mfma_f32_16x16x32_bf16 v[72:75], v[132:135], v[202:205], v[72:75]
	s_setprio 0
	s_setprio 1
	v_mfma_f32_16x16x32_bf16 v[128:131], v[150:153], v[170:173], v[128:131]
	v_mfma_f32_16x16x32_bf16 v[124:127], v[162:165], v[170:173], v[124:127]
	v_mfma_f32_16x16x32_bf16 v[100:103], v[150:153], v[182:185], v[100:103]
	v_mfma_f32_16x16x32_bf16 v[96:99], v[162:165], v[182:185], v[96:99]
	v_mfma_f32_16x16x32_bf16 v[84:87], v[150:153], v[190:193], v[84:87]
	v_mfma_f32_16x16x32_bf16 v[80:83], v[162:165], v[190:193], v[80:83]
	v_mfma_f32_16x16x32_bf16 v[68:71], v[150:153], v[198:201], v[68:71]
	v_mfma_f32_16x16x32_bf16 v[64:67], v[162:165], v[198:201], v[64:67]
	v_mfma_f32_16x16x32_bf16 v[128:131], v[158:161], v[178:181], v[128:131]
	v_mfma_f32_16x16x32_bf16 v[124:127], v[166:169], v[178:181], v[124:127]
	v_mfma_f32_16x16x32_bf16 v[100:103], v[158:161], v[186:189], v[100:103]
	v_mfma_f32_16x16x32_bf16 v[96:99], v[166:169], v[186:189], v[96:99]
	v_mfma_f32_16x16x32_bf16 v[84:87], v[158:161], v[194:197], v[84:87]
	v_mfma_f32_16x16x32_bf16 v[80:83], v[166:169], v[194:197], v[80:83]
	v_mfma_f32_16x16x32_bf16 v[68:71], v[158:161], v[202:205], v[68:71]
	v_mfma_f32_16x16x32_bf16 v[64:67], v[166:169], v[202:205], v[64:67]
	s_setprio 0
	s_barrier
; #define PG8_STAGE(bufoff, gbase, voff) do { _Pragma("unroll") for (int _i = 0; _i < 2; ++_i) \
;         __builtin_amdgcn_global_load_lds((const unsigned*)((const char*)(gbase) + (voff)[_i]), (PG8_LAS unsigned*)(lds + (bufoff) + ldsw + _i * 8192), 16, 0, 0); } while (0)
; #define PG8_LDA(dst, b, h) do { _Pragma("unroll") for (int m = 0; m < 4; ++m) _Pragma("unroll") for (int k = 0; k < 2; ++k) dst[m][k] = *(const PG8_LAS bf16x8*)(lds + PG8_SA(b, h) + aoff + m * 2048 + k * 1024); } while (0)
; #define PG8_MMA(ai, bj, At, Bt) do { __builtin_amdgcn_s_setprio(1); _Pragma("unroll") for (int m = 0; m < 4; ++m) _Pragma("unroll") for (int n = 0; n < 2; ++n) _Pragma("unroll") for (int k = 0; k < 2; ++k) \
;         acc[ai][bj][m][n] = __builtin_amdgcn_mfma_f32_16x16x32_bf16(Bt[n][k], At[m][k], acc[ai][bj][m][n], 0, 0, 0); __builtin_amdgcn_s_setprio(0); } while (0)
; #define PG8_WAIT_V(n) asm volatile("s_waitcnt vmcnt(" #n ")" ::: "memory")
; #define PG8_WAIT_L(n) asm volatile("s_waitcnt lgkmcnt(" #n ")" ::: "memory")
; #define PG8_BAR __builtin_amdgcn_s_barrier()
; #define PG8_SCHED __builtin_amdgcn_sched_barrier(0)
; template <class Epi, class Sched, bool ALIGN_EPI = false, bool SP2 = false>
; __device__ __forceinline__ void gemm_phase(PG8_LAS unsigned char* lds, const int Kdim  , const int Klen  , const Sched& S, const Epi& E, const int wave_s) {
;     ...
;         for (int t = 0; t < nt; t += 2) {
;             const bool last = (t == nt - 2);
;     ...
;             PG8_LDA(At, 1, 1); PG8_STAGE(PG8_SB(1, 0), b3, voffB); PG8_STAGE(PG8_SB(1, 1), b3 + hstep, voffB); PG8_STAGE(PG8_SA(1, 0), a3, voffA);
;             PG8_WAIT_V(8); PG8_WAIT_L(0); PG8_BAR; PG8_MMA(1, 0, At, B0); PG8_MMA(1, 1, At, B1); PG8_BAR; PG8_SCHED;
	s_add_i32 s18, s71, s0
	v_lshl_add_u64 v[154:155], v[154:155], 0, s[96:97]
	s_mov_b32 m0, s18
	ds_read_b128 v[170:173], v157 offset:49152
	ds_read_b128 v[178:181], v157 offset:50176
	ds_read_b128 v[182:185], v157 offset:51200
	ds_read_b128 v[186:189], v157 offset:52224
	ds_read_b128 v[190:193], v157 offset:53248
	ds_read_b128 v[194:197], v157 offset:54272
	ds_read_b128 v[198:201], v157 offset:55296
	ds_read_b128 v[202:205], v157 offset:56320
	global_load_lds_dwordx4 v[154:155], off
	s_add_i32 m0, s18, 0x2000
	s_add_u32 s18, s22, 0x160080
	v_lshl_add_u64 v[154:155], v[174:175], 0, s[96:97]
	s_addc_u32 s19, s23, 0
	s_add_i32 s22, s73, s0
	global_load_lds_dwordx4 v[154:155], off
	v_lshl_add_u64 v[154:155], s[18:19], 0, v[176:177]
	s_mov_b32 m0, s22
	s_nop 0
	global_load_lds_dwordx4 v[154:155], off
	v_lshl_add_u64 v[154:155], s[18:19], 0, v[144:145]
	s_add_i32 m0, s22, 0x2000
	s_nop 0
	global_load_lds_dwordx4 v[154:155], off
	v_lshl_add_u64 v[154:155], v[206:207], 0, s[96:97]
	s_mov_b32 m0, s30
	s_nop 0
	global_load_lds_dwordx4 v[154:155], off
	v_lshl_add_u64 v[154:155], v[208:209], 0, s[96:97]
	s_mov_b32 m0, s31
	s_nop 0
	global_load_lds_dwordx4 v[154:155], off
	s_waitcnt vmcnt(8)
	s_waitcnt lgkmcnt(0)
	s_barrier
	s_setprio 1
	s_waitcnt lgkmcnt(0)
	v_mfma_f32_16x16x32_bf16 v[60:63], v[112:115], v[170:173], v[60:63]
	v_mfma_f32_16x16x32_bf16 v[56:59], v[120:123], v[170:173], v[56:59]
	v_mfma_f32_16x16x32_bf16 v[52:55], v[112:115], v[182:185], v[52:55]
	v_mfma_f32_16x16x32_bf16 v[40:43], v[120:123], v[182:185], v[40:43]
	v_mfma_f32_16x16x32_bf16 v[36:39], v[112:115], v[190:193], v[36:39]
	v_mfma_f32_16x16x32_bf16 v[24:27], v[120:123], v[190:193], v[24:27]
	v_mfma_f32_16x16x32_bf16 v[20:23], v[112:115], v[198:201], v[20:23]
	v_mfma_f32_16x16x32_bf16 v[8:11], v[120:123], v[198:201], v[8:11]
	v_mfma_f32_16x16x32_bf16 v[60:63], v[116:119], v[178:181], v[60:63]
	v_mfma_f32_16x16x32_bf16 v[56:59], v[132:135], v[178:181], v[56:59]
	v_mfma_f32_16x16x32_bf16 v[52:55], v[116:119], v[186:189], v[52:55]
	v_mfma_f32_16x16x32_bf16 v[40:43], v[132:135], v[186:189], v[40:43]
	v_mfma_f32_16x16x32_bf16 v[36:39], v[116:119], v[194:197], v[36:39]
	v_mfma_f32_16x16x32_bf16 v[24:27], v[132:135], v[194:197], v[24:27]
	v_mfma_f32_16x16x32_bf16 v[20:23], v[116:119], v[202:205], v[20:23]
	v_mfma_f32_16x16x32_bf16 v[8:11], v[132:135], v[202:205], v[8:11]
	s_setprio 0
	s_setprio 1
	v_mfma_f32_16x16x32_bf16 v[48:51], v[150:153], v[170:173], v[48:51]
	v_mfma_f32_16x16x32_bf16 v[44:47], v[162:165], v[170:173], v[44:47]
	v_mfma_f32_16x16x32_bf16 v[32:35], v[150:153], v[182:185], v[32:35]
	v_mfma_f32_16x16x32_bf16 v[28:31], v[162:165], v[182:185], v[28:31]
	v_mfma_f32_16x16x32_bf16 v[16:19], v[150:153], v[190:193], v[16:19]
	v_mfma_f32_16x16x32_bf16 v[12:15], v[162:165], v[190:193], v[12:15]
	v_mfma_f32_16x16x32_bf16 v[4:7], v[150:153], v[198:201], v[4:7]
	v_mfma_f32_16x16x32_bf16 v[0:3], v[162:165], v[198:201], v[0:3]
	v_mfma_f32_16x16x32_bf16 v[48:51], v[158:161], v[178:181], v[48:51]
	v_mfma_f32_16x16x32_bf16 v[44:47], v[166:169], v[178:181], v[44:47]
	v_mfma_f32_16x16x32_bf16 v[32:35], v[158:161], v[186:189], v[32:35]
	v_mfma_f32_16x16x32_bf16 v[28:31], v[166:169], v[186:189], v[28:31]
	v_mfma_f32_16x16x32_bf16 v[16:19], v[158:161], v[194:197], v[16:19]
	v_mfma_f32_16x16x32_bf16 v[12:15], v[166:169], v[194:197], v[12:15]
	v_mfma_f32_16x16x32_bf16 v[4:7], v[158:161], v[202:205], v[4:7]
	v_mfma_f32_16x16x32_bf16 v[0:3], v[166:169], v[202:205], v[0:3]
	s_setprio 0
	s_barrier
	s_add_i32 s58, s58, 2
	s_add_u32 s49, s49, 0x100
	s_addc_u32 s50, s50, 0
	s_cmp_gt_u32 s58, 19
	s_mov_b64 s[18:19], s[20:21]
	s_cbranch_scc1 .Lkdone_6
